# v136 with low-half workgroups lowering priority after MFMA group 3 instead of 5 (re-tune under guarded barriers)
# baseline (speedup 1.0000x reference)
; #define LWRITE(S, buf) do { bf16_t* sA_ = sbase + (buf) * BUF; bf16_t* sB_ = sA_ + 256 * PITCH; \
;     _Pragma("unroll") for (int i_ = 0; i_ < 4; ++i_) *(u32x4*)(sA_ + (sr + i_ * 64) * PITCH + scv * 8) = ra[S][i_]; \
;     _Pragma("unroll") for (int i_ = 0; i_ < 2; ++i_) *(u32x4*)(sB_ + (sr + i_ * 64) * PITCH + scv * 8) = rb[S][i_]; } while (0)
; template <class Epi>
; DI void gemm_tile(char* smem, const bf16_t* __restrict__ A0, int lda0, int ksplit, const bf16_t* __restrict__ A1, int lda1,
;                   const bf16_t* __restrict__ Bt, int K, int row0, int col0, const Epi& epi, int tid) {
;     ...
;     for (int kt = 0; kt < nk; kt += 2) {
;       LWRITE(1, 1);
;       __builtin_amdgcn_sched_barrier(0);
;       GLOAD(1, (kt + 3 < last ? kt + 3 : last));
;       __builtin_amdgcn_sched_barrier(0);
;       COMPUTE(0);
;       __syncthreads();
;       LWRITE(0, 0);
;       __builtin_amdgcn_sched_barrier(0);
;       GLOAD(0, (kt + 4 < last ? kt + 4 : last));
;       __builtin_amdgcn_sched_barrier(0);
;       COMPUTE(1);
;       __syncthreads();
;     }
.Lg1_kloop:
	s_waitcnt vmcnt(6)
	s_waitcnt lgkmcnt(0)
	s_barrier
	v_add_u32_e32 v232, s31, v230
	v_add_u32_e32 v233, s31, v231
	s_add_u32 s22, s30, s100
	s_setprio 1
	v_mfma_f32_16x16x32_bf16 v[0:3], v[128:131], v[144:147], v[0:3]
	v_mfma_f32_16x16x32_bf16 v[4:7], v[132:135], v[144:147], v[4:7]
	v_mfma_f32_16x16x32_bf16 v[8:11], v[136:139], v[144:147], v[8:11]
	v_mfma_f32_16x16x32_bf16 v[12:15], v[140:143], v[144:147], v[12:15]
	ds_read_b128 v[176:179], v233 offset:0
	ds_read_b128 v[180:183], v233 offset:1024
	s_add_u32 m0, s22, 0
	s_nop 0
	global_load_lds_dwordx4 v224, s[0:1]
	v_mfma_f32_16x16x32_bf16 v[16:19], v[128:131], v[148:151], v[16:19]
	v_mfma_f32_16x16x32_bf16 v[20:23], v[132:135], v[148:151], v[20:23]
	v_mfma_f32_16x16x32_bf16 v[24:27], v[136:139], v[148:151], v[24:27]
	v_mfma_f32_16x16x32_bf16 v[28:31], v[140:143], v[148:151], v[28:31]
	ds_read_b128 v[184:187], v233 offset:2048
	ds_read_b128 v[188:191], v233 offset:3072
	s_add_u32 m0, s22, 4096
	s_nop 0
	global_load_lds_dwordx4 v225, s[0:1]
	v_mfma_f32_16x16x32_bf16 v[32:35], v[128:131], v[152:155], v[32:35]
	v_mfma_f32_16x16x32_bf16 v[36:39], v[132:135], v[152:155], v[36:39]
	v_mfma_f32_16x16x32_bf16 v[40:43], v[136:139], v[152:155], v[40:43]
	v_mfma_f32_16x16x32_bf16 v[44:47], v[140:143], v[152:155], v[44:47]
	ds_read_b128 v[192:195], v232 offset:0
	ds_read_b128 v[196:199], v232 offset:1024
	s_add_u32 m0, s22, 8192
	s_nop 0
	global_load_lds_dwordx4 v226, s[0:1]
	v_mfma_f32_16x16x32_bf16 v[48:51], v[128:131], v[156:159], v[48:51]
	v_mfma_f32_16x16x32_bf16 v[52:55], v[132:135], v[156:159], v[52:55]
	v_mfma_f32_16x16x32_bf16 v[56:59], v[136:139], v[156:159], v[56:59]
	v_mfma_f32_16x16x32_bf16 v[60:63], v[140:143], v[156:159], v[60:63]
	ds_read_b128 v[200:203], v232 offset:2048
	ds_read_b128 v[204:207], v232 offset:3072
	s_add_u32 m0, s22, 12288
	s_nop 0
	global_load_lds_dwordx4 v227, s[0:1]
	s_cmp_eq_u32 s21, 0
	s_cbranch_scc0 .Lg1_hi0
	s_setprio 0
.Lg1_hi0:
	v_mfma_f32_16x16x32_bf16 v[64:67], v[128:131], v[160:163], v[64:67]
	v_mfma_f32_16x16x32_bf16 v[68:71], v[132:135], v[160:163], v[68:71]
	v_mfma_f32_16x16x32_bf16 v[72:75], v[136:139], v[160:163], v[72:75]
	v_mfma_f32_16x16x32_bf16 v[76:79], v[140:143], v[160:163], v[76:79]
	ds_read_b128 v[208:211], v232 offset:4096
	s_add_u32 m0, s22, 16384
	s_nop 0
	global_load_lds_dwordx4 v228, s[2:3]
	v_mfma_f32_16x16x32_bf16 v[80:83], v[128:131], v[164:167], v[80:83]
	v_mfma_f32_16x16x32_bf16 v[84:87], v[132:135], v[164:167], v[84:87]
	v_mfma_f32_16x16x32_bf16 v[88:91], v[136:139], v[164:167], v[88:91]
	v_mfma_f32_16x16x32_bf16 v[92:95], v[140:143], v[164:167], v[92:95]
	ds_read_b128 v[212:215], v232 offset:5120
	s_add_u32 m0, s22, 20480
	s_nop 0
	global_load_lds_dwordx4 v229, s[2:3]
	v_mfma_f32_16x16x32_bf16 v[96:99], v[128:131], v[168:171], v[96:99]
	v_mfma_f32_16x16x32_bf16 v[100:103], v[132:135], v[168:171], v[100:103]
	v_mfma_f32_16x16x32_bf16 v[104:107], v[136:139], v[168:171], v[104:107]
	v_mfma_f32_16x16x32_bf16 v[108:111], v[140:143], v[168:171], v[108:111]
	ds_read_b128 v[216:219], v232 offset:6144
	s_add_u32 s0, s0, 64
	s_addc_u32 s1, s1, 0
	s_add_u32 s2, s2, 64
	s_addc_u32 s3, s3, 0
	s_add_u32 s99, s99, 1
	s_add_u32 s30, s30, 24576
	s_cmp_eq_u32 s30, 73728
	s_cselect_b32 s30, 0, s30
	s_add_u32 s31, s31, 24576
	s_cmp_eq_u32 s31, 73728
	s_cselect_b32 s31, 0, s31
	v_mfma_f32_16x16x32_bf16 v[112:115], v[128:131], v[172:175], v[112:115]
	v_mfma_f32_16x16x32_bf16 v[116:119], v[132:135], v[172:175], v[116:119]
	v_mfma_f32_16x16x32_bf16 v[120:123], v[136:139], v[172:175], v[120:123]
	v_mfma_f32_16x16x32_bf16 v[124:127], v[140:143], v[172:175], v[124:127]
	ds_read_b128 v[220:223], v232 offset:7168
	s_waitcnt vmcnt(6)
	s_waitcnt lgkmcnt(0)
	s_barrier
	v_add_u32_e32 v232, s31, v230
	v_add_u32_e32 v233, s31, v231
	s_add_u32 s22, s30, s100
	s_setprio 1
	v_mfma_f32_16x16x32_bf16 v[0:3], v[176:179], v[192:195], v[0:3]
	v_mfma_f32_16x16x32_bf16 v[4:7], v[180:183], v[192:195], v[4:7]
	v_mfma_f32_16x16x32_bf16 v[8:11], v[184:187], v[192:195], v[8:11]
	v_mfma_f32_16x16x32_bf16 v[12:15], v[188:191], v[192:195], v[12:15]
	ds_read_b128 v[128:131], v233 offset:0
	ds_read_b128 v[132:135], v233 offset:1024
	s_add_u32 m0, s22, 0
	s_nop 0
	global_load_lds_dwordx4 v224, s[0:1]
	v_mfma_f32_16x16x32_bf16 v[16:19], v[176:179], v[196:199], v[16:19]
	v_mfma_f32_16x16x32_bf16 v[20:23], v[180:183], v[196:199], v[20:23]
	v_mfma_f32_16x16x32_bf16 v[24:27], v[184:187], v[196:199], v[24:27]
	v_mfma_f32_16x16x32_bf16 v[28:31], v[188:191], v[196:199], v[28:31]
	ds_read_b128 v[136:139], v233 offset:2048
	ds_read_b128 v[140:143], v233 offset:3072
	s_add_u32 m0, s22, 4096
	s_nop 0
	global_load_lds_dwordx4 v225, s[0:1]
	v_mfma_f32_16x16x32_bf16 v[32:35], v[176:179], v[200:203], v[32:35]
	v_mfma_f32_16x16x32_bf16 v[36:39], v[180:183], v[200:203], v[36:39]
	v_mfma_f32_16x16x32_bf16 v[40:43], v[184:187], v[200:203], v[40:43]
	v_mfma_f32_16x16x32_bf16 v[44:47], v[188:191], v[200:203], v[44:47]
	ds_read_b128 v[144:147], v232 offset:0
	ds_read_b128 v[148:151], v232 offset:1024
	s_add_u32 m0, s22, 8192
	s_nop 0
	global_load_lds_dwordx4 v226, s[0:1]
	v_mfma_f32_16x16x32_bf16 v[48:51], v[176:179], v[204:207], v[48:51]
	v_mfma_f32_16x16x32_bf16 v[52:55], v[180:183], v[204:207], v[52:55]
	v_mfma_f32_16x16x32_bf16 v[56:59], v[184:187], v[204:207], v[56:59]
	v_mfma_f32_16x16x32_bf16 v[60:63], v[188:191], v[204:207], v[60:63]
	ds_read_b128 v[152:155], v232 offset:2048
	ds_read_b128 v[156:159], v232 offset:3072
	s_add_u32 m0, s22, 12288
	s_nop 0
	global_load_lds_dwordx4 v227, s[0:1]
	s_cmp_eq_u32 s21, 0
	s_cbranch_scc0 .Lg1_hi1
	s_setprio 0
; #define LWRITE(S, buf) do { bf16_t* sA_ = sbase + (buf) * BUF; bf16_t* sB_ = sA_ + 256 * PITCH; \
;     _Pragma("unroll") for (int i_ = 0; i_ < 4; ++i_) *(u32x4*)(sA_ + (sr + i_ * 64) * PITCH + scv * 8) = ra[S][i_]; \
;     _Pragma("unroll") for (int i_ = 0; i_ < 2; ++i_) *(u32x4*)(sB_ + (sr + i_ * 64) * PITCH + scv * 8) = rb[S][i_]; } while (0)
; template <class Epi>
; DI void gemm_tile(char* smem, const bf16_t* __restrict__ A0, int lda0, int ksplit, const bf16_t* __restrict__ A1, int lda1,
;                   const bf16_t* __restrict__ Bt, int K, int row0, int col0, const Epi& epi, int tid) {
;     ...
;     for (int kt = 0; kt < nk; kt += 2) {
;       LWRITE(1, 1);
;       __builtin_amdgcn_sched_barrier(0);
;       GLOAD(1, (kt + 3 < last ? kt + 3 : last));
;       __builtin_amdgcn_sched_barrier(0);
;       COMPUTE(0);
;       __syncthreads();
;       LWRITE(0, 0);
;       __builtin_amdgcn_sched_barrier(0);
;       GLOAD(0, (kt + 4 < last ? kt + 4 : last));
;       __builtin_amdgcn_sched_barrier(0);
;       COMPUTE(1);
;       __syncthreads();
;     }
.Lg1_hi1:
	v_mfma_f32_16x16x32_bf16 v[64:67], v[176:179], v[208:211], v[64:67]
	v_mfma_f32_16x16x32_bf16 v[68:71], v[180:183], v[208:211], v[68:71]
	v_mfma_f32_16x16x32_bf16 v[72:75], v[184:187], v[208:211], v[72:75]
	v_mfma_f32_16x16x32_bf16 v[76:79], v[188:191], v[208:211], v[76:79]
	ds_read_b128 v[160:163], v232 offset:4096
	s_add_u32 m0, s22, 16384
	s_nop 0
	global_load_lds_dwordx4 v228, s[2:3]
	v_mfma_f32_16x16x32_bf16 v[80:83], v[176:179], v[212:215], v[80:83]
	v_mfma_f32_16x16x32_bf16 v[84:87], v[180:183], v[212:215], v[84:87]
	v_mfma_f32_16x16x32_bf16 v[88:91], v[184:187], v[212:215], v[88:91]
	v_mfma_f32_16x16x32_bf16 v[92:95], v[188:191], v[212:215], v[92:95]
	ds_read_b128 v[164:167], v232 offset:5120
	s_add_u32 m0, s22, 20480
	s_nop 0
	global_load_lds_dwordx4 v229, s[2:3]
	v_mfma_f32_16x16x32_bf16 v[96:99], v[176:179], v[216:219], v[96:99]
	v_mfma_f32_16x16x32_bf16 v[100:103], v[180:183], v[216:219], v[100:103]
	v_mfma_f32_16x16x32_bf16 v[104:107], v[184:187], v[216:219], v[104:107]
	v_mfma_f32_16x16x32_bf16 v[108:111], v[188:191], v[216:219], v[108:111]
	ds_read_b128 v[168:171], v232 offset:6144
	s_add_u32 s0, s0, 64
	s_addc_u32 s1, s1, 0
	s_add_u32 s2, s2, 64
	s_addc_u32 s3, s3, 0
	s_add_u32 s99, s99, 1
	s_add_u32 s30, s30, 24576
	s_cmp_eq_u32 s30, 73728
	s_cselect_b32 s30, 0, s30
	s_add_u32 s31, s31, 24576
	s_cmp_eq_u32 s31, 73728
	s_cselect_b32 s31, 0, s31
	v_mfma_f32_16x16x32_bf16 v[112:115], v[176:179], v[220:223], v[112:115]
	v_mfma_f32_16x16x32_bf16 v[116:119], v[180:183], v[220:223], v[116:119]
	v_mfma_f32_16x16x32_bf16 v[120:123], v[184:187], v[220:223], v[120:123]
	v_mfma_f32_16x16x32_bf16 v[124:127], v[188:191], v[220:223], v[124:127]
	ds_read_b128 v[172:175], v232 offset:7168
	s_add_u32 s98, s98, 2
	s_cmp_lt_u32 s98, 28
	s_cbranch_scc1 .Lg1_kloop
	s_waitcnt vmcnt(6)
	s_waitcnt lgkmcnt(0)
	s_barrier
	v_add_u32_e32 v232, s31, v230
	v_add_u32_e32 v233, s31, v231
	s_add_u32 s22, s30, s100
	s_setprio 1
	v_mfma_f32_16x16x32_bf16 v[0:3], v[128:131], v[144:147], v[0:3]
	v_mfma_f32_16x16x32_bf16 v[4:7], v[132:135], v[144:147], v[4:7]
	v_mfma_f32_16x16x32_bf16 v[8:11], v[136:139], v[144:147], v[8:11]
	v_mfma_f32_16x16x32_bf16 v[12:15], v[140:143], v[144:147], v[12:15]
	ds_read_b128 v[176:179], v233 offset:0
	ds_read_b128 v[180:183], v233 offset:1024
	s_add_u32 m0, s22, 0
	s_nop 0
	global_load_lds_dwordx4 v224, s[0:1]
	v_mfma_f32_16x16x32_bf16 v[16:19], v[128:131], v[148:151], v[16:19]
	v_mfma_f32_16x16x32_bf16 v[20:23], v[132:135], v[148:151], v[20:23]
	v_mfma_f32_16x16x32_bf16 v[24:27], v[136:139], v[148:151], v[24:27]
	v_mfma_f32_16x16x32_bf16 v[28:31], v[140:143], v[148:151], v[28:31]
	ds_read_b128 v[184:187], v233 offset:2048
	ds_read_b128 v[188:191], v233 offset:3072
	s_add_u32 m0, s22, 4096
	s_nop 0
	global_load_lds_dwordx4 v225, s[0:1]
	v_mfma_f32_16x16x32_bf16 v[32:35], v[128:131], v[152:155], v[32:35]
	v_mfma_f32_16x16x32_bf16 v[36:39], v[132:135], v[152:155], v[36:39]
	v_mfma_f32_16x16x32_bf16 v[40:43], v[136:139], v[152:155], v[40:43]
	v_mfma_f32_16x16x32_bf16 v[44:47], v[140:143], v[152:155], v[44:47]
	ds_read_b128 v[192:195], v232 offset:0
	ds_read_b128 v[196:199], v232 offset:1024
	s_add_u32 m0, s22, 8192
	s_nop 0
	global_load_lds_dwordx4 v226, s[0:1]
	v_mfma_f32_16x16x32_bf16 v[48:51], v[128:131], v[156:159], v[48:51]
	v_mfma_f32_16x16x32_bf16 v[52:55], v[132:135], v[156:159], v[52:55]
	v_mfma_f32_16x16x32_bf16 v[56:59], v[136:139], v[156:159], v[56:59]
	v_mfma_f32_16x16x32_bf16 v[60:63], v[140:143], v[156:159], v[60:63]
	ds_read_b128 v[200:203], v232 offset:2048
	ds_read_b128 v[204:207], v232 offset:3072
	s_add_u32 m0, s22, 12288
	s_nop 0
	global_load_lds_dwordx4 v227, s[0:1]
	s_cmp_eq_u32 s21, 0
	s_cbranch_scc0 .Lg1_hi2
	s_setprio 0
.Lg1_hi2:
	v_mfma_f32_16x16x32_bf16 v[64:67], v[128:131], v[160:163], v[64:67]
	v_mfma_f32_16x16x32_bf16 v[68:71], v[132:135], v[160:163], v[68:71]
	v_mfma_f32_16x16x32_bf16 v[72:75], v[136:139], v[160:163], v[72:75]
	v_mfma_f32_16x16x32_bf16 v[76:79], v[140:143], v[160:163], v[76:79]
	ds_read_b128 v[208:211], v232 offset:4096
	s_add_u32 m0, s22, 16384
	s_nop 0
	global_load_lds_dwordx4 v228, s[2:3]
	v_mfma_f32_16x16x32_bf16 v[80:83], v[128:131], v[164:167], v[80:83]
	v_mfma_f32_16x16x32_bf16 v[84:87], v[132:135], v[164:167], v[84:87]
	v_mfma_f32_16x16x32_bf16 v[88:91], v[136:139], v[164:167], v[88:91]
	v_mfma_f32_16x16x32_bf16 v[92:95], v[140:143], v[164:167], v[92:95]
	ds_read_b128 v[212:215], v232 offset:5120
	s_add_u32 m0, s22, 20480
	s_nop 0
	global_load_lds_dwordx4 v229, s[2:3]
	v_mfma_f32_16x16x32_bf16 v[96:99], v[128:131], v[168:171], v[96:99]
	v_mfma_f32_16x16x32_bf16 v[100:103], v[132:135], v[168:171], v[100:103]
	v_mfma_f32_16x16x32_bf16 v[104:107], v[136:139], v[168:171], v[104:107]
	v_mfma_f32_16x16x32_bf16 v[108:111], v[140:143], v[168:171], v[108:111]
	ds_read_b128 v[216:219], v232 offset:6144
	s_add_u32 s0, s0, 64
	s_addc_u32 s1, s1, 0
	s_add_u32 s2, s2, 64
	s_addc_u32 s3, s3, 0
	s_add_u32 s99, s99, 1
	s_add_u32 s30, s30, 24576
	s_cmp_eq_u32 s30, 73728
	s_cselect_b32 s30, 0, s30
	s_add_u32 s31, s31, 24576
	s_cmp_eq_u32 s31, 73728
	s_cselect_b32 s31, 0, s31
	v_mfma_f32_16x16x32_bf16 v[112:115], v[128:131], v[172:175], v[112:115]
	v_mfma_f32_16x16x32_bf16 v[116:119], v[132:135], v[172:175], v[116:119]
	v_mfma_f32_16x16x32_bf16 v[120:123], v[136:139], v[172:175], v[120:123]
	v_mfma_f32_16x16x32_bf16 v[124:127], v[140:143], v[172:175], v[124:127]
	ds_read_b128 v[220:223], v232 offset:7168
	s_waitcnt vmcnt(6)
	s_waitcnt lgkmcnt(0)
	s_barrier
; #define LWRITE(S, buf) do { bf16_t* sA_ = sbase + (buf) * BUF; bf16_t* sB_ = sA_ + 256 * PITCH; \
;     _Pragma("unroll") for (int i_ = 0; i_ < 4; ++i_) *(u32x4*)(sA_ + (sr + i_ * 64) * PITCH + scv * 8) = ra[S][i_]; \
;     _Pragma("unroll") for (int i_ = 0; i_ < 2; ++i_) *(u32x4*)(sB_ + (sr + i_ * 64) * PITCH + scv * 8) = rb[S][i_]; } while (0)
; template <class Epi>
; DI void gemm_tile(char* smem, const bf16_t* __restrict__ A0, int lda0, int ksplit, const bf16_t* __restrict__ A1, int lda1,
;                   const bf16_t* __restrict__ Bt, int K, int row0, int col0, const Epi& epi, int tid) {
;     ...
;     for (int kt = 0; kt < nk; kt += 2) {
;       LWRITE(1, 1);
;       __builtin_amdgcn_sched_barrier(0);
;       GLOAD(1, (kt + 3 < last ? kt + 3 : last));
;       __builtin_amdgcn_sched_barrier(0);
;       COMPUTE(0);
;       __syncthreads();
;       LWRITE(0, 0);
;       __builtin_amdgcn_sched_barrier(0);
;       GLOAD(0, (kt + 4 < last ? kt + 4 : last));
;       __builtin_amdgcn_sched_barrier(0);
;       COMPUTE(1);
;       __syncthreads();
;     }
	v_add_u32_e32 v232, s31, v230
	v_add_u32_e32 v233, s31, v231
	s_setprio 1
	v_mfma_f32_16x16x32_bf16 v[0:3], v[176:179], v[192:195], v[0:3]
	v_mfma_f32_16x16x32_bf16 v[4:7], v[180:183], v[192:195], v[4:7]
	v_mfma_f32_16x16x32_bf16 v[8:11], v[184:187], v[192:195], v[8:11]
	v_mfma_f32_16x16x32_bf16 v[12:15], v[188:191], v[192:195], v[12:15]
	ds_read_b128 v[128:131], v233 offset:0
	ds_read_b128 v[132:135], v233 offset:1024
	v_mfma_f32_16x16x32_bf16 v[16:19], v[176:179], v[196:199], v[16:19]
	v_mfma_f32_16x16x32_bf16 v[20:23], v[180:183], v[196:199], v[20:23]
	v_mfma_f32_16x16x32_bf16 v[24:27], v[184:187], v[196:199], v[24:27]
	v_mfma_f32_16x16x32_bf16 v[28:31], v[188:191], v[196:199], v[28:31]
	ds_read_b128 v[136:139], v233 offset:2048
	ds_read_b128 v[140:143], v233 offset:3072
	v_mfma_f32_16x16x32_bf16 v[32:35], v[176:179], v[200:203], v[32:35]
	v_mfma_f32_16x16x32_bf16 v[36:39], v[180:183], v[200:203], v[36:39]
	v_mfma_f32_16x16x32_bf16 v[40:43], v[184:187], v[200:203], v[40:43]
	v_mfma_f32_16x16x32_bf16 v[44:47], v[188:191], v[200:203], v[44:47]
	ds_read_b128 v[144:147], v232 offset:0
	ds_read_b128 v[148:151], v232 offset:1024
	v_mfma_f32_16x16x32_bf16 v[48:51], v[176:179], v[204:207], v[48:51]
	v_mfma_f32_16x16x32_bf16 v[52:55], v[180:183], v[204:207], v[52:55]
	v_mfma_f32_16x16x32_bf16 v[56:59], v[184:187], v[204:207], v[56:59]
	v_mfma_f32_16x16x32_bf16 v[60:63], v[188:191], v[204:207], v[60:63]
	ds_read_b128 v[152:155], v232 offset:2048
	ds_read_b128 v[156:159], v232 offset:3072
	s_cmp_eq_u32 s21, 0
	s_cbranch_scc0 .Lg1_hi3
	s_setprio 0
.Lg1_hi3:
	v_mfma_f32_16x16x32_bf16 v[64:67], v[176:179], v[208:211], v[64:67]
	v_mfma_f32_16x16x32_bf16 v[68:71], v[180:183], v[208:211], v[68:71]
	v_mfma_f32_16x16x32_bf16 v[72:75], v[184:187], v[208:211], v[72:75]
	v_mfma_f32_16x16x32_bf16 v[76:79], v[188:191], v[208:211], v[76:79]
	ds_read_b128 v[160:163], v232 offset:4096
	v_mfma_f32_16x16x32_bf16 v[80:83], v[176:179], v[212:215], v[80:83]
	v_mfma_f32_16x16x32_bf16 v[84:87], v[180:183], v[212:215], v[84:87]
	v_mfma_f32_16x16x32_bf16 v[88:91], v[184:187], v[212:215], v[88:91]
	v_mfma_f32_16x16x32_bf16 v[92:95], v[188:191], v[212:215], v[92:95]
	ds_read_b128 v[164:167], v232 offset:5120
	v_mfma_f32_16x16x32_bf16 v[96:99], v[176:179], v[216:219], v[96:99]
	v_mfma_f32_16x16x32_bf16 v[100:103], v[180:183], v[216:219], v[100:103]
	v_mfma_f32_16x16x32_bf16 v[104:107], v[184:187], v[216:219], v[104:107]
	v_mfma_f32_16x16x32_bf16 v[108:111], v[188:191], v[216:219], v[108:111]
	ds_read_b128 v[168:171], v232 offset:6144
	s_add_u32 s31, s31, 24576
	s_cmp_eq_u32 s31, 73728
	s_cselect_b32 s31, 0, s31
	v_mfma_f32_16x16x32_bf16 v[112:115], v[176:179], v[220:223], v[112:115]
	v_mfma_f32_16x16x32_bf16 v[116:119], v[180:183], v[220:223], v[116:119]
	v_mfma_f32_16x16x32_bf16 v[120:123], v[184:187], v[220:223], v[120:123]
	v_mfma_f32_16x16x32_bf16 v[124:127], v[188:191], v[220:223], v[124:127]
	ds_read_b128 v[172:175], v232 offset:7168
	s_waitcnt vmcnt(0)
	s_waitcnt lgkmcnt(0)
	s_barrier
	v_add_u32_e32 v232, s31, v230
	v_add_u32_e32 v233, s31, v231
	s_setprio 1
	v_mfma_f32_16x16x32_bf16 v[0:3], v[128:131], v[144:147], v[0:3]
	v_mfma_f32_16x16x32_bf16 v[4:7], v[132:135], v[144:147], v[4:7]
	v_mfma_f32_16x16x32_bf16 v[8:11], v[136:139], v[144:147], v[8:11]
	v_mfma_f32_16x16x32_bf16 v[12:15], v[140:143], v[144:147], v[12:15]
	ds_read_b128 v[176:179], v233 offset:0
	ds_read_b128 v[180:183], v233 offset:1024
	v_mfma_f32_16x16x32_bf16 v[16:19], v[128:131], v[148:151], v[16:19]
	v_mfma_f32_16x16x32_bf16 v[20:23], v[132:135], v[148:151], v[20:23]
	v_mfma_f32_16x16x32_bf16 v[24:27], v[136:139], v[148:151], v[24:27]
	v_mfma_f32_16x16x32_bf16 v[28:31], v[140:143], v[148:151], v[28:31]
	ds_read_b128 v[184:187], v233 offset:2048
	ds_read_b128 v[188:191], v233 offset:3072
	v_mfma_f32_16x16x32_bf16 v[32:35], v[128:131], v[152:155], v[32:35]
	v_mfma_f32_16x16x32_bf16 v[36:39], v[132:135], v[152:155], v[36:39]
	v_mfma_f32_16x16x32_bf16 v[40:43], v[136:139], v[152:155], v[40:43]
	v_mfma_f32_16x16x32_bf16 v[44:47], v[140:143], v[152:155], v[44:47]
	ds_read_b128 v[192:195], v232 offset:0
	ds_read_b128 v[196:199], v232 offset:1024
	v_mfma_f32_16x16x32_bf16 v[48:51], v[128:131], v[156:159], v[48:51]
	v_mfma_f32_16x16x32_bf16 v[52:55], v[132:135], v[156:159], v[52:55]
	v_mfma_f32_16x16x32_bf16 v[56:59], v[136:139], v[156:159], v[56:59]
	v_mfma_f32_16x16x32_bf16 v[60:63], v[140:143], v[156:159], v[60:63]
	ds_read_b128 v[200:203], v232 offset:2048
	ds_read_b128 v[204:207], v232 offset:3072
	s_cmp_eq_u32 s21, 0
	s_cbranch_scc0 .Lg1_hi4
	s_setprio 0
; #define LWRITE(S, buf) do { bf16_t* sA_ = sbase + (buf) * BUF; bf16_t* sB_ = sA_ + 256 * PITCH; \
;     _Pragma("unroll") for (int i_ = 0; i_ < 4; ++i_) *(u32x4*)(sA_ + (sr + i_ * 64) * PITCH + scv * 8) = ra[S][i_]; \
;     _Pragma("unroll") for (int i_ = 0; i_ < 2; ++i_) *(u32x4*)(sB_ + (sr + i_ * 64) * PITCH + scv * 8) = rb[S][i_]; } while (0)
; template <class Epi>
; DI void gemm_tile(char* smem, const bf16_t* __restrict__ A0, int lda0, int ksplit, const bf16_t* __restrict__ A1, int lda1,
;                   const bf16_t* __restrict__ Bt, int K, int row0, int col0, const Epi& epi, int tid) {
;     ...
;     for (int kt = 0; kt < nk; kt += 2) {
;       LWRITE(1, 1);
;       __builtin_amdgcn_sched_barrier(0);
;       GLOAD(1, (kt + 3 < last ? kt + 3 : last));
;       __builtin_amdgcn_sched_barrier(0);
;       COMPUTE(0);
;       __syncthreads();
;       LWRITE(0, 0);
;       __builtin_amdgcn_sched_barrier(0);
;       GLOAD(0, (kt + 4 < last ? kt + 4 : last));
;       __builtin_amdgcn_sched_barrier(0);
;       COMPUTE(1);
;       __syncthreads();
;     }
.Lg1_hi4:
	v_mfma_f32_16x16x32_bf16 v[64:67], v[128:131], v[160:163], v[64:67]
	v_mfma_f32_16x16x32_bf16 v[68:71], v[132:135], v[160:163], v[68:71]
	v_mfma_f32_16x16x32_bf16 v[72:75], v[136:139], v[160:163], v[72:75]
	v_mfma_f32_16x16x32_bf16 v[76:79], v[140:143], v[160:163], v[76:79]
	ds_read_b128 v[208:211], v232 offset:4096
	v_mfma_f32_16x16x32_bf16 v[80:83], v[128:131], v[164:167], v[80:83]
	v_mfma_f32_16x16x32_bf16 v[84:87], v[132:135], v[164:167], v[84:87]
	v_mfma_f32_16x16x32_bf16 v[88:91], v[136:139], v[164:167], v[88:91]
	v_mfma_f32_16x16x32_bf16 v[92:95], v[140:143], v[164:167], v[92:95]
	ds_read_b128 v[212:215], v232 offset:5120
	v_mfma_f32_16x16x32_bf16 v[96:99], v[128:131], v[168:171], v[96:99]
	v_mfma_f32_16x16x32_bf16 v[100:103], v[132:135], v[168:171], v[100:103]
	v_mfma_f32_16x16x32_bf16 v[104:107], v[136:139], v[168:171], v[104:107]
	v_mfma_f32_16x16x32_bf16 v[108:111], v[140:143], v[168:171], v[108:111]
	ds_read_b128 v[216:219], v232 offset:6144
	s_add_u32 s31, s31, 24576
	s_cmp_eq_u32 s31, 73728
	s_cselect_b32 s31, 0, s31
	v_mfma_f32_16x16x32_bf16 v[112:115], v[128:131], v[172:175], v[112:115]
	v_mfma_f32_16x16x32_bf16 v[116:119], v[132:135], v[172:175], v[116:119]
	v_mfma_f32_16x16x32_bf16 v[120:123], v[136:139], v[172:175], v[120:123]
	v_mfma_f32_16x16x32_bf16 v[124:127], v[140:143], v[172:175], v[124:127]
	ds_read_b128 v[220:223], v232 offset:7168
	s_waitcnt lgkmcnt(0)
	s_barrier
	s_setprio 1
	v_mfma_f32_16x16x32_bf16 v[0:3], v[176:179], v[192:195], v[0:3]
	v_mfma_f32_16x16x32_bf16 v[4:7], v[180:183], v[192:195], v[4:7]
	v_mfma_f32_16x16x32_bf16 v[8:11], v[184:187], v[192:195], v[8:11]
	v_mfma_f32_16x16x32_bf16 v[12:15], v[188:191], v[192:195], v[12:15]
	v_mfma_f32_16x16x32_bf16 v[16:19], v[176:179], v[196:199], v[16:19]
	v_mfma_f32_16x16x32_bf16 v[20:23], v[180:183], v[196:199], v[20:23]
	v_mfma_f32_16x16x32_bf16 v[24:27], v[184:187], v[196:199], v[24:27]
	v_mfma_f32_16x16x32_bf16 v[28:31], v[188:191], v[196:199], v[28:31]
	v_mfma_f32_16x16x32_bf16 v[32:35], v[176:179], v[200:203], v[32:35]
	v_mfma_f32_16x16x32_bf16 v[36:39], v[180:183], v[200:203], v[36:39]
	v_mfma_f32_16x16x32_bf16 v[40:43], v[184:187], v[200:203], v[40:43]
	v_mfma_f32_16x16x32_bf16 v[44:47], v[188:191], v[200:203], v[44:47]
	v_mfma_f32_16x16x32_bf16 v[48:51], v[176:179], v[204:207], v[48:51]
	v_mfma_f32_16x16x32_bf16 v[52:55], v[180:183], v[204:207], v[52:55]
	v_mfma_f32_16x16x32_bf16 v[56:59], v[184:187], v[204:207], v[56:59]
	v_mfma_f32_16x16x32_bf16 v[60:63], v[188:191], v[204:207], v[60:63]
	s_cmp_eq_u32 s21, 0
	s_cbranch_scc0 .Lg1_hi5
	s_setprio 0
.Lg1_hi5:
	v_mfma_f32_16x16x32_bf16 v[64:67], v[176:179], v[208:211], v[64:67]
	v_mfma_f32_16x16x32_bf16 v[68:71], v[180:183], v[208:211], v[68:71]
	v_mfma_f32_16x16x32_bf16 v[72:75], v[184:187], v[208:211], v[72:75]
	v_mfma_f32_16x16x32_bf16 v[76:79], v[188:191], v[208:211], v[76:79]
	v_mfma_f32_16x16x32_bf16 v[80:83], v[176:179], v[212:215], v[80:83]
	v_mfma_f32_16x16x32_bf16 v[84:87], v[180:183], v[212:215], v[84:87]
	v_mfma_f32_16x16x32_bf16 v[88:91], v[184:187], v[212:215], v[88:91]
	v_mfma_f32_16x16x32_bf16 v[92:95], v[188:191], v[212:215], v[92:95]
	v_mfma_f32_16x16x32_bf16 v[96:99], v[176:179], v[216:219], v[96:99]
	v_mfma_f32_16x16x32_bf16 v[100:103], v[180:183], v[216:219], v[100:103]
	v_mfma_f32_16x16x32_bf16 v[104:107], v[184:187], v[216:219], v[104:107]
	v_mfma_f32_16x16x32_bf16 v[108:111], v[188:191], v[216:219], v[108:111]
	v_mfma_f32_16x16x32_bf16 v[112:115], v[176:179], v[220:223], v[112:115]
	v_mfma_f32_16x16x32_bf16 v[116:119], v[180:183], v[220:223], v[116:119]
	v_mfma_f32_16x16x32_bf16 v[120:123], v[184:187], v[220:223], v[120:123]
	v_mfma_f32_16x16x32_bf16 v[124:127], v[188:191], v[220:223], v[124:127]
	s_branch .Lg1_epi

; #define LWRITE(S, buf) do { bf16_t* sA_ = sbase + (buf) * BUF; bf16_t* sB_ = sA_ + 256 * PITCH; \
;     _Pragma("unroll") for (int i_ = 0; i_ < 4; ++i_) *(u32x4*)(sA_ + (sr + i_ * 64) * PITCH + scv * 8) = ra[S][i_]; \
;     _Pragma("unroll") for (int i_ = 0; i_ < 2; ++i_) *(u32x4*)(sB_ + (sr + i_ * 64) * PITCH + scv * 8) = rb[S][i_]; } while (0)
; template <class Epi>
; DI void gemm_tile(char* smem, const bf16_t* __restrict__ A0, int lda0, int ksplit, const bf16_t* __restrict__ A1, int lda1,
;                   const bf16_t* __restrict__ Bt, int K, int row0, int col0, const Epi& epi, int tid) {
;     ...
;   f32x4 acc[8][4];
; #pragma unroll
;   for (int m = 0; m < 8; ++m)
; #pragma unroll
;     for (int n = 0; n < 4; ++n) acc[m][n] = (f32x4){0.f, 0.f, 0.f, 0.f};
;   u32x4 ra[2][4], rb[2][2];
;   const int nk = K / BK;
;   const int sr = tid >> 2, scv = tid & 3;
;     ...
;   __syncthreads();
;   {
;     const int last = nk - 1;
;     GLOAD(0, 0);
;     __builtin_amdgcn_sched_barrier(0);
;     GLOAD(1, 1);
;     __builtin_amdgcn_sched_barrier(0);
;     LWRITE(0, 0);
;     __builtin_amdgcn_sched_barrier(0);
;     GLOAD(0, (2 < last ? 2 : last));
;     __builtin_amdgcn_sched_barrier(0);
;     __syncthreads();
; template <class Epi>
; DI void gemm_phase(char* smem, const bf16_t* A0, int lda0, int ksplit, const bf16_t* A1, int lda1, const bf16_t* Bt, int K, int nN, const Epi& epi, int tid) {
;     ...
;     const int x = blockIdx.x & 7, l = blockIdx.x >> 3, L = G >> 3, per = 8 * nN, tot = 2 * per;
;     for (int q = l; q < tot; q += L) { const int rgl = q / per, rem = q % per, ct = rem >> 3, rt = (x * 2 + rgl) * 8 + (rem & 7);
;       gemm_tile(smem, A0, lda0, ksplit, A1, lda1, Bt, K, rt * 256, ct * 128, epi, tid); }
.Lg3a_tile:
	s_cmpk_ge_u32 s15, 64
	s_cbranch_scc1 .Lg3a_done
	s_cmpk_ge_u32 s15, 32
	s_cselect_b32 s27, 1, 0
	s_cselect_b32 s26, 32, 0
	s_sub_u32 s26, s15, s26
	s_add_u32 s27, s27, s101
	s_lshl_b32 s27, s27, 3
	s_and_b32 s29, s26, 7
	s_add_u32 s29, s29, s27
	s_lshl_b32 s29, s29, 8
	s_lshr_b32 s28, s26, 3
	s_lshl_b32 s28, s28, 7
	s_mul_i32 s27, s29, 512
	s_add_u32 s27, s27, 0x1ea00000
	s_add_u32 s0, s92, s27
	s_addc_u32 s1, s93, 0
	s_mul_i32 s27, s28, 128
	s_add_u32 s27, s27, 0x34a0000
	s_add_u32 s2, s92, s27
	s_addc_u32 s3, s93, 0
	s_waitcnt lgkmcnt(0)
	s_barrier
	s_mov_b32 s99, 0
	s_mov_b32 s30, 0
	s_add_u32 s26, s30, s100
	s_add_u32 m0, s26, 0
	s_nop 0
	global_load_lds_dwordx4 v224, s[0:1]
	s_add_u32 m0, s26, 4096
	s_nop 0
	global_load_lds_dwordx4 v225, s[0:1]
	s_add_u32 m0, s26, 8192
	s_nop 0
	global_load_lds_dwordx4 v226, s[0:1]
	s_add_u32 m0, s26, 12288
	s_nop 0
	global_load_lds_dwordx4 v227, s[0:1]
	s_add_u32 m0, s26, 16384
	s_nop 0
	global_load_lds_dwordx4 v228, s[2:3]
	s_add_u32 m0, s26, 20480
	s_nop 0
	global_load_lds_dwordx4 v229, s[2:3]
	s_add_u32 s0, s0, 64
	s_addc_u32 s1, s1, 0
	s_add_u32 s2, s2, 64
	s_addc_u32 s3, s3, 0
	s_add_u32 s99, s99, 1
	s_add_u32 s30, s30, 24576
	s_cmp_eq_u32 s30, 73728
	s_cselect_b32 s30, 0, s30
	s_add_u32 s26, s30, s100
	s_add_u32 m0, s26, 0
	s_nop 0
	global_load_lds_dwordx4 v224, s[0:1]
	s_add_u32 m0, s26, 4096
	s_nop 0
	global_load_lds_dwordx4 v225, s[0:1]
	s_add_u32 m0, s26, 8192
	s_nop 0
	global_load_lds_dwordx4 v226, s[0:1]
	s_add_u32 m0, s26, 12288
	s_nop 0
	global_load_lds_dwordx4 v227, s[0:1]
	s_add_u32 m0, s26, 16384
	s_nop 0
	global_load_lds_dwordx4 v228, s[2:3]
	s_add_u32 m0, s26, 20480
	s_nop 0
	global_load_lds_dwordx4 v229, s[2:3]
	s_add_u32 s0, s0, 64
	s_addc_u32 s1, s1, 0
	s_add_u32 s2, s2, 64
	s_addc_u32 s3, s3, 0
	s_add_u32 s99, s99, 1
	s_add_u32 s30, s30, 24576
	s_cmp_eq_u32 s30, 73728
	s_cselect_b32 s30, 0, s30
	v_mov_b32_e32 v0, 0
	v_mov_b32_e32 v1, 0
	v_mov_b32_e32 v2, 0
	v_mov_b32_e32 v3, 0
	v_mov_b32_e32 v4, 0
	v_mov_b32_e32 v5, 0
	v_mov_b32_e32 v6, 0
	v_mov_b32_e32 v7, 0
	v_mov_b32_e32 v8, 0
	v_mov_b32_e32 v9, 0
	v_mov_b32_e32 v10, 0
	v_mov_b32_e32 v11, 0
	v_mov_b32_e32 v12, 0
	v_mov_b32_e32 v13, 0
	v_mov_b32_e32 v14, 0
	v_mov_b32_e32 v15, 0
	v_mov_b32_e32 v16, 0
	v_mov_b32_e32 v17, 0
	v_mov_b32_e32 v18, 0
	v_mov_b32_e32 v19, 0
	v_mov_b32_e32 v20, 0
	v_mov_b32_e32 v21, 0
	v_mov_b32_e32 v22, 0
	v_mov_b32_e32 v23, 0
	v_mov_b32_e32 v24, 0
	v_mov_b32_e32 v25, 0
	v_mov_b32_e32 v26, 0
	v_mov_b32_e32 v27, 0
	v_mov_b32_e32 v28, 0
	v_mov_b32_e32 v29, 0
	v_mov_b32_e32 v30, 0
	v_mov_b32_e32 v31, 0
	v_mov_b32_e32 v32, 0
	v_mov_b32_e32 v33, 0
	v_mov_b32_e32 v34, 0
	v_mov_b32_e32 v35, 0
	v_mov_b32_e32 v36, 0
	v_mov_b32_e32 v37, 0
	v_mov_b32_e32 v38, 0
	v_mov_b32_e32 v39, 0
	v_mov_b32_e32 v40, 0
	v_mov_b32_e32 v41, 0
	v_mov_b32_e32 v42, 0
	v_mov_b32_e32 v43, 0
	v_mov_b32_e32 v44, 0
	v_mov_b32_e32 v45, 0
	v_mov_b32_e32 v46, 0
	v_mov_b32_e32 v47, 0
	v_mov_b32_e32 v48, 0
	v_mov_b32_e32 v49, 0
	v_mov_b32_e32 v50, 0
	v_mov_b32_e32 v51, 0
	v_mov_b32_e32 v52, 0
	v_mov_b32_e32 v53, 0
	v_mov_b32_e32 v54, 0
	v_mov_b32_e32 v55, 0
	v_mov_b32_e32 v56, 0
	v_mov_b32_e32 v57, 0
	v_mov_b32_e32 v58, 0
	v_mov_b32_e32 v59, 0
	v_mov_b32_e32 v60, 0
	v_mov_b32_e32 v61, 0
	v_mov_b32_e32 v62, 0
	v_mov_b32_e32 v63, 0
	v_mov_b32_e32 v64, 0
	v_mov_b32_e32 v65, 0
	v_mov_b32_e32 v66, 0
	v_mov_b32_e32 v67, 0
	v_mov_b32_e32 v68, 0
	v_mov_b32_e32 v69, 0
	v_mov_b32_e32 v70, 0
	v_mov_b32_e32 v71, 0
	v_mov_b32_e32 v72, 0
	v_mov_b32_e32 v73, 0
	v_mov_b32_e32 v74, 0
	v_mov_b32_e32 v75, 0
	v_mov_b32_e32 v76, 0
	v_mov_b32_e32 v77, 0
	v_mov_b32_e32 v78, 0
	v_mov_b32_e32 v79, 0
	v_mov_b32_e32 v80, 0
	v_mov_b32_e32 v81, 0
	v_mov_b32_e32 v82, 0
	v_mov_b32_e32 v83, 0
	v_mov_b32_e32 v84, 0
	v_mov_b32_e32 v85, 0
	v_mov_b32_e32 v86, 0
	v_mov_b32_e32 v87, 0
	v_mov_b32_e32 v88, 0
	v_mov_b32_e32 v89, 0
	v_mov_b32_e32 v90, 0
	v_mov_b32_e32 v91, 0
	v_mov_b32_e32 v92, 0
	v_mov_b32_e32 v93, 0
	v_mov_b32_e32 v94, 0
	v_mov_b32_e32 v95, 0
	v_mov_b32_e32 v96, 0
	v_mov_b32_e32 v97, 0
	v_mov_b32_e32 v98, 0
	v_mov_b32_e32 v99, 0
	v_mov_b32_e32 v100, 0
	v_mov_b32_e32 v101, 0
	v_mov_b32_e32 v102, 0
	v_mov_b32_e32 v103, 0
	v_mov_b32_e32 v104, 0
	v_mov_b32_e32 v105, 0
	v_mov_b32_e32 v106, 0
	v_mov_b32_e32 v107, 0
	v_mov_b32_e32 v108, 0
	v_mov_b32_e32 v109, 0
	v_mov_b32_e32 v110, 0
	v_mov_b32_e32 v111, 0
	v_mov_b32_e32 v112, 0
	v_mov_b32_e32 v113, 0
	v_mov_b32_e32 v114, 0
	v_mov_b32_e32 v115, 0
	v_mov_b32_e32 v116, 0
	v_mov_b32_e32 v117, 0
	v_mov_b32_e32 v118, 0
	v_mov_b32_e32 v119, 0
	v_mov_b32_e32 v120, 0
	v_mov_b32_e32 v121, 0
	v_mov_b32_e32 v122, 0
	v_mov_b32_e32 v123, 0
	v_mov_b32_e32 v124, 0
	v_mov_b32_e32 v125, 0
	v_mov_b32_e32 v126, 0
	v_mov_b32_e32 v127, 0
	s_mov_b32 s98, 0
	s_mov_b32 s31, 24576
	s_waitcnt vmcnt(6)
	s_barrier
	ds_read_b128 v[128:131], v231 offset:0
	ds_read_b128 v[132:135], v231 offset:1024
	ds_read_b128 v[136:139], v231 offset:2048
	ds_read_b128 v[140:143], v231 offset:3072
	ds_read_b128 v[144:147], v230 offset:0
	ds_read_b128 v[148:151], v230 offset:1024
	ds_read_b128 v[152:155], v230 offset:2048
	ds_read_b128 v[156:159], v230 offset:3072
	ds_read_b128 v[160:163], v230 offset:4096
	ds_read_b128 v[164:167], v230 offset:5120
	ds_read_b128 v[168:171], v230 offset:6144
	ds_read_b128 v[172:175], v230 offset:7168
	s_waitcnt vmcnt(0)
	s_waitcnt lgkmcnt(0)
	s_barrier
	v_add_u32_e32 v232, s31, v230
	v_add_u32_e32 v233, s31, v231
	s_setprio 1
	v_mfma_f32_16x16x32_bf16 v[0:3], v[128:131], v[144:147], v[0:3]
	v_mfma_f32_16x16x32_bf16 v[4:7], v[132:135], v[144:147], v[4:7]
	v_mfma_f32_16x16x32_bf16 v[8:11], v[136:139], v[144:147], v[8:11]
	v_mfma_f32_16x16x32_bf16 v[12:15], v[140:143], v[144:147], v[12:15]
	ds_read_b128 v[176:179], v233 offset:0
	ds_read_b128 v[180:183], v233 offset:1024
	v_mfma_f32_16x16x32_bf16 v[16:19], v[128:131], v[148:151], v[16:19]
	v_mfma_f32_16x16x32_bf16 v[20:23], v[132:135], v[148:151], v[20:23]
	v_mfma_f32_16x16x32_bf16 v[24:27], v[136:139], v[148:151], v[24:27]
	v_mfma_f32_16x16x32_bf16 v[28:31], v[140:143], v[148:151], v[28:31]
	ds_read_b128 v[184:187], v233 offset:2048
	ds_read_b128 v[188:191], v233 offset:3072
	v_mfma_f32_16x16x32_bf16 v[32:35], v[128:131], v[152:155], v[32:35]
	v_mfma_f32_16x16x32_bf16 v[36:39], v[132:135], v[152:155], v[36:39]
	v_mfma_f32_16x16x32_bf16 v[40:43], v[136:139], v[152:155], v[40:43]
	v_mfma_f32_16x16x32_bf16 v[44:47], v[140:143], v[152:155], v[44:47]
	ds_read_b128 v[192:195], v232 offset:0
	ds_read_b128 v[196:199], v232 offset:1024
	v_mfma_f32_16x16x32_bf16 v[48:51], v[128:131], v[156:159], v[48:51]
	v_mfma_f32_16x16x32_bf16 v[52:55], v[132:135], v[156:159], v[52:55]
	v_mfma_f32_16x16x32_bf16 v[56:59], v[136:139], v[156:159], v[56:59]
	v_mfma_f32_16x16x32_bf16 v[60:63], v[140:143], v[156:159], v[60:63]
	ds_read_b128 v[200:203], v232 offset:2048
	ds_read_b128 v[204:207], v232 offset:3072
	s_cmp_eq_u32 s25, 0
	s_cbranch_scc0 .Lg3a_hi0
	s_setprio 0
; #define LWRITE(S, buf) do { bf16_t* sA_ = sbase + (buf) * BUF; bf16_t* sB_ = sA_ + 256 * PITCH; \
;     _Pragma("unroll") for (int i_ = 0; i_ < 4; ++i_) *(u32x4*)(sA_ + (sr + i_ * 64) * PITCH + scv * 8) = ra[S][i_]; \
;     _Pragma("unroll") for (int i_ = 0; i_ < 2; ++i_) *(u32x4*)(sB_ + (sr + i_ * 64) * PITCH + scv * 8) = rb[S][i_]; } while (0)
; template <class Epi>
; DI void gemm_tile(char* smem, const bf16_t* __restrict__ A0, int lda0, int ksplit, const bf16_t* __restrict__ A1, int lda1,
;                   const bf16_t* __restrict__ Bt, int K, int row0, int col0, const Epi& epi, int tid) {
;     ...
;     for (int kt = 0; kt < nk; kt += 2) {
;       LWRITE(1, 1);
;       __builtin_amdgcn_sched_barrier(0);
;       GLOAD(1, (kt + 3 < last ? kt + 3 : last));
;       __builtin_amdgcn_sched_barrier(0);
;       COMPUTE(0);
;       __syncthreads();
;       LWRITE(0, 0);
;       __builtin_amdgcn_sched_barrier(0);
;       GLOAD(0, (kt + 4 < last ? kt + 4 : last));
;       __builtin_amdgcn_sched_barrier(0);
;       COMPUTE(1);
;       __syncthreads();
;     }
.Lg3a_hi0:
	v_mfma_f32_16x16x32_bf16 v[64:67], v[128:131], v[160:163], v[64:67]
	v_mfma_f32_16x16x32_bf16 v[68:71], v[132:135], v[160:163], v[68:71]
	v_mfma_f32_16x16x32_bf16 v[72:75], v[136:139], v[160:163], v[72:75]
	v_mfma_f32_16x16x32_bf16 v[76:79], v[140:143], v[160:163], v[76:79]
	ds_read_b128 v[208:211], v232 offset:4096
	v_mfma_f32_16x16x32_bf16 v[80:83], v[128:131], v[164:167], v[80:83]
	v_mfma_f32_16x16x32_bf16 v[84:87], v[132:135], v[164:167], v[84:87]
	v_mfma_f32_16x16x32_bf16 v[88:91], v[136:139], v[164:167], v[88:91]
	v_mfma_f32_16x16x32_bf16 v[92:95], v[140:143], v[164:167], v[92:95]
	ds_read_b128 v[212:215], v232 offset:5120
	v_mfma_f32_16x16x32_bf16 v[96:99], v[128:131], v[168:171], v[96:99]
	v_mfma_f32_16x16x32_bf16 v[100:103], v[132:135], v[168:171], v[100:103]
	v_mfma_f32_16x16x32_bf16 v[104:107], v[136:139], v[168:171], v[104:107]
	v_mfma_f32_16x16x32_bf16 v[108:111], v[140:143], v[168:171], v[108:111]
	ds_read_b128 v[216:219], v232 offset:6144
	s_add_u32 s31, s31, 24576
	s_cmp_eq_u32 s31, 73728
	s_cselect_b32 s31, 0, s31
	v_mfma_f32_16x16x32_bf16 v[112:115], v[128:131], v[172:175], v[112:115]
	v_mfma_f32_16x16x32_bf16 v[116:119], v[132:135], v[172:175], v[116:119]
	v_mfma_f32_16x16x32_bf16 v[120:123], v[136:139], v[172:175], v[120:123]
	v_mfma_f32_16x16x32_bf16 v[124:127], v[140:143], v[172:175], v[124:127]
	ds_read_b128 v[220:223], v232 offset:7168
	s_waitcnt lgkmcnt(0)
	s_barrier
	s_setprio 1
	v_mfma_f32_16x16x32_bf16 v[0:3], v[176:179], v[192:195], v[0:3]
	v_mfma_f32_16x16x32_bf16 v[4:7], v[180:183], v[192:195], v[4:7]
	v_mfma_f32_16x16x32_bf16 v[8:11], v[184:187], v[192:195], v[8:11]
	v_mfma_f32_16x16x32_bf16 v[12:15], v[188:191], v[192:195], v[12:15]
	v_mfma_f32_16x16x32_bf16 v[16:19], v[176:179], v[196:199], v[16:19]
	v_mfma_f32_16x16x32_bf16 v[20:23], v[180:183], v[196:199], v[20:23]
	v_mfma_f32_16x16x32_bf16 v[24:27], v[184:187], v[196:199], v[24:27]
	v_mfma_f32_16x16x32_bf16 v[28:31], v[188:191], v[196:199], v[28:31]
	v_mfma_f32_16x16x32_bf16 v[32:35], v[176:179], v[200:203], v[32:35]
	v_mfma_f32_16x16x32_bf16 v[36:39], v[180:183], v[200:203], v[36:39]
	v_mfma_f32_16x16x32_bf16 v[40:43], v[184:187], v[200:203], v[40:43]
	v_mfma_f32_16x16x32_bf16 v[44:47], v[188:191], v[200:203], v[44:47]
	v_mfma_f32_16x16x32_bf16 v[48:51], v[176:179], v[204:207], v[48:51]
	v_mfma_f32_16x16x32_bf16 v[52:55], v[180:183], v[204:207], v[52:55]
	v_mfma_f32_16x16x32_bf16 v[56:59], v[184:187], v[204:207], v[56:59]
	v_mfma_f32_16x16x32_bf16 v[60:63], v[188:191], v[204:207], v[60:63]
	s_cmp_eq_u32 s25, 0
	s_cbranch_scc0 .Lg3a_hi1
	s_setprio 0

; #define LWRITE(S, buf) do { bf16_t* sA_ = sbase + (buf) * BUF; bf16_t* sB_ = sA_ + 256 * PITCH; \
;     _Pragma("unroll") for (int i_ = 0; i_ < 4; ++i_) *(u32x4*)(sA_ + (sr + i_ * 64) * PITCH + scv * 8) = ra[S][i_]; \
;     _Pragma("unroll") for (int i_ = 0; i_ < 2; ++i_) *(u32x4*)(sB_ + (sr + i_ * 64) * PITCH + scv * 8) = rb[S][i_]; } while (0)
; template <class Epi>
; DI void gemm_tile(char* smem, const bf16_t* __restrict__ A0, int lda0, int ksplit, const bf16_t* __restrict__ A1, int lda1,
;                   const bf16_t* __restrict__ Bt, int K, int row0, int col0, const Epi& epi, int tid) {
;     ...
;   f32x4 acc[8][4];
; #pragma unroll
;   for (int m = 0; m < 8; ++m)
; #pragma unroll
;     for (int n = 0; n < 4; ++n) acc[m][n] = (f32x4){0.f, 0.f, 0.f, 0.f};
;   u32x4 ra[2][4], rb[2][2];
;   const int nk = K / BK;
;   const int sr = tid >> 2, scv = tid & 3;
;     ...
;   __syncthreads();
;   {
;     const int last = nk - 1;
;     GLOAD(0, 0);
;     __builtin_amdgcn_sched_barrier(0);
;     GLOAD(1, 1);
;     __builtin_amdgcn_sched_barrier(0);
;     LWRITE(0, 0);
;     __builtin_amdgcn_sched_barrier(0);
;     GLOAD(0, (2 < last ? 2 : last));
;     __builtin_amdgcn_sched_barrier(0);
;     __syncthreads();
; template <class Epi>
; DI void gemm_phase(char* smem, const bf16_t* A0, int lda0, int ksplit, const bf16_t* A1, int lda1, const bf16_t* Bt, int K, int nN, const Epi& epi, int tid) {
;     ...
;     const int x = blockIdx.x & 7, l = blockIdx.x >> 3, L = G >> 3, per = 8 * nN, tot = 2 * per;
;     for (int q = l; q < tot; q += L) { const int rgl = q / per, rem = q % per, ct = rem >> 3, rt = (x * 2 + rgl) * 8 + (rem & 7);
;       gemm_tile(smem, A0, lda0, ksplit, A1, lda1, Bt, K, rt * 256, ct * 128, epi, tid); }
.Lg3b_tile:
	s_cmpk_ge_u32 s15, 64
	s_cbranch_scc1 .Lg3b_done
	s_cmpk_ge_u32 s15, 32
	s_cselect_b32 s27, 1, 0
	s_cselect_b32 s26, 32, 0
	s_sub_u32 s26, s15, s26
	s_add_u32 s27, s27, s101
	s_lshl_b32 s27, s27, 3
	s_and_b32 s29, s26, 7
	s_add_u32 s29, s29, s27
	s_lshl_b32 s29, s29, 8
	s_lshr_b32 s28, s26, 3
	s_lshl_b32 s28, s28, 7
	s_mul_i32 s27, s29, 512
	s_add_u32 s27, s27, 0x1ea00000
	s_add_u32 s0, s92, s27
	s_addc_u32 s1, s93, 0
	s_mul_i32 s27, s28, 128
	s_add_u32 s27, s27, 0x34b0000
	s_add_u32 s2, s92, s27
	s_addc_u32 s3, s93, 0
	s_waitcnt lgkmcnt(0)
	s_barrier
	s_mov_b32 s99, 0
	s_mov_b32 s30, 0
	s_add_u32 s26, s30, s100
	s_add_u32 m0, s26, 0
	s_nop 0
	global_load_lds_dwordx4 v224, s[0:1]
	s_add_u32 m0, s26, 4096
	s_nop 0
	global_load_lds_dwordx4 v225, s[0:1]
	s_add_u32 m0, s26, 8192
	s_nop 0
	global_load_lds_dwordx4 v226, s[0:1]
	s_add_u32 m0, s26, 12288
	s_nop 0
	global_load_lds_dwordx4 v227, s[0:1]
	s_add_u32 m0, s26, 16384
	s_nop 0
	global_load_lds_dwordx4 v228, s[2:3]
	s_add_u32 m0, s26, 20480
	s_nop 0
	global_load_lds_dwordx4 v229, s[2:3]
	s_add_u32 s0, s0, 64
	s_addc_u32 s1, s1, 0
	s_add_u32 s2, s2, 64
	s_addc_u32 s3, s3, 0
	s_add_u32 s99, s99, 1
	s_add_u32 s30, s30, 24576
	s_cmp_eq_u32 s30, 73728
	s_cselect_b32 s30, 0, s30
	s_add_u32 s26, s30, s100
	s_add_u32 m0, s26, 0
	s_nop 0
	global_load_lds_dwordx4 v224, s[0:1]
	s_add_u32 m0, s26, 4096
	s_nop 0
	global_load_lds_dwordx4 v225, s[0:1]
	s_add_u32 m0, s26, 8192
	s_nop 0
	global_load_lds_dwordx4 v226, s[0:1]
	s_add_u32 m0, s26, 12288
	s_nop 0
	global_load_lds_dwordx4 v227, s[0:1]
	s_add_u32 m0, s26, 16384
	s_nop 0
	global_load_lds_dwordx4 v228, s[2:3]
	s_add_u32 m0, s26, 20480
	s_nop 0
	global_load_lds_dwordx4 v229, s[2:3]
	s_add_u32 s0, s0, 64
	s_addc_u32 s1, s1, 0
	s_add_u32 s2, s2, 64
	s_addc_u32 s3, s3, 0
	s_add_u32 s99, s99, 1
	s_add_u32 s30, s30, 24576
	s_cmp_eq_u32 s30, 73728
	s_cselect_b32 s30, 0, s30
	v_mov_b32_e32 v0, 0
	v_mov_b32_e32 v1, 0
	v_mov_b32_e32 v2, 0
	v_mov_b32_e32 v3, 0
	v_mov_b32_e32 v4, 0
	v_mov_b32_e32 v5, 0
	v_mov_b32_e32 v6, 0
	v_mov_b32_e32 v7, 0
	v_mov_b32_e32 v8, 0
	v_mov_b32_e32 v9, 0
	v_mov_b32_e32 v10, 0
	v_mov_b32_e32 v11, 0
	v_mov_b32_e32 v12, 0
	v_mov_b32_e32 v13, 0
	v_mov_b32_e32 v14, 0
	v_mov_b32_e32 v15, 0
	v_mov_b32_e32 v16, 0
	v_mov_b32_e32 v17, 0
	v_mov_b32_e32 v18, 0
	v_mov_b32_e32 v19, 0
	v_mov_b32_e32 v20, 0
	v_mov_b32_e32 v21, 0
	v_mov_b32_e32 v22, 0
	v_mov_b32_e32 v23, 0
	v_mov_b32_e32 v24, 0
	v_mov_b32_e32 v25, 0
	v_mov_b32_e32 v26, 0
	v_mov_b32_e32 v27, 0
	v_mov_b32_e32 v28, 0
	v_mov_b32_e32 v29, 0
	v_mov_b32_e32 v30, 0
	v_mov_b32_e32 v31, 0
	v_mov_b32_e32 v32, 0
	v_mov_b32_e32 v33, 0
	v_mov_b32_e32 v34, 0
	v_mov_b32_e32 v35, 0
	v_mov_b32_e32 v36, 0
	v_mov_b32_e32 v37, 0
	v_mov_b32_e32 v38, 0
	v_mov_b32_e32 v39, 0
	v_mov_b32_e32 v40, 0
	v_mov_b32_e32 v41, 0
	v_mov_b32_e32 v42, 0
	v_mov_b32_e32 v43, 0
	v_mov_b32_e32 v44, 0
	v_mov_b32_e32 v45, 0
	v_mov_b32_e32 v46, 0
	v_mov_b32_e32 v47, 0
	v_mov_b32_e32 v48, 0
	v_mov_b32_e32 v49, 0
	v_mov_b32_e32 v50, 0
	v_mov_b32_e32 v51, 0
	v_mov_b32_e32 v52, 0
	v_mov_b32_e32 v53, 0
	v_mov_b32_e32 v54, 0
	v_mov_b32_e32 v55, 0
	v_mov_b32_e32 v56, 0
	v_mov_b32_e32 v57, 0
	v_mov_b32_e32 v58, 0
	v_mov_b32_e32 v59, 0
	v_mov_b32_e32 v60, 0
	v_mov_b32_e32 v61, 0
	v_mov_b32_e32 v62, 0
	v_mov_b32_e32 v63, 0
	v_mov_b32_e32 v64, 0
	v_mov_b32_e32 v65, 0
	v_mov_b32_e32 v66, 0
	v_mov_b32_e32 v67, 0
	v_mov_b32_e32 v68, 0
	v_mov_b32_e32 v69, 0
	v_mov_b32_e32 v70, 0
	v_mov_b32_e32 v71, 0
	v_mov_b32_e32 v72, 0
	v_mov_b32_e32 v73, 0
	v_mov_b32_e32 v74, 0
	v_mov_b32_e32 v75, 0
	v_mov_b32_e32 v76, 0
	v_mov_b32_e32 v77, 0
	v_mov_b32_e32 v78, 0
	v_mov_b32_e32 v79, 0
	v_mov_b32_e32 v80, 0
	v_mov_b32_e32 v81, 0
	v_mov_b32_e32 v82, 0
	v_mov_b32_e32 v83, 0
	v_mov_b32_e32 v84, 0
	v_mov_b32_e32 v85, 0
	v_mov_b32_e32 v86, 0
	v_mov_b32_e32 v87, 0
	v_mov_b32_e32 v88, 0
	v_mov_b32_e32 v89, 0
	v_mov_b32_e32 v90, 0
	v_mov_b32_e32 v91, 0
	v_mov_b32_e32 v92, 0
	v_mov_b32_e32 v93, 0
	v_mov_b32_e32 v94, 0
	v_mov_b32_e32 v95, 0
	v_mov_b32_e32 v96, 0
	v_mov_b32_e32 v97, 0
	v_mov_b32_e32 v98, 0
	v_mov_b32_e32 v99, 0
	v_mov_b32_e32 v100, 0
	v_mov_b32_e32 v101, 0
	v_mov_b32_e32 v102, 0
	v_mov_b32_e32 v103, 0
	v_mov_b32_e32 v104, 0
	v_mov_b32_e32 v105, 0
	v_mov_b32_e32 v106, 0
	v_mov_b32_e32 v107, 0
	v_mov_b32_e32 v108, 0
	v_mov_b32_e32 v109, 0
	v_mov_b32_e32 v110, 0
	v_mov_b32_e32 v111, 0
	v_mov_b32_e32 v112, 0
	v_mov_b32_e32 v113, 0
	v_mov_b32_e32 v114, 0
	v_mov_b32_e32 v115, 0
	v_mov_b32_e32 v116, 0
	v_mov_b32_e32 v117, 0
	v_mov_b32_e32 v118, 0
	v_mov_b32_e32 v119, 0
	v_mov_b32_e32 v120, 0
	v_mov_b32_e32 v121, 0
	v_mov_b32_e32 v122, 0
	v_mov_b32_e32 v123, 0
	v_mov_b32_e32 v124, 0
	v_mov_b32_e32 v125, 0
	v_mov_b32_e32 v126, 0
	v_mov_b32_e32 v127, 0
	s_mov_b32 s98, 0
	s_mov_b32 s31, 24576
	s_waitcnt vmcnt(6)
	s_barrier
	ds_read_b128 v[128:131], v231 offset:0
	ds_read_b128 v[132:135], v231 offset:1024
	ds_read_b128 v[136:139], v231 offset:2048
	ds_read_b128 v[140:143], v231 offset:3072
	ds_read_b128 v[144:147], v230 offset:0
	ds_read_b128 v[148:151], v230 offset:1024
	ds_read_b128 v[152:155], v230 offset:2048
	ds_read_b128 v[156:159], v230 offset:3072
	ds_read_b128 v[160:163], v230 offset:4096
	ds_read_b128 v[164:167], v230 offset:5120
	ds_read_b128 v[168:171], v230 offset:6144
	ds_read_b128 v[172:175], v230 offset:7168
	s_waitcnt vmcnt(0)
	s_waitcnt lgkmcnt(0)
	s_barrier
	v_add_u32_e32 v232, s31, v230
	v_add_u32_e32 v233, s31, v231
	s_setprio 1
	v_mfma_f32_16x16x32_bf16 v[0:3], v[128:131], v[144:147], v[0:3]
	v_mfma_f32_16x16x32_bf16 v[4:7], v[132:135], v[144:147], v[4:7]
	v_mfma_f32_16x16x32_bf16 v[8:11], v[136:139], v[144:147], v[8:11]
	v_mfma_f32_16x16x32_bf16 v[12:15], v[140:143], v[144:147], v[12:15]
	ds_read_b128 v[176:179], v233 offset:0
	ds_read_b128 v[180:183], v233 offset:1024
	v_mfma_f32_16x16x32_bf16 v[16:19], v[128:131], v[148:151], v[16:19]
	v_mfma_f32_16x16x32_bf16 v[20:23], v[132:135], v[148:151], v[20:23]
	v_mfma_f32_16x16x32_bf16 v[24:27], v[136:139], v[148:151], v[24:27]
	v_mfma_f32_16x16x32_bf16 v[28:31], v[140:143], v[148:151], v[28:31]
	ds_read_b128 v[184:187], v233 offset:2048
	ds_read_b128 v[188:191], v233 offset:3072
	v_mfma_f32_16x16x32_bf16 v[32:35], v[128:131], v[152:155], v[32:35]
	v_mfma_f32_16x16x32_bf16 v[36:39], v[132:135], v[152:155], v[36:39]
	v_mfma_f32_16x16x32_bf16 v[40:43], v[136:139], v[152:155], v[40:43]
	v_mfma_f32_16x16x32_bf16 v[44:47], v[140:143], v[152:155], v[44:47]
	ds_read_b128 v[192:195], v232 offset:0
	ds_read_b128 v[196:199], v232 offset:1024
	v_mfma_f32_16x16x32_bf16 v[48:51], v[128:131], v[156:159], v[48:51]
	v_mfma_f32_16x16x32_bf16 v[52:55], v[132:135], v[156:159], v[52:55]
	v_mfma_f32_16x16x32_bf16 v[56:59], v[136:139], v[156:159], v[56:59]
	v_mfma_f32_16x16x32_bf16 v[60:63], v[140:143], v[156:159], v[60:63]
	ds_read_b128 v[200:203], v232 offset:2048
	ds_read_b128 v[204:207], v232 offset:3072
	s_cmp_eq_u32 s25, 0
	s_cbranch_scc0 .Lg3b_hi0
	s_setprio 0

; #define LWRITE(S, buf) do { bf16_t* sA_ = sbase + (buf) * BUF; bf16_t* sB_ = sA_ + 256 * PITCH; \
;     _Pragma("unroll") for (int i_ = 0; i_ < 4; ++i_) *(u32x4*)(sA_ + (sr + i_ * 64) * PITCH + scv * 8) = ra[S][i_]; \
;     _Pragma("unroll") for (int i_ = 0; i_ < 2; ++i_) *(u32x4*)(sB_ + (sr + i_ * 64) * PITCH + scv * 8) = rb[S][i_]; } while (0)
; template <class Epi>
; DI void gemm_tile(char* smem, const bf16_t* __restrict__ A0, int lda0, int ksplit, const bf16_t* __restrict__ A1, int lda1,
;                   const bf16_t* __restrict__ Bt, int K, int row0, int col0, const Epi& epi, int tid) {
;     ...
;   f32x4 acc[8][4];
; #pragma unroll
;   for (int m = 0; m < 8; ++m)
; #pragma unroll
;     for (int n = 0; n < 4; ++n) acc[m][n] = (f32x4){0.f, 0.f, 0.f, 0.f};
;   u32x4 ra[2][4], rb[2][2];
;   const int nk = K / BK;
;   const int sr = tid >> 2, scv = tid & 3;
;     ...
;   __syncthreads();
;   {
;     const int last = nk - 1;
;     GLOAD(0, 0);
;     __builtin_amdgcn_sched_barrier(0);
;     GLOAD(1, 1);
;     __builtin_amdgcn_sched_barrier(0);
;     LWRITE(0, 0);
;     __builtin_amdgcn_sched_barrier(0);
;     GLOAD(0, (2 < last ? 2 : last));
;     __builtin_amdgcn_sched_barrier(0);
;     __syncthreads();
; template <class Epi>
; DI void gemm_phase(char* smem, const bf16_t* A0, int lda0, int ksplit, const bf16_t* A1, int lda1, const bf16_t* Bt, int K, int nN, const Epi& epi, int tid) {
;     ...
;     const int x = blockIdx.x & 7, l = blockIdx.x >> 3, L = G >> 3, per = 8 * nN, tot = 2 * per;
;     for (int q = l; q < tot; q += L) { const int rgl = q / per, rem = q % per, ct = rem >> 3, rt = (x * 2 + rgl) * 8 + (rem & 7);
;       gemm_tile(smem, A0, lda0, ksplit, A1, lda1, Bt, K, rt * 256, ct * 128, epi, tid); }
.Lg3c_tile:
	s_cmpk_ge_u32 s15, 64
	s_cbranch_scc1 .Lg3c_done
	s_cmpk_ge_u32 s15, 32
	s_cselect_b32 s27, 1, 0
	s_cselect_b32 s26, 32, 0
	s_sub_u32 s26, s15, s26
	s_add_u32 s27, s27, s101
	s_lshl_b32 s27, s27, 3
	s_and_b32 s29, s26, 7
	s_add_u32 s29, s29, s27
	s_lshl_b32 s29, s29, 8
	s_lshr_b32 s28, s26, 3
	s_lshl_b32 s28, s28, 7
	s_mul_i32 s27, s29, 512
	s_add_u32 s27, s27, 0x1ea00080
	s_add_u32 s0, s92, s27
	s_addc_u32 s1, s93, 0
	s_mul_i32 s27, s28, 128
	s_add_u32 s27, s27, 0x34c0000
	s_add_u32 s2, s92, s27
	s_addc_u32 s3, s93, 0
	s_waitcnt lgkmcnt(0)
	s_barrier
	s_mov_b32 s99, 0
	s_mov_b32 s30, 0
	s_add_u32 s26, s30, s100
	s_add_u32 m0, s26, 0
	s_nop 0
	global_load_lds_dwordx4 v224, s[0:1]
	s_add_u32 m0, s26, 4096
	s_nop 0
	global_load_lds_dwordx4 v225, s[0:1]
	s_add_u32 m0, s26, 8192
	s_nop 0
	global_load_lds_dwordx4 v226, s[0:1]
	s_add_u32 m0, s26, 12288
	s_nop 0
	global_load_lds_dwordx4 v227, s[0:1]
	s_add_u32 m0, s26, 16384
	s_nop 0
	global_load_lds_dwordx4 v228, s[2:3]
	s_add_u32 m0, s26, 20480
	s_nop 0
	global_load_lds_dwordx4 v229, s[2:3]
	s_add_u32 s0, s0, 64
	s_addc_u32 s1, s1, 0
	s_add_u32 s2, s2, 64
	s_addc_u32 s3, s3, 0
	s_add_u32 s99, s99, 1
	s_add_u32 s30, s30, 24576
	s_cmp_eq_u32 s30, 73728
	s_cselect_b32 s30, 0, s30
	s_add_u32 s26, s30, s100
	s_add_u32 m0, s26, 0
	s_nop 0
	global_load_lds_dwordx4 v224, s[0:1]
	s_add_u32 m0, s26, 4096
	s_nop 0
	global_load_lds_dwordx4 v225, s[0:1]
	s_add_u32 m0, s26, 8192
	s_nop 0
	global_load_lds_dwordx4 v226, s[0:1]
	s_add_u32 m0, s26, 12288
	s_nop 0
	global_load_lds_dwordx4 v227, s[0:1]
	s_add_u32 m0, s26, 16384
	s_nop 0
	global_load_lds_dwordx4 v228, s[2:3]
	s_add_u32 m0, s26, 20480
	s_nop 0
	global_load_lds_dwordx4 v229, s[2:3]
	s_add_u32 s0, s0, 64
	s_addc_u32 s1, s1, 0
	s_add_u32 s2, s2, 64
	s_addc_u32 s3, s3, 0
	s_add_u32 s99, s99, 1
	s_add_u32 s30, s30, 24576
	s_cmp_eq_u32 s30, 73728
	s_cselect_b32 s30, 0, s30
	v_mov_b32_e32 v0, 0
	v_mov_b32_e32 v1, 0
	v_mov_b32_e32 v2, 0
	v_mov_b32_e32 v3, 0
	v_mov_b32_e32 v4, 0
	v_mov_b32_e32 v5, 0
	v_mov_b32_e32 v6, 0
	v_mov_b32_e32 v7, 0
	v_mov_b32_e32 v8, 0
	v_mov_b32_e32 v9, 0
	v_mov_b32_e32 v10, 0
	v_mov_b32_e32 v11, 0
	v_mov_b32_e32 v12, 0
	v_mov_b32_e32 v13, 0
	v_mov_b32_e32 v14, 0
	v_mov_b32_e32 v15, 0
	v_mov_b32_e32 v16, 0
	v_mov_b32_e32 v17, 0
	v_mov_b32_e32 v18, 0
	v_mov_b32_e32 v19, 0
	v_mov_b32_e32 v20, 0
	v_mov_b32_e32 v21, 0
	v_mov_b32_e32 v22, 0
	v_mov_b32_e32 v23, 0
	v_mov_b32_e32 v24, 0
	v_mov_b32_e32 v25, 0
	v_mov_b32_e32 v26, 0
	v_mov_b32_e32 v27, 0
	v_mov_b32_e32 v28, 0
	v_mov_b32_e32 v29, 0
	v_mov_b32_e32 v30, 0
	v_mov_b32_e32 v31, 0
	v_mov_b32_e32 v32, 0
	v_mov_b32_e32 v33, 0
	v_mov_b32_e32 v34, 0
	v_mov_b32_e32 v35, 0
	v_mov_b32_e32 v36, 0
	v_mov_b32_e32 v37, 0
	v_mov_b32_e32 v38, 0
	v_mov_b32_e32 v39, 0
	v_mov_b32_e32 v40, 0
	v_mov_b32_e32 v41, 0
	v_mov_b32_e32 v42, 0
	v_mov_b32_e32 v43, 0
	v_mov_b32_e32 v44, 0
	v_mov_b32_e32 v45, 0
	v_mov_b32_e32 v46, 0
	v_mov_b32_e32 v47, 0
	v_mov_b32_e32 v48, 0
	v_mov_b32_e32 v49, 0
	v_mov_b32_e32 v50, 0
	v_mov_b32_e32 v51, 0
	v_mov_b32_e32 v52, 0
	v_mov_b32_e32 v53, 0
	v_mov_b32_e32 v54, 0
	v_mov_b32_e32 v55, 0
	v_mov_b32_e32 v56, 0
	v_mov_b32_e32 v57, 0
	v_mov_b32_e32 v58, 0
	v_mov_b32_e32 v59, 0
	v_mov_b32_e32 v60, 0
	v_mov_b32_e32 v61, 0
	v_mov_b32_e32 v62, 0
	v_mov_b32_e32 v63, 0
	v_mov_b32_e32 v64, 0
	v_mov_b32_e32 v65, 0
	v_mov_b32_e32 v66, 0
	v_mov_b32_e32 v67, 0
	v_mov_b32_e32 v68, 0
	v_mov_b32_e32 v69, 0
	v_mov_b32_e32 v70, 0
	v_mov_b32_e32 v71, 0
	v_mov_b32_e32 v72, 0
	v_mov_b32_e32 v73, 0
	v_mov_b32_e32 v74, 0
	v_mov_b32_e32 v75, 0
	v_mov_b32_e32 v76, 0
	v_mov_b32_e32 v77, 0
	v_mov_b32_e32 v78, 0
	v_mov_b32_e32 v79, 0
	v_mov_b32_e32 v80, 0
	v_mov_b32_e32 v81, 0
	v_mov_b32_e32 v82, 0
	v_mov_b32_e32 v83, 0
	v_mov_b32_e32 v84, 0
	v_mov_b32_e32 v85, 0
	v_mov_b32_e32 v86, 0
	v_mov_b32_e32 v87, 0
	v_mov_b32_e32 v88, 0
	v_mov_b32_e32 v89, 0
	v_mov_b32_e32 v90, 0
	v_mov_b32_e32 v91, 0
	v_mov_b32_e32 v92, 0
	v_mov_b32_e32 v93, 0
	v_mov_b32_e32 v94, 0
	v_mov_b32_e32 v95, 0
	v_mov_b32_e32 v96, 0
	v_mov_b32_e32 v97, 0
	v_mov_b32_e32 v98, 0
	v_mov_b32_e32 v99, 0
	v_mov_b32_e32 v100, 0
	v_mov_b32_e32 v101, 0
	v_mov_b32_e32 v102, 0
	v_mov_b32_e32 v103, 0
	v_mov_b32_e32 v104, 0
	v_mov_b32_e32 v105, 0
	v_mov_b32_e32 v106, 0
	v_mov_b32_e32 v107, 0
	v_mov_b32_e32 v108, 0
	v_mov_b32_e32 v109, 0
	v_mov_b32_e32 v110, 0
	v_mov_b32_e32 v111, 0
	v_mov_b32_e32 v112, 0
	v_mov_b32_e32 v113, 0
	v_mov_b32_e32 v114, 0
	v_mov_b32_e32 v115, 0
	v_mov_b32_e32 v116, 0
	v_mov_b32_e32 v117, 0
	v_mov_b32_e32 v118, 0
	v_mov_b32_e32 v119, 0
	v_mov_b32_e32 v120, 0
	v_mov_b32_e32 v121, 0
	v_mov_b32_e32 v122, 0
	v_mov_b32_e32 v123, 0
	v_mov_b32_e32 v124, 0
	v_mov_b32_e32 v125, 0
	v_mov_b32_e32 v126, 0
	v_mov_b32_e32 v127, 0
	s_mov_b32 s98, 0
	s_mov_b32 s31, 24576
	s_waitcnt vmcnt(6)
	s_barrier
	ds_read_b128 v[128:131], v231 offset:0
	ds_read_b128 v[132:135], v231 offset:1024
	ds_read_b128 v[136:139], v231 offset:2048
	ds_read_b128 v[140:143], v231 offset:3072
	ds_read_b128 v[144:147], v230 offset:0
	ds_read_b128 v[148:151], v230 offset:1024
	ds_read_b128 v[152:155], v230 offset:2048
	ds_read_b128 v[156:159], v230 offset:3072
	ds_read_b128 v[160:163], v230 offset:4096
	ds_read_b128 v[164:167], v230 offset:5120
	ds_read_b128 v[168:171], v230 offset:6144
	ds_read_b128 v[172:175], v230 offset:7168
	s_waitcnt vmcnt(0)
	s_waitcnt lgkmcnt(0)
	s_barrier
	v_add_u32_e32 v232, s31, v230
	v_add_u32_e32 v233, s31, v231
	s_setprio 1
	v_mfma_f32_16x16x32_bf16 v[0:3], v[128:131], v[144:147], v[0:3]
	v_mfma_f32_16x16x32_bf16 v[4:7], v[132:135], v[144:147], v[4:7]
	v_mfma_f32_16x16x32_bf16 v[8:11], v[136:139], v[144:147], v[8:11]
	v_mfma_f32_16x16x32_bf16 v[12:15], v[140:143], v[144:147], v[12:15]
	ds_read_b128 v[176:179], v233 offset:0
	ds_read_b128 v[180:183], v233 offset:1024
	v_mfma_f32_16x16x32_bf16 v[16:19], v[128:131], v[148:151], v[16:19]
	v_mfma_f32_16x16x32_bf16 v[20:23], v[132:135], v[148:151], v[20:23]
	v_mfma_f32_16x16x32_bf16 v[24:27], v[136:139], v[148:151], v[24:27]
	v_mfma_f32_16x16x32_bf16 v[28:31], v[140:143], v[148:151], v[28:31]
	ds_read_b128 v[184:187], v233 offset:2048
	ds_read_b128 v[188:191], v233 offset:3072
	v_mfma_f32_16x16x32_bf16 v[32:35], v[128:131], v[152:155], v[32:35]
	v_mfma_f32_16x16x32_bf16 v[36:39], v[132:135], v[152:155], v[36:39]
	v_mfma_f32_16x16x32_bf16 v[40:43], v[136:139], v[152:155], v[40:43]
	v_mfma_f32_16x16x32_bf16 v[44:47], v[140:143], v[152:155], v[44:47]
	ds_read_b128 v[192:195], v232 offset:0
	ds_read_b128 v[196:199], v232 offset:1024
	v_mfma_f32_16x16x32_bf16 v[48:51], v[128:131], v[156:159], v[48:51]
	v_mfma_f32_16x16x32_bf16 v[52:55], v[132:135], v[156:159], v[52:55]
	v_mfma_f32_16x16x32_bf16 v[56:59], v[136:139], v[156:159], v[56:59]
	v_mfma_f32_16x16x32_bf16 v[60:63], v[140:143], v[156:159], v[60:63]
	ds_read_b128 v[200:203], v232 offset:2048
	ds_read_b128 v[204:207], v232 offset:3072
	s_cmp_eq_u32 s25, 0
	s_cbranch_scc0 .Lg3c_hi0
	s_setprio 0

; #define LWRITE(S, buf) do { bf16_t* sA_ = sbase + (buf) * BUF; bf16_t* sB_ = sA_ + 256 * PITCH; \
;     _Pragma("unroll") for (int i_ = 0; i_ < 4; ++i_) *(u32x4*)(sA_ + (sr + i_ * 64) * PITCH + scv * 8) = ra[S][i_]; \
;     _Pragma("unroll") for (int i_ = 0; i_ < 2; ++i_) *(u32x4*)(sB_ + (sr + i_ * 64) * PITCH + scv * 8) = rb[S][i_]; } while (0)
; template <class Epi>
; DI void gemm_tile(char* smem, const bf16_t* __restrict__ A0, int lda0, int ksplit, const bf16_t* __restrict__ A1, int lda1,
;                   const bf16_t* __restrict__ Bt, int K, int row0, int col0, const Epi& epi, int tid) {
;     ...
;   f32x4 acc[8][4];
; #pragma unroll
;   for (int m = 0; m < 8; ++m)
; #pragma unroll
;     for (int n = 0; n < 4; ++n) acc[m][n] = (f32x4){0.f, 0.f, 0.f, 0.f};
;   u32x4 ra[2][4], rb[2][2];
;   const int nk = K / BK;
;   const int sr = tid >> 2, scv = tid & 3;
;     ...
;   __syncthreads();
;   {
;     const int last = nk - 1;
;     GLOAD(0, 0);
;     __builtin_amdgcn_sched_barrier(0);
;     GLOAD(1, 1);
;     __builtin_amdgcn_sched_barrier(0);
;     LWRITE(0, 0);
;     __builtin_amdgcn_sched_barrier(0);
;     GLOAD(0, (2 < last ? 2 : last));
;     __builtin_amdgcn_sched_barrier(0);
;     __syncthreads();
; template <class Epi>
; DI void gemm_phase(char* smem, const bf16_t* A0, int lda0, int ksplit, const bf16_t* A1, int lda1, const bf16_t* Bt, int K, int nN, const Epi& epi, int tid) {
;     ...
;     const int x = blockIdx.x & 7, l = blockIdx.x >> 3, L = G >> 3, per = 8 * nN, tot = 2 * per;
;     for (int q = l; q < tot; q += L) { const int rgl = q / per, rem = q % per, ct = rem >> 3, rt = (x * 2 + rgl) * 8 + (rem & 7);
;       gemm_tile(smem, A0, lda0, ksplit, A1, lda1, Bt, K, rt * 256, ct * 128, epi, tid); }
.Lg3d_tile:
	s_cmpk_ge_u32 s15, 64
	s_cbranch_scc1 .Lg3d_done
	s_cmpk_ge_u32 s15, 32
	s_cselect_b32 s27, 1, 0
	s_cselect_b32 s26, 32, 0
	s_sub_u32 s26, s15, s26
	s_add_u32 s27, s27, s101
	s_lshl_b32 s27, s27, 3
	s_and_b32 s29, s26, 7
	s_add_u32 s29, s29, s27
	s_lshl_b32 s29, s29, 8
	s_lshr_b32 s28, s26, 3
	s_lshl_b32 s28, s28, 7
	s_mul_i32 s27, s29, 512
	s_add_u32 s27, s27, 0x1ea00100
	s_add_u32 s0, s92, s27
	s_addc_u32 s1, s93, 0
	s_mul_i32 s27, s28, 256
	s_add_u32 s27, s27, 0x3480000
	s_add_u32 s2, s92, s27
	s_addc_u32 s3, s93, 0
	s_waitcnt lgkmcnt(0)
	s_barrier
	s_mov_b32 s99, 0
	s_mov_b32 s30, 0
	s_add_u32 s26, s30, s100
	s_add_u32 m0, s26, 0
	s_nop 0
	global_load_lds_dwordx4 v224, s[0:1]
	s_add_u32 m0, s26, 4096
	s_nop 0
	global_load_lds_dwordx4 v225, s[0:1]
	s_add_u32 m0, s26, 8192
	s_nop 0
	global_load_lds_dwordx4 v226, s[0:1]
	s_add_u32 m0, s26, 12288
	s_nop 0
	global_load_lds_dwordx4 v227, s[0:1]
	s_add_u32 m0, s26, 16384
	s_nop 0
	global_load_lds_dwordx4 v228, s[2:3]
	s_add_u32 m0, s26, 20480
	s_nop 0
	global_load_lds_dwordx4 v229, s[2:3]
	s_add_u32 s0, s0, 64
	s_addc_u32 s1, s1, 0
	s_add_u32 s2, s2, 64
	s_addc_u32 s3, s3, 0
	s_add_u32 s99, s99, 1
	s_add_u32 s30, s30, 24576
	s_cmp_eq_u32 s30, 73728
	s_cselect_b32 s30, 0, s30
	s_add_u32 s26, s30, s100
	s_add_u32 m0, s26, 0
	s_nop 0
	global_load_lds_dwordx4 v224, s[0:1]
	s_add_u32 m0, s26, 4096
	s_nop 0
	global_load_lds_dwordx4 v225, s[0:1]
	s_add_u32 m0, s26, 8192
	s_nop 0
	global_load_lds_dwordx4 v226, s[0:1]
	s_add_u32 m0, s26, 12288
	s_nop 0
	global_load_lds_dwordx4 v227, s[0:1]
	s_add_u32 m0, s26, 16384
	s_nop 0
	global_load_lds_dwordx4 v228, s[2:3]
	s_add_u32 m0, s26, 20480
	s_nop 0
	global_load_lds_dwordx4 v229, s[2:3]
	s_add_u32 s0, s0, 64
	s_addc_u32 s1, s1, 0
	s_add_u32 s2, s2, 64
	s_addc_u32 s3, s3, 0
	s_add_u32 s99, s99, 1
	s_add_u32 s30, s30, 24576
	s_cmp_eq_u32 s30, 73728
	s_cselect_b32 s30, 0, s30
	s_add_u32 s26, s30, s100
	s_add_u32 m0, s26, 0
	s_nop 0
	global_load_lds_dwordx4 v224, s[0:1]
	s_add_u32 m0, s26, 4096
	s_nop 0
	global_load_lds_dwordx4 v225, s[0:1]
	s_add_u32 m0, s26, 8192
	s_nop 0
	global_load_lds_dwordx4 v226, s[0:1]
	s_add_u32 m0, s26, 12288
	s_nop 0
	global_load_lds_dwordx4 v227, s[0:1]
	s_add_u32 m0, s26, 16384
	s_nop 0
	global_load_lds_dwordx4 v228, s[2:3]
	s_add_u32 m0, s26, 20480
	s_nop 0
	global_load_lds_dwordx4 v229, s[2:3]
	s_add_u32 s0, s0, 64
	s_addc_u32 s1, s1, 0
	s_add_u32 s2, s2, 64
	s_addc_u32 s3, s3, 0
	s_add_u32 s99, s99, 1
	s_add_u32 s30, s30, 24576
	s_cmp_eq_u32 s30, 73728
	s_cselect_b32 s30, 0, s30
	v_mov_b32_e32 v0, 0
	v_mov_b32_e32 v1, 0
	v_mov_b32_e32 v2, 0
	v_mov_b32_e32 v3, 0
	v_mov_b32_e32 v4, 0
	v_mov_b32_e32 v5, 0
	v_mov_b32_e32 v6, 0
	v_mov_b32_e32 v7, 0
	v_mov_b32_e32 v8, 0
	v_mov_b32_e32 v9, 0
	v_mov_b32_e32 v10, 0
	v_mov_b32_e32 v11, 0
	v_mov_b32_e32 v12, 0
	v_mov_b32_e32 v13, 0
	v_mov_b32_e32 v14, 0
	v_mov_b32_e32 v15, 0
	v_mov_b32_e32 v16, 0
	v_mov_b32_e32 v17, 0
	v_mov_b32_e32 v18, 0
	v_mov_b32_e32 v19, 0
	v_mov_b32_e32 v20, 0
	v_mov_b32_e32 v21, 0
	v_mov_b32_e32 v22, 0
	v_mov_b32_e32 v23, 0
	v_mov_b32_e32 v24, 0
	v_mov_b32_e32 v25, 0
	v_mov_b32_e32 v26, 0
	v_mov_b32_e32 v27, 0
	v_mov_b32_e32 v28, 0
	v_mov_b32_e32 v29, 0
	v_mov_b32_e32 v30, 0
	v_mov_b32_e32 v31, 0
	v_mov_b32_e32 v32, 0
	v_mov_b32_e32 v33, 0
	v_mov_b32_e32 v34, 0
	v_mov_b32_e32 v35, 0
	v_mov_b32_e32 v36, 0
	v_mov_b32_e32 v37, 0
	v_mov_b32_e32 v38, 0
	v_mov_b32_e32 v39, 0
	v_mov_b32_e32 v40, 0
	v_mov_b32_e32 v41, 0
	v_mov_b32_e32 v42, 0
	v_mov_b32_e32 v43, 0
	v_mov_b32_e32 v44, 0
	v_mov_b32_e32 v45, 0
	v_mov_b32_e32 v46, 0
	v_mov_b32_e32 v47, 0
	v_mov_b32_e32 v48, 0
	v_mov_b32_e32 v49, 0
	v_mov_b32_e32 v50, 0
	v_mov_b32_e32 v51, 0
	v_mov_b32_e32 v52, 0
	v_mov_b32_e32 v53, 0
	v_mov_b32_e32 v54, 0
	v_mov_b32_e32 v55, 0
	v_mov_b32_e32 v56, 0
	v_mov_b32_e32 v57, 0
	v_mov_b32_e32 v58, 0
	v_mov_b32_e32 v59, 0
	v_mov_b32_e32 v60, 0
	v_mov_b32_e32 v61, 0
	v_mov_b32_e32 v62, 0
	v_mov_b32_e32 v63, 0
	v_mov_b32_e32 v64, 0
	v_mov_b32_e32 v65, 0
	v_mov_b32_e32 v66, 0
	v_mov_b32_e32 v67, 0
	v_mov_b32_e32 v68, 0
	v_mov_b32_e32 v69, 0
	v_mov_b32_e32 v70, 0
	v_mov_b32_e32 v71, 0
	v_mov_b32_e32 v72, 0
	v_mov_b32_e32 v73, 0
	v_mov_b32_e32 v74, 0
	v_mov_b32_e32 v75, 0
	v_mov_b32_e32 v76, 0
	v_mov_b32_e32 v77, 0
	v_mov_b32_e32 v78, 0
	v_mov_b32_e32 v79, 0
	v_mov_b32_e32 v80, 0
	v_mov_b32_e32 v81, 0
	v_mov_b32_e32 v82, 0
	v_mov_b32_e32 v83, 0
	v_mov_b32_e32 v84, 0
	v_mov_b32_e32 v85, 0
	v_mov_b32_e32 v86, 0
	v_mov_b32_e32 v87, 0
	v_mov_b32_e32 v88, 0
	v_mov_b32_e32 v89, 0
	v_mov_b32_e32 v90, 0
	v_mov_b32_e32 v91, 0
	v_mov_b32_e32 v92, 0
	v_mov_b32_e32 v93, 0
	v_mov_b32_e32 v94, 0
	v_mov_b32_e32 v95, 0
	v_mov_b32_e32 v96, 0
	v_mov_b32_e32 v97, 0
	v_mov_b32_e32 v98, 0
	v_mov_b32_e32 v99, 0
	v_mov_b32_e32 v100, 0
	v_mov_b32_e32 v101, 0
	v_mov_b32_e32 v102, 0
	v_mov_b32_e32 v103, 0
	v_mov_b32_e32 v104, 0
	v_mov_b32_e32 v105, 0
	v_mov_b32_e32 v106, 0
	v_mov_b32_e32 v107, 0
	v_mov_b32_e32 v108, 0
	v_mov_b32_e32 v109, 0
	v_mov_b32_e32 v110, 0
	v_mov_b32_e32 v111, 0
	v_mov_b32_e32 v112, 0
	v_mov_b32_e32 v113, 0
	v_mov_b32_e32 v114, 0
	v_mov_b32_e32 v115, 0
	v_mov_b32_e32 v116, 0
	v_mov_b32_e32 v117, 0
	v_mov_b32_e32 v118, 0
	v_mov_b32_e32 v119, 0
	v_mov_b32_e32 v120, 0
	v_mov_b32_e32 v121, 0
	v_mov_b32_e32 v122, 0
	v_mov_b32_e32 v123, 0
	v_mov_b32_e32 v124, 0
	v_mov_b32_e32 v125, 0
	v_mov_b32_e32 v126, 0
	v_mov_b32_e32 v127, 0
	s_mov_b32 s98, 0
	s_mov_b32 s31, 24576
	s_waitcnt vmcnt(12)
	s_barrier
; #define LWRITE(S, buf) do { bf16_t* sA_ = sbase + (buf) * BUF; bf16_t* sB_ = sA_ + 256 * PITCH; \
;     _Pragma("unroll") for (int i_ = 0; i_ < 4; ++i_) *(u32x4*)(sA_ + (sr + i_ * 64) * PITCH + scv * 8) = ra[S][i_]; \
;     _Pragma("unroll") for (int i_ = 0; i_ < 2; ++i_) *(u32x4*)(sB_ + (sr + i_ * 64) * PITCH + scv * 8) = rb[S][i_]; } while (0)
; template <class Epi>
; DI void gemm_tile(char* smem, const bf16_t* __restrict__ A0, int lda0, int ksplit, const bf16_t* __restrict__ A1, int lda1,
;                   const bf16_t* __restrict__ Bt, int K, int row0, int col0, const Epi& epi, int tid) {
;     ...
;     for (int kt = 0; kt < nk; kt += 2) {
;       LWRITE(1, 1);
;       __builtin_amdgcn_sched_barrier(0);
;       GLOAD(1, (kt + 3 < last ? kt + 3 : last));
;       __builtin_amdgcn_sched_barrier(0);
;       COMPUTE(0);
;       __syncthreads();
;       LWRITE(0, 0);
;       __builtin_amdgcn_sched_barrier(0);
;       GLOAD(0, (kt + 4 < last ? kt + 4 : last));
;       __builtin_amdgcn_sched_barrier(0);
;       COMPUTE(1);
;       __syncthreads();
;     }
	ds_read_b128 v[128:131], v231 offset:0
	ds_read_b128 v[132:135], v231 offset:1024
	ds_read_b128 v[136:139], v231 offset:2048
	ds_read_b128 v[140:143], v231 offset:3072
	ds_read_b128 v[144:147], v230 offset:0
	ds_read_b128 v[148:151], v230 offset:1024
	ds_read_b128 v[152:155], v230 offset:2048
	ds_read_b128 v[156:159], v230 offset:3072
	ds_read_b128 v[160:163], v230 offset:4096
	ds_read_b128 v[164:167], v230 offset:5120
	ds_read_b128 v[168:171], v230 offset:6144
	ds_read_b128 v[172:175], v230 offset:7168
	s_waitcnt vmcnt(6)
	s_waitcnt lgkmcnt(0)
	s_barrier
	v_add_u32_e32 v232, s31, v230
	v_add_u32_e32 v233, s31, v231
	s_add_u32 s26, s30, s100
	s_setprio 1
	v_mfma_f32_16x16x32_bf16 v[0:3], v[128:131], v[144:147], v[0:3]
	v_mfma_f32_16x16x32_bf16 v[4:7], v[132:135], v[144:147], v[4:7]
	v_mfma_f32_16x16x32_bf16 v[8:11], v[136:139], v[144:147], v[8:11]
	v_mfma_f32_16x16x32_bf16 v[12:15], v[140:143], v[144:147], v[12:15]
	ds_read_b128 v[176:179], v233 offset:0
	ds_read_b128 v[180:183], v233 offset:1024
	s_add_u32 m0, s26, 0
	s_nop 0
	global_load_lds_dwordx4 v224, s[0:1]
	v_mfma_f32_16x16x32_bf16 v[16:19], v[128:131], v[148:151], v[16:19]
	v_mfma_f32_16x16x32_bf16 v[20:23], v[132:135], v[148:151], v[20:23]
	v_mfma_f32_16x16x32_bf16 v[24:27], v[136:139], v[148:151], v[24:27]
	v_mfma_f32_16x16x32_bf16 v[28:31], v[140:143], v[148:151], v[28:31]
	ds_read_b128 v[184:187], v233 offset:2048
	ds_read_b128 v[188:191], v233 offset:3072
	s_add_u32 m0, s26, 4096
	s_nop 0
	global_load_lds_dwordx4 v225, s[0:1]
	v_mfma_f32_16x16x32_bf16 v[32:35], v[128:131], v[152:155], v[32:35]
	v_mfma_f32_16x16x32_bf16 v[36:39], v[132:135], v[152:155], v[36:39]
	v_mfma_f32_16x16x32_bf16 v[40:43], v[136:139], v[152:155], v[40:43]
	v_mfma_f32_16x16x32_bf16 v[44:47], v[140:143], v[152:155], v[44:47]
	ds_read_b128 v[192:195], v232 offset:0
	ds_read_b128 v[196:199], v232 offset:1024
	s_add_u32 m0, s26, 8192
	s_nop 0
	global_load_lds_dwordx4 v226, s[0:1]
	v_mfma_f32_16x16x32_bf16 v[48:51], v[128:131], v[156:159], v[48:51]
	v_mfma_f32_16x16x32_bf16 v[52:55], v[132:135], v[156:159], v[52:55]
	v_mfma_f32_16x16x32_bf16 v[56:59], v[136:139], v[156:159], v[56:59]
	v_mfma_f32_16x16x32_bf16 v[60:63], v[140:143], v[156:159], v[60:63]
	ds_read_b128 v[200:203], v232 offset:2048
	ds_read_b128 v[204:207], v232 offset:3072
	s_add_u32 m0, s26, 12288
	s_nop 0
	global_load_lds_dwordx4 v227, s[0:1]
	s_cmp_eq_u32 s25, 0
	s_cbranch_scc0 .Lg3d_hi0
	s_setprio 0
.Lg3d_hi0:
	v_mfma_f32_16x16x32_bf16 v[64:67], v[128:131], v[160:163], v[64:67]
	v_mfma_f32_16x16x32_bf16 v[68:71], v[132:135], v[160:163], v[68:71]
	v_mfma_f32_16x16x32_bf16 v[72:75], v[136:139], v[160:163], v[72:75]
	v_mfma_f32_16x16x32_bf16 v[76:79], v[140:143], v[160:163], v[76:79]
	ds_read_b128 v[208:211], v232 offset:4096
	s_add_u32 m0, s26, 16384
	s_nop 0
	global_load_lds_dwordx4 v228, s[2:3]
	v_mfma_f32_16x16x32_bf16 v[80:83], v[128:131], v[164:167], v[80:83]
	v_mfma_f32_16x16x32_bf16 v[84:87], v[132:135], v[164:167], v[84:87]
	v_mfma_f32_16x16x32_bf16 v[88:91], v[136:139], v[164:167], v[88:91]
	v_mfma_f32_16x16x32_bf16 v[92:95], v[140:143], v[164:167], v[92:95]
	ds_read_b128 v[212:215], v232 offset:5120
	s_add_u32 m0, s26, 20480
	s_nop 0
	global_load_lds_dwordx4 v229, s[2:3]
	v_mfma_f32_16x16x32_bf16 v[96:99], v[128:131], v[168:171], v[96:99]
	v_mfma_f32_16x16x32_bf16 v[100:103], v[132:135], v[168:171], v[100:103]
	v_mfma_f32_16x16x32_bf16 v[104:107], v[136:139], v[168:171], v[104:107]
	v_mfma_f32_16x16x32_bf16 v[108:111], v[140:143], v[168:171], v[108:111]
	ds_read_b128 v[216:219], v232 offset:6144
	s_add_u32 s0, s0, 64
	s_addc_u32 s1, s1, 0
	s_add_u32 s2, s2, 64
	s_addc_u32 s3, s3, 0
	s_add_u32 s99, s99, 1
	s_add_u32 s30, s30, 24576
	s_cmp_eq_u32 s30, 73728
	s_cselect_b32 s30, 0, s30
	s_add_u32 s31, s31, 24576
	s_cmp_eq_u32 s31, 73728
	s_cselect_b32 s31, 0, s31
	v_mfma_f32_16x16x32_bf16 v[112:115], v[128:131], v[172:175], v[112:115]
	v_mfma_f32_16x16x32_bf16 v[116:119], v[132:135], v[172:175], v[116:119]
	v_mfma_f32_16x16x32_bf16 v[120:123], v[136:139], v[172:175], v[120:123]
	v_mfma_f32_16x16x32_bf16 v[124:127], v[140:143], v[172:175], v[124:127]
	ds_read_b128 v[220:223], v232 offset:7168
	s_waitcnt vmcnt(6)
	s_waitcnt lgkmcnt(0)
	s_barrier
	v_add_u32_e32 v232, s31, v230
	v_add_u32_e32 v233, s31, v231
	s_setprio 1
	v_mfma_f32_16x16x32_bf16 v[0:3], v[176:179], v[192:195], v[0:3]
	v_mfma_f32_16x16x32_bf16 v[4:7], v[180:183], v[192:195], v[4:7]
	v_mfma_f32_16x16x32_bf16 v[8:11], v[184:187], v[192:195], v[8:11]
	v_mfma_f32_16x16x32_bf16 v[12:15], v[188:191], v[192:195], v[12:15]
	ds_read_b128 v[128:131], v233 offset:0
	ds_read_b128 v[132:135], v233 offset:1024
	v_mfma_f32_16x16x32_bf16 v[16:19], v[176:179], v[196:199], v[16:19]
	v_mfma_f32_16x16x32_bf16 v[20:23], v[180:183], v[196:199], v[20:23]
	v_mfma_f32_16x16x32_bf16 v[24:27], v[184:187], v[196:199], v[24:27]
	v_mfma_f32_16x16x32_bf16 v[28:31], v[188:191], v[196:199], v[28:31]
	ds_read_b128 v[136:139], v233 offset:2048
	ds_read_b128 v[140:143], v233 offset:3072
	v_mfma_f32_16x16x32_bf16 v[32:35], v[176:179], v[200:203], v[32:35]
	v_mfma_f32_16x16x32_bf16 v[36:39], v[180:183], v[200:203], v[36:39]
	v_mfma_f32_16x16x32_bf16 v[40:43], v[184:187], v[200:203], v[40:43]
	v_mfma_f32_16x16x32_bf16 v[44:47], v[188:191], v[200:203], v[44:47]
	ds_read_b128 v[144:147], v232 offset:0
	ds_read_b128 v[148:151], v232 offset:1024
	v_mfma_f32_16x16x32_bf16 v[48:51], v[176:179], v[204:207], v[48:51]
	v_mfma_f32_16x16x32_bf16 v[52:55], v[180:183], v[204:207], v[52:55]
	v_mfma_f32_16x16x32_bf16 v[56:59], v[184:187], v[204:207], v[56:59]
	v_mfma_f32_16x16x32_bf16 v[60:63], v[188:191], v[204:207], v[60:63]
	ds_read_b128 v[152:155], v232 offset:2048
	ds_read_b128 v[156:159], v232 offset:3072
	s_cmp_eq_u32 s25, 0
	s_cbranch_scc0 .Lg3d_hi1
	s_setprio 0
; #define LWRITE(S, buf) do { bf16_t* sA_ = sbase + (buf) * BUF; bf16_t* sB_ = sA_ + 256 * PITCH; \
;     _Pragma("unroll") for (int i_ = 0; i_ < 4; ++i_) *(u32x4*)(sA_ + (sr + i_ * 64) * PITCH + scv * 8) = ra[S][i_]; \
;     _Pragma("unroll") for (int i_ = 0; i_ < 2; ++i_) *(u32x4*)(sB_ + (sr + i_ * 64) * PITCH + scv * 8) = rb[S][i_]; } while (0)
; template <class Epi>
; DI void gemm_tile(char* smem, const bf16_t* __restrict__ A0, int lda0, int ksplit, const bf16_t* __restrict__ A1, int lda1,
;                   const bf16_t* __restrict__ Bt, int K, int row0, int col0, const Epi& epi, int tid) {
;     ...
;     for (int kt = 0; kt < nk; kt += 2) {
;       LWRITE(1, 1);
;       __builtin_amdgcn_sched_barrier(0);
;       GLOAD(1, (kt + 3 < last ? kt + 3 : last));
;       __builtin_amdgcn_sched_barrier(0);
;       COMPUTE(0);
;       __syncthreads();
;       LWRITE(0, 0);
;       __builtin_amdgcn_sched_barrier(0);
;       GLOAD(0, (kt + 4 < last ? kt + 4 : last));
;       __builtin_amdgcn_sched_barrier(0);
;       COMPUTE(1);
;       __syncthreads();
;     }
.Lg3d_hi1:
	v_mfma_f32_16x16x32_bf16 v[64:67], v[176:179], v[208:211], v[64:67]
	v_mfma_f32_16x16x32_bf16 v[68:71], v[180:183], v[208:211], v[68:71]
	v_mfma_f32_16x16x32_bf16 v[72:75], v[184:187], v[208:211], v[72:75]
	v_mfma_f32_16x16x32_bf16 v[76:79], v[188:191], v[208:211], v[76:79]
	ds_read_b128 v[160:163], v232 offset:4096
	v_mfma_f32_16x16x32_bf16 v[80:83], v[176:179], v[212:215], v[80:83]
	v_mfma_f32_16x16x32_bf16 v[84:87], v[180:183], v[212:215], v[84:87]
	v_mfma_f32_16x16x32_bf16 v[88:91], v[184:187], v[212:215], v[88:91]
	v_mfma_f32_16x16x32_bf16 v[92:95], v[188:191], v[212:215], v[92:95]
	ds_read_b128 v[164:167], v232 offset:5120
	v_mfma_f32_16x16x32_bf16 v[96:99], v[176:179], v[216:219], v[96:99]
	v_mfma_f32_16x16x32_bf16 v[100:103], v[180:183], v[216:219], v[100:103]
	v_mfma_f32_16x16x32_bf16 v[104:107], v[184:187], v[216:219], v[104:107]
	v_mfma_f32_16x16x32_bf16 v[108:111], v[188:191], v[216:219], v[108:111]
	ds_read_b128 v[168:171], v232 offset:6144
	s_add_u32 s31, s31, 24576
	s_cmp_eq_u32 s31, 73728
	s_cselect_b32 s31, 0, s31
	v_mfma_f32_16x16x32_bf16 v[112:115], v[176:179], v[220:223], v[112:115]
	v_mfma_f32_16x16x32_bf16 v[116:119], v[180:183], v[220:223], v[116:119]
	v_mfma_f32_16x16x32_bf16 v[120:123], v[184:187], v[220:223], v[120:123]
	v_mfma_f32_16x16x32_bf16 v[124:127], v[188:191], v[220:223], v[124:127]
	ds_read_b128 v[172:175], v232 offset:7168
	s_waitcnt vmcnt(0)
	s_waitcnt lgkmcnt(0)
	s_barrier
	v_add_u32_e32 v232, s31, v230
	v_add_u32_e32 v233, s31, v231
	s_setprio 1
	v_mfma_f32_16x16x32_bf16 v[0:3], v[128:131], v[144:147], v[0:3]
	v_mfma_f32_16x16x32_bf16 v[4:7], v[132:135], v[144:147], v[4:7]
	v_mfma_f32_16x16x32_bf16 v[8:11], v[136:139], v[144:147], v[8:11]
	v_mfma_f32_16x16x32_bf16 v[12:15], v[140:143], v[144:147], v[12:15]
	ds_read_b128 v[176:179], v233 offset:0
	ds_read_b128 v[180:183], v233 offset:1024
	v_mfma_f32_16x16x32_bf16 v[16:19], v[128:131], v[148:151], v[16:19]
	v_mfma_f32_16x16x32_bf16 v[20:23], v[132:135], v[148:151], v[20:23]
	v_mfma_f32_16x16x32_bf16 v[24:27], v[136:139], v[148:151], v[24:27]
	v_mfma_f32_16x16x32_bf16 v[28:31], v[140:143], v[148:151], v[28:31]
	ds_read_b128 v[184:187], v233 offset:2048
	ds_read_b128 v[188:191], v233 offset:3072
	v_mfma_f32_16x16x32_bf16 v[32:35], v[128:131], v[152:155], v[32:35]
	v_mfma_f32_16x16x32_bf16 v[36:39], v[132:135], v[152:155], v[36:39]
	v_mfma_f32_16x16x32_bf16 v[40:43], v[136:139], v[152:155], v[40:43]
	v_mfma_f32_16x16x32_bf16 v[44:47], v[140:143], v[152:155], v[44:47]
	ds_read_b128 v[192:195], v232 offset:0
	ds_read_b128 v[196:199], v232 offset:1024
	v_mfma_f32_16x16x32_bf16 v[48:51], v[128:131], v[156:159], v[48:51]
	v_mfma_f32_16x16x32_bf16 v[52:55], v[132:135], v[156:159], v[52:55]
	v_mfma_f32_16x16x32_bf16 v[56:59], v[136:139], v[156:159], v[56:59]
	v_mfma_f32_16x16x32_bf16 v[60:63], v[140:143], v[156:159], v[60:63]
	ds_read_b128 v[200:203], v232 offset:2048
	ds_read_b128 v[204:207], v232 offset:3072
	s_cmp_eq_u32 s25, 0
	s_cbranch_scc0 .Lg3d_hi2
	s_setprio 0

; #define LWRITE(S, buf) do { bf16_t* sA_ = sbase + (buf) * BUF; bf16_t* sB_ = sA_ + 256 * PITCH; \
;     _Pragma("unroll") for (int i_ = 0; i_ < 4; ++i_) *(u32x4*)(sA_ + (sr + i_ * 64) * PITCH + scv * 8) = ra[S][i_]; \
;     _Pragma("unroll") for (int i_ = 0; i_ < 2; ++i_) *(u32x4*)(sB_ + (sr + i_ * 64) * PITCH + scv * 8) = rb[S][i_]; } while (0)
; template <class Epi>
; DI void gemm_tile(char* smem, const bf16_t* __restrict__ A0, int lda0, int ksplit, const bf16_t* __restrict__ A1, int lda1,
;                   const bf16_t* __restrict__ Bt, int K, int row0, int col0, const Epi& epi, int tid) {
;     ...
;     for (int kt = 0; kt < nk; kt += 2) {
;       LWRITE(1, 1);
;       __builtin_amdgcn_sched_barrier(0);
;       GLOAD(1, (kt + 3 < last ? kt + 3 : last));
;       __builtin_amdgcn_sched_barrier(0);
;       COMPUTE(0);
;       __syncthreads();
;       LWRITE(0, 0);
;       __builtin_amdgcn_sched_barrier(0);
;       GLOAD(0, (kt + 4 < last ? kt + 4 : last));
;       __builtin_amdgcn_sched_barrier(0);
;       COMPUTE(1);
;       __syncthreads();
;     }
.Lg6_swb0:
	s_waitcnt vmcnt(6)
	s_waitcnt lgkmcnt(0)
	s_barrier
	v_add_u32_e32 v232, s100, v230
	v_add_u32_e32 v233, s100, v231
	s_add_u32 s19, s99, s13
	s_setprio 1
	v_mfma_f32_16x16x32_bf16 v[0:3], v[128:131], v[144:147], v[0:3]
	v_mfma_f32_16x16x32_bf16 v[4:7], v[132:135], v[144:147], v[4:7]
	v_mfma_f32_16x16x32_bf16 v[8:11], v[136:139], v[144:147], v[8:11]
	v_mfma_f32_16x16x32_bf16 v[12:15], v[140:143], v[144:147], v[12:15]
	ds_read_b128 v[176:179], v233 offset:0
	ds_read_b128 v[180:183], v233 offset:1024
	s_add_u32 m0, s19, 0
	s_nop 0
	global_load_lds_dwordx4 v224, s[0:1]
	v_mfma_f32_16x16x32_bf16 v[16:19], v[128:131], v[148:151], v[16:19]
	v_mfma_f32_16x16x32_bf16 v[20:23], v[132:135], v[148:151], v[20:23]
	v_mfma_f32_16x16x32_bf16 v[24:27], v[136:139], v[148:151], v[24:27]
	v_mfma_f32_16x16x32_bf16 v[28:31], v[140:143], v[148:151], v[28:31]
	ds_read_b128 v[184:187], v233 offset:2048
	ds_read_b128 v[188:191], v233 offset:3072
	s_add_u32 m0, s19, 4096
	s_nop 0
	global_load_lds_dwordx4 v225, s[0:1]
	v_mfma_f32_16x16x32_bf16 v[32:35], v[128:131], v[152:155], v[32:35]
	v_mfma_f32_16x16x32_bf16 v[36:39], v[132:135], v[152:155], v[36:39]
	v_mfma_f32_16x16x32_bf16 v[40:43], v[136:139], v[152:155], v[40:43]
	v_mfma_f32_16x16x32_bf16 v[44:47], v[140:143], v[152:155], v[44:47]
	ds_read_b128 v[192:195], v232 offset:0
	ds_read_b128 v[196:199], v232 offset:1024
	s_add_u32 m0, s19, 8192
	s_nop 0
	global_load_lds_dwordx4 v226, s[0:1]
	v_mfma_f32_16x16x32_bf16 v[48:51], v[128:131], v[156:159], v[48:51]
	v_mfma_f32_16x16x32_bf16 v[52:55], v[132:135], v[156:159], v[52:55]
	v_mfma_f32_16x16x32_bf16 v[56:59], v[136:139], v[156:159], v[56:59]
	v_mfma_f32_16x16x32_bf16 v[60:63], v[140:143], v[156:159], v[60:63]
	ds_read_b128 v[200:203], v232 offset:2048
	ds_read_b128 v[204:207], v232 offset:3072
	s_add_u32 m0, s19, 12288
	s_nop 0
	global_load_lds_dwordx4 v227, s[0:1]
	s_cmp_eq_u32 s18, 0
	s_cbranch_scc0 .Lg6_hi0
	s_setprio 0
.Lg6_hi0:
	v_mfma_f32_16x16x32_bf16 v[64:67], v[128:131], v[160:163], v[64:67]
	v_mfma_f32_16x16x32_bf16 v[68:71], v[132:135], v[160:163], v[68:71]
	v_mfma_f32_16x16x32_bf16 v[72:75], v[136:139], v[160:163], v[72:75]
	v_mfma_f32_16x16x32_bf16 v[76:79], v[140:143], v[160:163], v[76:79]
	ds_read_b128 v[208:211], v232 offset:4096
	s_add_u32 m0, s19, 16384
	s_nop 0
	global_load_lds_dwordx4 v228, s[2:3]
	v_mfma_f32_16x16x32_bf16 v[80:83], v[128:131], v[164:167], v[80:83]
	v_mfma_f32_16x16x32_bf16 v[84:87], v[132:135], v[164:167], v[84:87]
	v_mfma_f32_16x16x32_bf16 v[88:91], v[136:139], v[164:167], v[88:91]
	v_mfma_f32_16x16x32_bf16 v[92:95], v[140:143], v[164:167], v[92:95]
	ds_read_b128 v[212:215], v232 offset:5120
	s_add_u32 m0, s19, 20480
	s_nop 0
	global_load_lds_dwordx4 v229, s[2:3]
	v_mfma_f32_16x16x32_bf16 v[96:99], v[128:131], v[168:171], v[96:99]
	v_mfma_f32_16x16x32_bf16 v[100:103], v[132:135], v[168:171], v[100:103]
	v_mfma_f32_16x16x32_bf16 v[104:107], v[136:139], v[168:171], v[104:107]
	v_mfma_f32_16x16x32_bf16 v[108:111], v[140:143], v[168:171], v[108:111]
	ds_read_b128 v[216:219], v232 offset:6144
	s_add_u32 s0, s0, 64
	s_addc_u32 s1, s1, 0
	s_add_u32 s2, s2, 64
	s_addc_u32 s3, s3, 0
	s_add_u32 s22, s22, 1
	s_add_u32 s99, s99, 24576
	s_cmp_eq_u32 s99, 73728
	s_cselect_b32 s99, 0, s99
	s_add_u32 s100, s100, 24576
	s_cmp_eq_u32 s100, 73728
	s_cselect_b32 s100, 0, s100
	v_mfma_f32_16x16x32_bf16 v[112:115], v[128:131], v[172:175], v[112:115]
	v_mfma_f32_16x16x32_bf16 v[116:119], v[132:135], v[172:175], v[116:119]
	v_mfma_f32_16x16x32_bf16 v[120:123], v[136:139], v[172:175], v[120:123]
	v_mfma_f32_16x16x32_bf16 v[124:127], v[140:143], v[172:175], v[124:127]
	ds_read_b128 v[220:223], v232 offset:7168
	s_cmp_eq_u32 s22, 16
	s_cbranch_scc1 .Lg6_sw1
; #define LWRITE(S, buf) do { bf16_t* sA_ = sbase + (buf) * BUF; bf16_t* sB_ = sA_ + 256 * PITCH; \
;     _Pragma("unroll") for (int i_ = 0; i_ < 4; ++i_) *(u32x4*)(sA_ + (sr + i_ * 64) * PITCH + scv * 8) = ra[S][i_]; \
;     _Pragma("unroll") for (int i_ = 0; i_ < 2; ++i_) *(u32x4*)(sB_ + (sr + i_ * 64) * PITCH + scv * 8) = rb[S][i_]; } while (0)
; template <class Epi>
; DI void gemm_tile(char* smem, const bf16_t* __restrict__ A0, int lda0, int ksplit, const bf16_t* __restrict__ A1, int lda1,
;                   const bf16_t* __restrict__ Bt, int K, int row0, int col0, const Epi& epi, int tid) {
;     ...
;     for (int kt = 0; kt < nk; kt += 2) {
;       LWRITE(1, 1);
;       __builtin_amdgcn_sched_barrier(0);
;       GLOAD(1, (kt + 3 < last ? kt + 3 : last));
;       __builtin_amdgcn_sched_barrier(0);
;       COMPUTE(0);
;       __syncthreads();
;       LWRITE(0, 0);
;       __builtin_amdgcn_sched_barrier(0);
;       GLOAD(0, (kt + 4 < last ? kt + 4 : last));
;       __builtin_amdgcn_sched_barrier(0);
;       COMPUTE(1);
;       __syncthreads();
;     }
.Lg6_swb1:
	s_waitcnt vmcnt(6)
	s_waitcnt lgkmcnt(0)
	s_barrier
	v_add_u32_e32 v232, s100, v230
	v_add_u32_e32 v233, s100, v231
	s_add_u32 s19, s99, s13
	s_setprio 1
	v_mfma_f32_16x16x32_bf16 v[0:3], v[176:179], v[192:195], v[0:3]
	v_mfma_f32_16x16x32_bf16 v[4:7], v[180:183], v[192:195], v[4:7]
	v_mfma_f32_16x16x32_bf16 v[8:11], v[184:187], v[192:195], v[8:11]
	v_mfma_f32_16x16x32_bf16 v[12:15], v[188:191], v[192:195], v[12:15]
	ds_read_b128 v[128:131], v233 offset:0
	ds_read_b128 v[132:135], v233 offset:1024
	s_add_u32 m0, s19, 0
	s_nop 0
	global_load_lds_dwordx4 v224, s[0:1]
	v_mfma_f32_16x16x32_bf16 v[16:19], v[176:179], v[196:199], v[16:19]
	v_mfma_f32_16x16x32_bf16 v[20:23], v[180:183], v[196:199], v[20:23]
	v_mfma_f32_16x16x32_bf16 v[24:27], v[184:187], v[196:199], v[24:27]
	v_mfma_f32_16x16x32_bf16 v[28:31], v[188:191], v[196:199], v[28:31]
	ds_read_b128 v[136:139], v233 offset:2048
	ds_read_b128 v[140:143], v233 offset:3072
	s_add_u32 m0, s19, 4096
	s_nop 0
	global_load_lds_dwordx4 v225, s[0:1]
	v_mfma_f32_16x16x32_bf16 v[32:35], v[176:179], v[200:203], v[32:35]
	v_mfma_f32_16x16x32_bf16 v[36:39], v[180:183], v[200:203], v[36:39]
	v_mfma_f32_16x16x32_bf16 v[40:43], v[184:187], v[200:203], v[40:43]
	v_mfma_f32_16x16x32_bf16 v[44:47], v[188:191], v[200:203], v[44:47]
	ds_read_b128 v[144:147], v232 offset:0
	ds_read_b128 v[148:151], v232 offset:1024
	s_add_u32 m0, s19, 8192
	s_nop 0
	global_load_lds_dwordx4 v226, s[0:1]
	v_mfma_f32_16x16x32_bf16 v[48:51], v[176:179], v[204:207], v[48:51]
	v_mfma_f32_16x16x32_bf16 v[52:55], v[180:183], v[204:207], v[52:55]
	v_mfma_f32_16x16x32_bf16 v[56:59], v[184:187], v[204:207], v[56:59]
	v_mfma_f32_16x16x32_bf16 v[60:63], v[188:191], v[204:207], v[60:63]
	ds_read_b128 v[152:155], v232 offset:2048
	ds_read_b128 v[156:159], v232 offset:3072
	s_add_u32 m0, s19, 12288
	s_nop 0
	global_load_lds_dwordx4 v227, s[0:1]
	s_cmp_eq_u32 s18, 0
	s_cbranch_scc0 .Lg6_hi1
	s_setprio 0
.Lg6_hi1:
	v_mfma_f32_16x16x32_bf16 v[64:67], v[176:179], v[208:211], v[64:67]
	v_mfma_f32_16x16x32_bf16 v[68:71], v[180:183], v[208:211], v[68:71]
	v_mfma_f32_16x16x32_bf16 v[72:75], v[184:187], v[208:211], v[72:75]
	v_mfma_f32_16x16x32_bf16 v[76:79], v[188:191], v[208:211], v[76:79]
	ds_read_b128 v[160:163], v232 offset:4096
	s_add_u32 m0, s19, 16384
	s_nop 0
	global_load_lds_dwordx4 v228, s[2:3]
	v_mfma_f32_16x16x32_bf16 v[80:83], v[176:179], v[212:215], v[80:83]
	v_mfma_f32_16x16x32_bf16 v[84:87], v[180:183], v[212:215], v[84:87]
	v_mfma_f32_16x16x32_bf16 v[88:91], v[184:187], v[212:215], v[88:91]
	v_mfma_f32_16x16x32_bf16 v[92:95], v[188:191], v[212:215], v[92:95]
	ds_read_b128 v[164:167], v232 offset:5120
	s_add_u32 m0, s19, 20480
	s_nop 0
	global_load_lds_dwordx4 v229, s[2:3]
	v_mfma_f32_16x16x32_bf16 v[96:99], v[176:179], v[216:219], v[96:99]
	v_mfma_f32_16x16x32_bf16 v[100:103], v[180:183], v[216:219], v[100:103]
	v_mfma_f32_16x16x32_bf16 v[104:107], v[184:187], v[216:219], v[104:107]
	v_mfma_f32_16x16x32_bf16 v[108:111], v[188:191], v[216:219], v[108:111]
	ds_read_b128 v[168:171], v232 offset:6144
	s_add_u32 s0, s0, 64
	s_addc_u32 s1, s1, 0
	s_add_u32 s2, s2, 64
	s_addc_u32 s3, s3, 0
	s_add_u32 s22, s22, 1
	s_add_u32 s99, s99, 24576
	s_cmp_eq_u32 s99, 73728
	s_cselect_b32 s99, 0, s99
	s_add_u32 s100, s100, 24576
	s_cmp_eq_u32 s100, 73728
	s_cselect_b32 s100, 0, s100
	v_mfma_f32_16x16x32_bf16 v[112:115], v[176:179], v[220:223], v[112:115]
	v_mfma_f32_16x16x32_bf16 v[116:119], v[180:183], v[220:223], v[116:119]
	v_mfma_f32_16x16x32_bf16 v[120:123], v[184:187], v[220:223], v[120:123]
	v_mfma_f32_16x16x32_bf16 v[124:127], v[188:191], v[220:223], v[124:127]
	ds_read_b128 v[172:175], v232 offset:7168
	s_add_u32 s101, s101, 2
	s_cmp_lt_u32 s101, 44
	s_cbranch_scc1 .Lg6_kloop
	s_cmp_eq_u32 s22, 16
	s_cbranch_scc1 .Lg6_sw2

; #define LWRITE(S, buf) do { bf16_t* sA_ = sbase + (buf) * BUF; bf16_t* sB_ = sA_ + 256 * PITCH; \
;     _Pragma("unroll") for (int i_ = 0; i_ < 4; ++i_) *(u32x4*)(sA_ + (sr + i_ * 64) * PITCH + scv * 8) = ra[S][i_]; \
;     _Pragma("unroll") for (int i_ = 0; i_ < 2; ++i_) *(u32x4*)(sB_ + (sr + i_ * 64) * PITCH + scv * 8) = rb[S][i_]; } while (0)
; template <class Epi>
; DI void gemm_tile(char* smem, const bf16_t* __restrict__ A0, int lda0, int ksplit, const bf16_t* __restrict__ A1, int lda1,
;                   const bf16_t* __restrict__ Bt, int K, int row0, int col0, const Epi& epi, int tid) {
;     ...
;     for (int kt = 0; kt < nk; kt += 2) {
;       LWRITE(1, 1);
;       __builtin_amdgcn_sched_barrier(0);
;       GLOAD(1, (kt + 3 < last ? kt + 3 : last));
;       __builtin_amdgcn_sched_barrier(0);
;       COMPUTE(0);
;       __syncthreads();
;       LWRITE(0, 0);
;       __builtin_amdgcn_sched_barrier(0);
;       GLOAD(0, (kt + 4 < last ? kt + 4 : last));
;       __builtin_amdgcn_sched_barrier(0);
;       COMPUTE(1);
;       __syncthreads();
;     }
.Lg6_hi2:
	v_mfma_f32_16x16x32_bf16 v[64:67], v[128:131], v[160:163], v[64:67]
	v_mfma_f32_16x16x32_bf16 v[68:71], v[132:135], v[160:163], v[68:71]
	v_mfma_f32_16x16x32_bf16 v[72:75], v[136:139], v[160:163], v[72:75]
	v_mfma_f32_16x16x32_bf16 v[76:79], v[140:143], v[160:163], v[76:79]
	ds_read_b128 v[208:211], v232 offset:4096
	s_add_u32 m0, s19, 16384
	s_nop 0
	global_load_lds_dwordx4 v228, s[2:3]
	v_mfma_f32_16x16x32_bf16 v[80:83], v[128:131], v[164:167], v[80:83]
	v_mfma_f32_16x16x32_bf16 v[84:87], v[132:135], v[164:167], v[84:87]
	v_mfma_f32_16x16x32_bf16 v[88:91], v[136:139], v[164:167], v[88:91]
	v_mfma_f32_16x16x32_bf16 v[92:95], v[140:143], v[164:167], v[92:95]
	ds_read_b128 v[212:215], v232 offset:5120
	s_add_u32 m0, s19, 20480
	s_nop 0
	global_load_lds_dwordx4 v229, s[2:3]
	v_mfma_f32_16x16x32_bf16 v[96:99], v[128:131], v[168:171], v[96:99]
	v_mfma_f32_16x16x32_bf16 v[100:103], v[132:135], v[168:171], v[100:103]
	v_mfma_f32_16x16x32_bf16 v[104:107], v[136:139], v[168:171], v[104:107]
	v_mfma_f32_16x16x32_bf16 v[108:111], v[140:143], v[168:171], v[108:111]
	ds_read_b128 v[216:219], v232 offset:6144
	s_add_u32 s0, s0, 64
	s_addc_u32 s1, s1, 0
	s_add_u32 s2, s2, 64
	s_addc_u32 s3, s3, 0
	s_add_u32 s22, s22, 1
	s_add_u32 s99, s99, 24576
	s_cmp_eq_u32 s99, 73728
	s_cselect_b32 s99, 0, s99
	s_add_u32 s100, s100, 24576
	s_cmp_eq_u32 s100, 73728
	s_cselect_b32 s100, 0, s100
	v_mfma_f32_16x16x32_bf16 v[112:115], v[128:131], v[172:175], v[112:115]
	v_mfma_f32_16x16x32_bf16 v[116:119], v[132:135], v[172:175], v[116:119]
	v_mfma_f32_16x16x32_bf16 v[120:123], v[136:139], v[172:175], v[120:123]
	v_mfma_f32_16x16x32_bf16 v[124:127], v[140:143], v[172:175], v[124:127]
	ds_read_b128 v[220:223], v232 offset:7168
	s_waitcnt vmcnt(6)
	s_waitcnt lgkmcnt(0)
	s_barrier
	v_add_u32_e32 v232, s100, v230
	v_add_u32_e32 v233, s100, v231
	s_setprio 1
	v_mfma_f32_16x16x32_bf16 v[0:3], v[176:179], v[192:195], v[0:3]
	v_mfma_f32_16x16x32_bf16 v[4:7], v[180:183], v[192:195], v[4:7]
	v_mfma_f32_16x16x32_bf16 v[8:11], v[184:187], v[192:195], v[8:11]
	v_mfma_f32_16x16x32_bf16 v[12:15], v[188:191], v[192:195], v[12:15]
	ds_read_b128 v[128:131], v233 offset:0
	ds_read_b128 v[132:135], v233 offset:1024
	v_mfma_f32_16x16x32_bf16 v[16:19], v[176:179], v[196:199], v[16:19]
	v_mfma_f32_16x16x32_bf16 v[20:23], v[180:183], v[196:199], v[20:23]
	v_mfma_f32_16x16x32_bf16 v[24:27], v[184:187], v[196:199], v[24:27]
	v_mfma_f32_16x16x32_bf16 v[28:31], v[188:191], v[196:199], v[28:31]
	ds_read_b128 v[136:139], v233 offset:2048
	ds_read_b128 v[140:143], v233 offset:3072
	v_mfma_f32_16x16x32_bf16 v[32:35], v[176:179], v[200:203], v[32:35]
	v_mfma_f32_16x16x32_bf16 v[36:39], v[180:183], v[200:203], v[36:39]
	v_mfma_f32_16x16x32_bf16 v[40:43], v[184:187], v[200:203], v[40:43]
	v_mfma_f32_16x16x32_bf16 v[44:47], v[188:191], v[200:203], v[44:47]
	ds_read_b128 v[144:147], v232 offset:0
	ds_read_b128 v[148:151], v232 offset:1024
	v_mfma_f32_16x16x32_bf16 v[48:51], v[176:179], v[204:207], v[48:51]
	v_mfma_f32_16x16x32_bf16 v[52:55], v[180:183], v[204:207], v[52:55]
	v_mfma_f32_16x16x32_bf16 v[56:59], v[184:187], v[204:207], v[56:59]
	v_mfma_f32_16x16x32_bf16 v[60:63], v[188:191], v[204:207], v[60:63]
	ds_read_b128 v[152:155], v232 offset:2048
	ds_read_b128 v[156:159], v232 offset:3072
	s_cmp_eq_u32 s18, 0
	s_cbranch_scc0 .Lg6_hi3
	s_setprio 0
; #define LWRITE(S, buf) do { bf16_t* sA_ = sbase + (buf) * BUF; bf16_t* sB_ = sA_ + 256 * PITCH; \
;     _Pragma("unroll") for (int i_ = 0; i_ < 4; ++i_) *(u32x4*)(sA_ + (sr + i_ * 64) * PITCH + scv * 8) = ra[S][i_]; \
;     _Pragma("unroll") for (int i_ = 0; i_ < 2; ++i_) *(u32x4*)(sB_ + (sr + i_ * 64) * PITCH + scv * 8) = rb[S][i_]; } while (0)
; template <class Epi>
; DI void gemm_tile(char* smem, const bf16_t* __restrict__ A0, int lda0, int ksplit, const bf16_t* __restrict__ A1, int lda1,
;                   const bf16_t* __restrict__ Bt, int K, int row0, int col0, const Epi& epi, int tid) {
;     ...
;     for (int kt = 0; kt < nk; kt += 2) {
;       LWRITE(1, 1);
;       __builtin_amdgcn_sched_barrier(0);
;       GLOAD(1, (kt + 3 < last ? kt + 3 : last));
;       __builtin_amdgcn_sched_barrier(0);
;       COMPUTE(0);
;       __syncthreads();
;       LWRITE(0, 0);
;       __builtin_amdgcn_sched_barrier(0);
;       GLOAD(0, (kt + 4 < last ? kt + 4 : last));
;       __builtin_amdgcn_sched_barrier(0);
;       COMPUTE(1);
;       __syncthreads();
;     }
.Lg6_hi3:
	v_mfma_f32_16x16x32_bf16 v[64:67], v[176:179], v[208:211], v[64:67]
	v_mfma_f32_16x16x32_bf16 v[68:71], v[180:183], v[208:211], v[68:71]
	v_mfma_f32_16x16x32_bf16 v[72:75], v[184:187], v[208:211], v[72:75]
	v_mfma_f32_16x16x32_bf16 v[76:79], v[188:191], v[208:211], v[76:79]
	ds_read_b128 v[160:163], v232 offset:4096
	v_mfma_f32_16x16x32_bf16 v[80:83], v[176:179], v[212:215], v[80:83]
	v_mfma_f32_16x16x32_bf16 v[84:87], v[180:183], v[212:215], v[84:87]
	v_mfma_f32_16x16x32_bf16 v[88:91], v[184:187], v[212:215], v[88:91]
	v_mfma_f32_16x16x32_bf16 v[92:95], v[188:191], v[212:215], v[92:95]
	ds_read_b128 v[164:167], v232 offset:5120
	v_mfma_f32_16x16x32_bf16 v[96:99], v[176:179], v[216:219], v[96:99]
	v_mfma_f32_16x16x32_bf16 v[100:103], v[180:183], v[216:219], v[100:103]
	v_mfma_f32_16x16x32_bf16 v[104:107], v[184:187], v[216:219], v[104:107]
	v_mfma_f32_16x16x32_bf16 v[108:111], v[188:191], v[216:219], v[108:111]
	ds_read_b128 v[168:171], v232 offset:6144
	s_add_u32 s100, s100, 24576
	s_cmp_eq_u32 s100, 73728
	s_cselect_b32 s100, 0, s100
	v_mfma_f32_16x16x32_bf16 v[112:115], v[176:179], v[220:223], v[112:115]
	v_mfma_f32_16x16x32_bf16 v[116:119], v[180:183], v[220:223], v[116:119]
	v_mfma_f32_16x16x32_bf16 v[120:123], v[184:187], v[220:223], v[120:123]
	v_mfma_f32_16x16x32_bf16 v[124:127], v[188:191], v[220:223], v[124:127]
	ds_read_b128 v[172:175], v232 offset:7168
	s_waitcnt vmcnt(0)
	s_waitcnt lgkmcnt(0)
	s_barrier
	v_add_u32_e32 v232, s100, v230
	v_add_u32_e32 v233, s100, v231
	s_setprio 1
	v_mfma_f32_16x16x32_bf16 v[0:3], v[128:131], v[144:147], v[0:3]
	v_mfma_f32_16x16x32_bf16 v[4:7], v[132:135], v[144:147], v[4:7]
	v_mfma_f32_16x16x32_bf16 v[8:11], v[136:139], v[144:147], v[8:11]
	v_mfma_f32_16x16x32_bf16 v[12:15], v[140:143], v[144:147], v[12:15]
	ds_read_b128 v[176:179], v233 offset:0
	ds_read_b128 v[180:183], v233 offset:1024
	v_mfma_f32_16x16x32_bf16 v[16:19], v[128:131], v[148:151], v[16:19]
	v_mfma_f32_16x16x32_bf16 v[20:23], v[132:135], v[148:151], v[20:23]
	v_mfma_f32_16x16x32_bf16 v[24:27], v[136:139], v[148:151], v[24:27]
	v_mfma_f32_16x16x32_bf16 v[28:31], v[140:143], v[148:151], v[28:31]
	ds_read_b128 v[184:187], v233 offset:2048
	ds_read_b128 v[188:191], v233 offset:3072
	v_mfma_f32_16x16x32_bf16 v[32:35], v[128:131], v[152:155], v[32:35]
	v_mfma_f32_16x16x32_bf16 v[36:39], v[132:135], v[152:155], v[36:39]
	v_mfma_f32_16x16x32_bf16 v[40:43], v[136:139], v[152:155], v[40:43]
	v_mfma_f32_16x16x32_bf16 v[44:47], v[140:143], v[152:155], v[44:47]
	ds_read_b128 v[192:195], v232 offset:0
	ds_read_b128 v[196:199], v232 offset:1024
	v_mfma_f32_16x16x32_bf16 v[48:51], v[128:131], v[156:159], v[48:51]
	v_mfma_f32_16x16x32_bf16 v[52:55], v[132:135], v[156:159], v[52:55]
	v_mfma_f32_16x16x32_bf16 v[56:59], v[136:139], v[156:159], v[56:59]
	v_mfma_f32_16x16x32_bf16 v[60:63], v[140:143], v[156:159], v[60:63]
	ds_read_b128 v[200:203], v232 offset:2048
	ds_read_b128 v[204:207], v232 offset:3072
	s_cmp_eq_u32 s18, 0
	s_cbranch_scc0 .Lg6_hi4
	s_setprio 0
.Lg6_hi4:
	v_mfma_f32_16x16x32_bf16 v[64:67], v[128:131], v[160:163], v[64:67]
	v_mfma_f32_16x16x32_bf16 v[68:71], v[132:135], v[160:163], v[68:71]
	v_mfma_f32_16x16x32_bf16 v[72:75], v[136:139], v[160:163], v[72:75]
	v_mfma_f32_16x16x32_bf16 v[76:79], v[140:143], v[160:163], v[76:79]
	ds_read_b128 v[208:211], v232 offset:4096
	v_mfma_f32_16x16x32_bf16 v[80:83], v[128:131], v[164:167], v[80:83]
	v_mfma_f32_16x16x32_bf16 v[84:87], v[132:135], v[164:167], v[84:87]
	v_mfma_f32_16x16x32_bf16 v[88:91], v[136:139], v[164:167], v[88:91]
	v_mfma_f32_16x16x32_bf16 v[92:95], v[140:143], v[164:167], v[92:95]
	ds_read_b128 v[212:215], v232 offset:5120
	v_mfma_f32_16x16x32_bf16 v[96:99], v[128:131], v[168:171], v[96:99]
	v_mfma_f32_16x16x32_bf16 v[100:103], v[132:135], v[168:171], v[100:103]
	v_mfma_f32_16x16x32_bf16 v[104:107], v[136:139], v[168:171], v[104:107]
	v_mfma_f32_16x16x32_bf16 v[108:111], v[140:143], v[168:171], v[108:111]
	ds_read_b128 v[216:219], v232 offset:6144
	s_add_u32 s100, s100, 24576
	s_cmp_eq_u32 s100, 73728
	s_cselect_b32 s100, 0, s100
	v_mfma_f32_16x16x32_bf16 v[112:115], v[128:131], v[172:175], v[112:115]
	v_mfma_f32_16x16x32_bf16 v[116:119], v[132:135], v[172:175], v[116:119]
	v_mfma_f32_16x16x32_bf16 v[120:123], v[136:139], v[172:175], v[120:123]
	v_mfma_f32_16x16x32_bf16 v[124:127], v[140:143], v[172:175], v[124:127]
	ds_read_b128 v[220:223], v232 offset:7168
	s_waitcnt lgkmcnt(0)
	s_barrier
	s_setprio 1
	v_mfma_f32_16x16x32_bf16 v[0:3], v[176:179], v[192:195], v[0:3]
	v_mfma_f32_16x16x32_bf16 v[4:7], v[180:183], v[192:195], v[4:7]
	v_mfma_f32_16x16x32_bf16 v[8:11], v[184:187], v[192:195], v[8:11]
	v_mfma_f32_16x16x32_bf16 v[12:15], v[188:191], v[192:195], v[12:15]
	v_mfma_f32_16x16x32_bf16 v[16:19], v[176:179], v[196:199], v[16:19]
	v_mfma_f32_16x16x32_bf16 v[20:23], v[180:183], v[196:199], v[20:23]
	v_mfma_f32_16x16x32_bf16 v[24:27], v[184:187], v[196:199], v[24:27]
	v_mfma_f32_16x16x32_bf16 v[28:31], v[188:191], v[196:199], v[28:31]
	v_mfma_f32_16x16x32_bf16 v[32:35], v[176:179], v[200:203], v[32:35]
	v_mfma_f32_16x16x32_bf16 v[36:39], v[180:183], v[200:203], v[36:39]
	v_mfma_f32_16x16x32_bf16 v[40:43], v[184:187], v[200:203], v[40:43]
	v_mfma_f32_16x16x32_bf16 v[44:47], v[188:191], v[200:203], v[44:47]
	v_mfma_f32_16x16x32_bf16 v[48:51], v[176:179], v[204:207], v[48:51]
	v_mfma_f32_16x16x32_bf16 v[52:55], v[180:183], v[204:207], v[52:55]
	v_mfma_f32_16x16x32_bf16 v[56:59], v[184:187], v[204:207], v[56:59]
	v_mfma_f32_16x16x32_bf16 v[60:63], v[188:191], v[204:207], v[60:63]
	s_cmp_eq_u32 s18, 0
	s_cbranch_scc0 .Lg6_hi5
	s_setprio 0

; #define LWRITE(S, buf) do { bf16_t* sA_ = sbase + (buf) * BUF; bf16_t* sB_ = sA_ + 256 * PITCH; \
;     _Pragma("unroll") for (int i_ = 0; i_ < 4; ++i_) *(u32x4*)(sA_ + (sr + i_ * 64) * PITCH + scv * 8) = ra[S][i_]; \
;     _Pragma("unroll") for (int i_ = 0; i_ < 2; ++i_) *(u32x4*)(sB_ + (sr + i_ * 64) * PITCH + scv * 8) = rb[S][i_]; } while (0)
; template <class Epi>
; DI void gemm_tile(char* smem, const bf16_t* __restrict__ A0, int lda0, int ksplit, const bf16_t* __restrict__ A1, int lda1,
;                   const bf16_t* __restrict__ Bt, int K, int row0, int col0, const Epi& epi, int tid) {
;     ...
;     for (int kt = 0; kt < nk; kt += 2) {
;       LWRITE(1, 1);
;       __builtin_amdgcn_sched_barrier(0);
;       GLOAD(1, (kt + 3 < last ? kt + 3 : last));
;       __builtin_amdgcn_sched_barrier(0);
;       COMPUTE(0);
;       __syncthreads();
;       LWRITE(0, 0);
;       __builtin_amdgcn_sched_barrier(0);
;       GLOAD(0, (kt + 4 < last ? kt + 4 : last));
;       __builtin_amdgcn_sched_barrier(0);
;       COMPUTE(1);
;       __syncthreads();
;     }
.Lg8_kloop:
	s_waitcnt vmcnt(6)
	s_waitcnt lgkmcnt(0)
	s_barrier
	v_add_u32_e32 v232, s98, v230
	v_add_u32_e32 v233, s98, v231
	s_add_u32 s11, s19, s101
	s_setprio 1
	v_mfma_f32_16x16x32_bf16 v[0:3], v[128:131], v[144:147], v[0:3]
	v_mfma_f32_16x16x32_bf16 v[4:7], v[132:135], v[144:147], v[4:7]
	v_mfma_f32_16x16x32_bf16 v[8:11], v[136:139], v[144:147], v[8:11]
	v_mfma_f32_16x16x32_bf16 v[12:15], v[140:143], v[144:147], v[12:15]
	ds_read_b128 v[176:179], v233 offset:0
	ds_read_b128 v[180:183], v233 offset:1024
	s_add_u32 m0, s11, 0
	s_nop 0
	global_load_lds_dwordx4 v224, s[0:1]
	v_mfma_f32_16x16x32_bf16 v[16:19], v[128:131], v[148:151], v[16:19]
	v_mfma_f32_16x16x32_bf16 v[20:23], v[132:135], v[148:151], v[20:23]
	v_mfma_f32_16x16x32_bf16 v[24:27], v[136:139], v[148:151], v[24:27]
	v_mfma_f32_16x16x32_bf16 v[28:31], v[140:143], v[148:151], v[28:31]
	ds_read_b128 v[184:187], v233 offset:2048
	ds_read_b128 v[188:191], v233 offset:3072
	s_add_u32 m0, s11, 4096
	s_nop 0
	global_load_lds_dwordx4 v225, s[0:1]
	v_mfma_f32_16x16x32_bf16 v[32:35], v[128:131], v[152:155], v[32:35]
	v_mfma_f32_16x16x32_bf16 v[36:39], v[132:135], v[152:155], v[36:39]
	v_mfma_f32_16x16x32_bf16 v[40:43], v[136:139], v[152:155], v[40:43]
	v_mfma_f32_16x16x32_bf16 v[44:47], v[140:143], v[152:155], v[44:47]
	ds_read_b128 v[192:195], v232 offset:0
	ds_read_b128 v[196:199], v232 offset:1024
	s_add_u32 m0, s11, 8192
	s_nop 0
	global_load_lds_dwordx4 v226, s[0:1]
	v_mfma_f32_16x16x32_bf16 v[48:51], v[128:131], v[156:159], v[48:51]
	v_mfma_f32_16x16x32_bf16 v[52:55], v[132:135], v[156:159], v[52:55]
	v_mfma_f32_16x16x32_bf16 v[56:59], v[136:139], v[156:159], v[56:59]
	v_mfma_f32_16x16x32_bf16 v[60:63], v[140:143], v[156:159], v[60:63]
	ds_read_b128 v[200:203], v232 offset:2048
	ds_read_b128 v[204:207], v232 offset:3072
	s_add_u32 m0, s11, 12288
	s_nop 0
	global_load_lds_dwordx4 v227, s[0:1]
	s_cmp_eq_u32 s10, 0
	s_cbranch_scc0 .Lg8_hi0
	s_setprio 0
.Lg8_hi0:
	v_mfma_f32_16x16x32_bf16 v[64:67], v[128:131], v[160:163], v[64:67]
	v_mfma_f32_16x16x32_bf16 v[68:71], v[132:135], v[160:163], v[68:71]
	v_mfma_f32_16x16x32_bf16 v[72:75], v[136:139], v[160:163], v[72:75]
	v_mfma_f32_16x16x32_bf16 v[76:79], v[140:143], v[160:163], v[76:79]
	ds_read_b128 v[208:211], v232 offset:4096
	s_add_u32 m0, s11, 16384
	s_nop 0
	global_load_lds_dwordx4 v228, s[2:3]
	v_mfma_f32_16x16x32_bf16 v[80:83], v[128:131], v[164:167], v[80:83]
	v_mfma_f32_16x16x32_bf16 v[84:87], v[132:135], v[164:167], v[84:87]
	v_mfma_f32_16x16x32_bf16 v[88:91], v[136:139], v[164:167], v[88:91]
	v_mfma_f32_16x16x32_bf16 v[92:95], v[140:143], v[164:167], v[92:95]
	ds_read_b128 v[212:215], v232 offset:5120
	s_add_u32 m0, s11, 20480
	s_nop 0
	global_load_lds_dwordx4 v229, s[2:3]
	v_mfma_f32_16x16x32_bf16 v[96:99], v[128:131], v[168:171], v[96:99]
	v_mfma_f32_16x16x32_bf16 v[100:103], v[132:135], v[168:171], v[100:103]
	v_mfma_f32_16x16x32_bf16 v[104:107], v[136:139], v[168:171], v[104:107]
	v_mfma_f32_16x16x32_bf16 v[108:111], v[140:143], v[168:171], v[108:111]
	ds_read_b128 v[216:219], v232 offset:6144
	s_add_u32 s0, s0, 64
	s_addc_u32 s1, s1, 0
	s_add_u32 s2, s2, 64
	s_addc_u32 s3, s3, 0
	s_add_u32 s100, s100, 1
	s_add_u32 s19, s19, 24576
	s_cmp_eq_u32 s19, 73728
	s_cselect_b32 s19, 0, s19
	s_add_u32 s98, s98, 24576
	s_cmp_eq_u32 s98, 73728
	s_cselect_b32 s98, 0, s98
	v_mfma_f32_16x16x32_bf16 v[112:115], v[128:131], v[172:175], v[112:115]
	v_mfma_f32_16x16x32_bf16 v[116:119], v[132:135], v[172:175], v[116:119]
	v_mfma_f32_16x16x32_bf16 v[120:123], v[136:139], v[172:175], v[120:123]
	v_mfma_f32_16x16x32_bf16 v[124:127], v[140:143], v[172:175], v[124:127]
	ds_read_b128 v[220:223], v232 offset:7168
	s_waitcnt vmcnt(6)
	s_waitcnt lgkmcnt(0)
	s_barrier
	v_add_u32_e32 v232, s98, v230
	v_add_u32_e32 v233, s98, v231
	s_add_u32 s11, s19, s101
	s_setprio 1
	v_mfma_f32_16x16x32_bf16 v[0:3], v[176:179], v[192:195], v[0:3]
	v_mfma_f32_16x16x32_bf16 v[4:7], v[180:183], v[192:195], v[4:7]
	v_mfma_f32_16x16x32_bf16 v[8:11], v[184:187], v[192:195], v[8:11]
	v_mfma_f32_16x16x32_bf16 v[12:15], v[188:191], v[192:195], v[12:15]
	ds_read_b128 v[128:131], v233 offset:0
	ds_read_b128 v[132:135], v233 offset:1024
	s_add_u32 m0, s11, 0
	s_nop 0
	global_load_lds_dwordx4 v224, s[0:1]
	v_mfma_f32_16x16x32_bf16 v[16:19], v[176:179], v[196:199], v[16:19]
	v_mfma_f32_16x16x32_bf16 v[20:23], v[180:183], v[196:199], v[20:23]
	v_mfma_f32_16x16x32_bf16 v[24:27], v[184:187], v[196:199], v[24:27]
	v_mfma_f32_16x16x32_bf16 v[28:31], v[188:191], v[196:199], v[28:31]
	ds_read_b128 v[136:139], v233 offset:2048
	ds_read_b128 v[140:143], v233 offset:3072
	s_add_u32 m0, s11, 4096
	s_nop 0
	global_load_lds_dwordx4 v225, s[0:1]
	v_mfma_f32_16x16x32_bf16 v[32:35], v[176:179], v[200:203], v[32:35]
	v_mfma_f32_16x16x32_bf16 v[36:39], v[180:183], v[200:203], v[36:39]
	v_mfma_f32_16x16x32_bf16 v[40:43], v[184:187], v[200:203], v[40:43]
	v_mfma_f32_16x16x32_bf16 v[44:47], v[188:191], v[200:203], v[44:47]
	ds_read_b128 v[144:147], v232 offset:0
	ds_read_b128 v[148:151], v232 offset:1024
	s_add_u32 m0, s11, 8192
	s_nop 0
	global_load_lds_dwordx4 v226, s[0:1]
	v_mfma_f32_16x16x32_bf16 v[48:51], v[176:179], v[204:207], v[48:51]
	v_mfma_f32_16x16x32_bf16 v[52:55], v[180:183], v[204:207], v[52:55]
	v_mfma_f32_16x16x32_bf16 v[56:59], v[184:187], v[204:207], v[56:59]
	v_mfma_f32_16x16x32_bf16 v[60:63], v[188:191], v[204:207], v[60:63]
	ds_read_b128 v[152:155], v232 offset:2048
	ds_read_b128 v[156:159], v232 offset:3072
	s_add_u32 m0, s11, 12288
	s_nop 0
	global_load_lds_dwordx4 v227, s[0:1]
	s_cmp_eq_u32 s10, 0
	s_cbranch_scc0 .Lg8_hi1
	s_setprio 0
; #define LWRITE(S, buf) do { bf16_t* sA_ = sbase + (buf) * BUF; bf16_t* sB_ = sA_ + 256 * PITCH; \
;     _Pragma("unroll") for (int i_ = 0; i_ < 4; ++i_) *(u32x4*)(sA_ + (sr + i_ * 64) * PITCH + scv * 8) = ra[S][i_]; \
;     _Pragma("unroll") for (int i_ = 0; i_ < 2; ++i_) *(u32x4*)(sB_ + (sr + i_ * 64) * PITCH + scv * 8) = rb[S][i_]; } while (0)
; template <class Epi>
; DI void gemm_tile(char* smem, const bf16_t* __restrict__ A0, int lda0, int ksplit, const bf16_t* __restrict__ A1, int lda1,
;                   const bf16_t* __restrict__ Bt, int K, int row0, int col0, const Epi& epi, int tid) {
;     ...
;     for (int kt = 0; kt < nk; kt += 2) {
;       LWRITE(1, 1);
;       __builtin_amdgcn_sched_barrier(0);
;       GLOAD(1, (kt + 3 < last ? kt + 3 : last));
;       __builtin_amdgcn_sched_barrier(0);
;       COMPUTE(0);
;       __syncthreads();
;       LWRITE(0, 0);
;       __builtin_amdgcn_sched_barrier(0);
;       GLOAD(0, (kt + 4 < last ? kt + 4 : last));
;       __builtin_amdgcn_sched_barrier(0);
;       COMPUTE(1);
;       __syncthreads();
;     }
.Lg8_hi1:
	v_mfma_f32_16x16x32_bf16 v[64:67], v[176:179], v[208:211], v[64:67]
	v_mfma_f32_16x16x32_bf16 v[68:71], v[180:183], v[208:211], v[68:71]
	v_mfma_f32_16x16x32_bf16 v[72:75], v[184:187], v[208:211], v[72:75]
	v_mfma_f32_16x16x32_bf16 v[76:79], v[188:191], v[208:211], v[76:79]
	ds_read_b128 v[160:163], v232 offset:4096
	s_add_u32 m0, s11, 16384
	s_nop 0
	global_load_lds_dwordx4 v228, s[2:3]
	v_mfma_f32_16x16x32_bf16 v[80:83], v[176:179], v[212:215], v[80:83]
	v_mfma_f32_16x16x32_bf16 v[84:87], v[180:183], v[212:215], v[84:87]
	v_mfma_f32_16x16x32_bf16 v[88:91], v[184:187], v[212:215], v[88:91]
	v_mfma_f32_16x16x32_bf16 v[92:95], v[188:191], v[212:215], v[92:95]
	ds_read_b128 v[164:167], v232 offset:5120
	s_add_u32 m0, s11, 20480
	s_nop 0
	global_load_lds_dwordx4 v229, s[2:3]
	v_mfma_f32_16x16x32_bf16 v[96:99], v[176:179], v[216:219], v[96:99]
	v_mfma_f32_16x16x32_bf16 v[100:103], v[180:183], v[216:219], v[100:103]
	v_mfma_f32_16x16x32_bf16 v[104:107], v[184:187], v[216:219], v[104:107]
	v_mfma_f32_16x16x32_bf16 v[108:111], v[188:191], v[216:219], v[108:111]
	ds_read_b128 v[168:171], v232 offset:6144
	s_add_u32 s0, s0, 64
	s_addc_u32 s1, s1, 0
	s_add_u32 s2, s2, 64
	s_addc_u32 s3, s3, 0
	s_add_u32 s100, s100, 1
	s_add_u32 s19, s19, 24576
	s_cmp_eq_u32 s19, 73728
	s_cselect_b32 s19, 0, s19
	s_add_u32 s98, s98, 24576
	s_cmp_eq_u32 s98, 73728
	s_cselect_b32 s98, 0, s98
	v_mfma_f32_16x16x32_bf16 v[112:115], v[176:179], v[220:223], v[112:115]
	v_mfma_f32_16x16x32_bf16 v[116:119], v[180:183], v[220:223], v[116:119]
	v_mfma_f32_16x16x32_bf16 v[120:123], v[184:187], v[220:223], v[120:123]
	v_mfma_f32_16x16x32_bf16 v[124:127], v[188:191], v[220:223], v[124:127]
	ds_read_b128 v[172:175], v232 offset:7168
	s_add_u32 s99, s99, 2
	s_cmp_lt_u32 s99, 28
	s_cbranch_scc1 .Lg8_kloop
	s_waitcnt vmcnt(6)
	s_waitcnt lgkmcnt(0)
	s_barrier
	v_add_u32_e32 v232, s98, v230
	v_add_u32_e32 v233, s98, v231
	s_add_u32 s11, s19, s101
	s_setprio 1
	v_mfma_f32_16x16x32_bf16 v[0:3], v[128:131], v[144:147], v[0:3]
	v_mfma_f32_16x16x32_bf16 v[4:7], v[132:135], v[144:147], v[4:7]
	v_mfma_f32_16x16x32_bf16 v[8:11], v[136:139], v[144:147], v[8:11]
	v_mfma_f32_16x16x32_bf16 v[12:15], v[140:143], v[144:147], v[12:15]
	ds_read_b128 v[176:179], v233 offset:0
	ds_read_b128 v[180:183], v233 offset:1024
	s_add_u32 m0, s11, 0
	s_nop 0
	global_load_lds_dwordx4 v224, s[0:1]
	v_mfma_f32_16x16x32_bf16 v[16:19], v[128:131], v[148:151], v[16:19]
	v_mfma_f32_16x16x32_bf16 v[20:23], v[132:135], v[148:151], v[20:23]
	v_mfma_f32_16x16x32_bf16 v[24:27], v[136:139], v[148:151], v[24:27]
	v_mfma_f32_16x16x32_bf16 v[28:31], v[140:143], v[148:151], v[28:31]
	ds_read_b128 v[184:187], v233 offset:2048
	ds_read_b128 v[188:191], v233 offset:3072
	s_add_u32 m0, s11, 4096
	s_nop 0
	global_load_lds_dwordx4 v225, s[0:1]
	v_mfma_f32_16x16x32_bf16 v[32:35], v[128:131], v[152:155], v[32:35]
	v_mfma_f32_16x16x32_bf16 v[36:39], v[132:135], v[152:155], v[36:39]
	v_mfma_f32_16x16x32_bf16 v[40:43], v[136:139], v[152:155], v[40:43]
	v_mfma_f32_16x16x32_bf16 v[44:47], v[140:143], v[152:155], v[44:47]
	ds_read_b128 v[192:195], v232 offset:0
	ds_read_b128 v[196:199], v232 offset:1024
	s_add_u32 m0, s11, 8192
	s_nop 0
	global_load_lds_dwordx4 v226, s[0:1]
	v_mfma_f32_16x16x32_bf16 v[48:51], v[128:131], v[156:159], v[48:51]
	v_mfma_f32_16x16x32_bf16 v[52:55], v[132:135], v[156:159], v[52:55]
	v_mfma_f32_16x16x32_bf16 v[56:59], v[136:139], v[156:159], v[56:59]
	v_mfma_f32_16x16x32_bf16 v[60:63], v[140:143], v[156:159], v[60:63]
	ds_read_b128 v[200:203], v232 offset:2048
	ds_read_b128 v[204:207], v232 offset:3072
	s_add_u32 m0, s11, 12288
	s_nop 0
	global_load_lds_dwordx4 v227, s[0:1]
	s_cmp_eq_u32 s10, 0
	s_cbranch_scc0 .Lg8_hi2
	s_setprio 0
.Lg8_hi2:
	v_mfma_f32_16x16x32_bf16 v[64:67], v[128:131], v[160:163], v[64:67]
	v_mfma_f32_16x16x32_bf16 v[68:71], v[132:135], v[160:163], v[68:71]
	v_mfma_f32_16x16x32_bf16 v[72:75], v[136:139], v[160:163], v[72:75]
	v_mfma_f32_16x16x32_bf16 v[76:79], v[140:143], v[160:163], v[76:79]
	ds_read_b128 v[208:211], v232 offset:4096
	s_add_u32 m0, s11, 16384
	s_nop 0
	global_load_lds_dwordx4 v228, s[2:3]
	v_mfma_f32_16x16x32_bf16 v[80:83], v[128:131], v[164:167], v[80:83]
	v_mfma_f32_16x16x32_bf16 v[84:87], v[132:135], v[164:167], v[84:87]
	v_mfma_f32_16x16x32_bf16 v[88:91], v[136:139], v[164:167], v[88:91]
	v_mfma_f32_16x16x32_bf16 v[92:95], v[140:143], v[164:167], v[92:95]
	ds_read_b128 v[212:215], v232 offset:5120
	s_add_u32 m0, s11, 20480
	s_nop 0
	global_load_lds_dwordx4 v229, s[2:3]
	v_mfma_f32_16x16x32_bf16 v[96:99], v[128:131], v[168:171], v[96:99]
	v_mfma_f32_16x16x32_bf16 v[100:103], v[132:135], v[168:171], v[100:103]
	v_mfma_f32_16x16x32_bf16 v[104:107], v[136:139], v[168:171], v[104:107]
	v_mfma_f32_16x16x32_bf16 v[108:111], v[140:143], v[168:171], v[108:111]
	ds_read_b128 v[216:219], v232 offset:6144
	s_add_u32 s0, s0, 64
	s_addc_u32 s1, s1, 0
	s_add_u32 s2, s2, 64
	s_addc_u32 s3, s3, 0
	s_add_u32 s100, s100, 1
	s_add_u32 s19, s19, 24576
	s_cmp_eq_u32 s19, 73728
	s_cselect_b32 s19, 0, s19
	s_add_u32 s98, s98, 24576
	s_cmp_eq_u32 s98, 73728
	s_cselect_b32 s98, 0, s98
	v_mfma_f32_16x16x32_bf16 v[112:115], v[128:131], v[172:175], v[112:115]
	v_mfma_f32_16x16x32_bf16 v[116:119], v[132:135], v[172:175], v[116:119]
	v_mfma_f32_16x16x32_bf16 v[120:123], v[136:139], v[172:175], v[120:123]
	v_mfma_f32_16x16x32_bf16 v[124:127], v[140:143], v[172:175], v[124:127]
	ds_read_b128 v[220:223], v232 offset:7168
	s_waitcnt vmcnt(6)
	s_waitcnt lgkmcnt(0)
	s_barrier
; #define LWRITE(S, buf) do { bf16_t* sA_ = sbase + (buf) * BUF; bf16_t* sB_ = sA_ + 256 * PITCH; \
;     _Pragma("unroll") for (int i_ = 0; i_ < 4; ++i_) *(u32x4*)(sA_ + (sr + i_ * 64) * PITCH + scv * 8) = ra[S][i_]; \
;     _Pragma("unroll") for (int i_ = 0; i_ < 2; ++i_) *(u32x4*)(sB_ + (sr + i_ * 64) * PITCH + scv * 8) = rb[S][i_]; } while (0)
; template <class Epi>
; DI void gemm_tile(char* smem, const bf16_t* __restrict__ A0, int lda0, int ksplit, const bf16_t* __restrict__ A1, int lda1,
;                   const bf16_t* __restrict__ Bt, int K, int row0, int col0, const Epi& epi, int tid) {
;     ...
;     for (int kt = 0; kt < nk; kt += 2) {
;       LWRITE(1, 1);
;       __builtin_amdgcn_sched_barrier(0);
;       GLOAD(1, (kt + 3 < last ? kt + 3 : last));
;       __builtin_amdgcn_sched_barrier(0);
;       COMPUTE(0);
;       __syncthreads();
;       LWRITE(0, 0);
;       __builtin_amdgcn_sched_barrier(0);
;       GLOAD(0, (kt + 4 < last ? kt + 4 : last));
;       __builtin_amdgcn_sched_barrier(0);
;       COMPUTE(1);
;       __syncthreads();
;     }
	v_add_u32_e32 v232, s98, v230
	v_add_u32_e32 v233, s98, v231
	s_setprio 1
	v_mfma_f32_16x16x32_bf16 v[0:3], v[176:179], v[192:195], v[0:3]
	v_mfma_f32_16x16x32_bf16 v[4:7], v[180:183], v[192:195], v[4:7]
	v_mfma_f32_16x16x32_bf16 v[8:11], v[184:187], v[192:195], v[8:11]
	v_mfma_f32_16x16x32_bf16 v[12:15], v[188:191], v[192:195], v[12:15]
	ds_read_b128 v[128:131], v233 offset:0
	ds_read_b128 v[132:135], v233 offset:1024
	v_mfma_f32_16x16x32_bf16 v[16:19], v[176:179], v[196:199], v[16:19]
	v_mfma_f32_16x16x32_bf16 v[20:23], v[180:183], v[196:199], v[20:23]
	v_mfma_f32_16x16x32_bf16 v[24:27], v[184:187], v[196:199], v[24:27]
	v_mfma_f32_16x16x32_bf16 v[28:31], v[188:191], v[196:199], v[28:31]
	ds_read_b128 v[136:139], v233 offset:2048
	ds_read_b128 v[140:143], v233 offset:3072
	v_mfma_f32_16x16x32_bf16 v[32:35], v[176:179], v[200:203], v[32:35]
	v_mfma_f32_16x16x32_bf16 v[36:39], v[180:183], v[200:203], v[36:39]
	v_mfma_f32_16x16x32_bf16 v[40:43], v[184:187], v[200:203], v[40:43]
	v_mfma_f32_16x16x32_bf16 v[44:47], v[188:191], v[200:203], v[44:47]
	ds_read_b128 v[144:147], v232 offset:0
	ds_read_b128 v[148:151], v232 offset:1024
	v_mfma_f32_16x16x32_bf16 v[48:51], v[176:179], v[204:207], v[48:51]
	v_mfma_f32_16x16x32_bf16 v[52:55], v[180:183], v[204:207], v[52:55]
	v_mfma_f32_16x16x32_bf16 v[56:59], v[184:187], v[204:207], v[56:59]
	v_mfma_f32_16x16x32_bf16 v[60:63], v[188:191], v[204:207], v[60:63]
	ds_read_b128 v[152:155], v232 offset:2048
	ds_read_b128 v[156:159], v232 offset:3072
	s_cmp_eq_u32 s10, 0
	s_cbranch_scc0 .Lg8_hi3
	s_setprio 0
.Lg8_hi3:
	v_mfma_f32_16x16x32_bf16 v[64:67], v[176:179], v[208:211], v[64:67]
	v_mfma_f32_16x16x32_bf16 v[68:71], v[180:183], v[208:211], v[68:71]
	v_mfma_f32_16x16x32_bf16 v[72:75], v[184:187], v[208:211], v[72:75]
	v_mfma_f32_16x16x32_bf16 v[76:79], v[188:191], v[208:211], v[76:79]
	ds_read_b128 v[160:163], v232 offset:4096
	v_mfma_f32_16x16x32_bf16 v[80:83], v[176:179], v[212:215], v[80:83]
	v_mfma_f32_16x16x32_bf16 v[84:87], v[180:183], v[212:215], v[84:87]
	v_mfma_f32_16x16x32_bf16 v[88:91], v[184:187], v[212:215], v[88:91]
	v_mfma_f32_16x16x32_bf16 v[92:95], v[188:191], v[212:215], v[92:95]
	ds_read_b128 v[164:167], v232 offset:5120
	v_mfma_f32_16x16x32_bf16 v[96:99], v[176:179], v[216:219], v[96:99]
	v_mfma_f32_16x16x32_bf16 v[100:103], v[180:183], v[216:219], v[100:103]
	v_mfma_f32_16x16x32_bf16 v[104:107], v[184:187], v[216:219], v[104:107]
	v_mfma_f32_16x16x32_bf16 v[108:111], v[188:191], v[216:219], v[108:111]
	ds_read_b128 v[168:171], v232 offset:6144
	s_add_u32 s98, s98, 24576
	s_cmp_eq_u32 s98, 73728
	s_cselect_b32 s98, 0, s98
	v_mfma_f32_16x16x32_bf16 v[112:115], v[176:179], v[220:223], v[112:115]
	v_mfma_f32_16x16x32_bf16 v[116:119], v[180:183], v[220:223], v[116:119]
	v_mfma_f32_16x16x32_bf16 v[120:123], v[184:187], v[220:223], v[120:123]
	v_mfma_f32_16x16x32_bf16 v[124:127], v[188:191], v[220:223], v[124:127]
	ds_read_b128 v[172:175], v232 offset:7168
	s_waitcnt vmcnt(0)
	s_waitcnt lgkmcnt(0)
	s_barrier
	v_add_u32_e32 v232, s98, v230
	v_add_u32_e32 v233, s98, v231
	s_setprio 1
	v_mfma_f32_16x16x32_bf16 v[0:3], v[128:131], v[144:147], v[0:3]
	v_mfma_f32_16x16x32_bf16 v[4:7], v[132:135], v[144:147], v[4:7]
	v_mfma_f32_16x16x32_bf16 v[8:11], v[136:139], v[144:147], v[8:11]
	v_mfma_f32_16x16x32_bf16 v[12:15], v[140:143], v[144:147], v[12:15]
	ds_read_b128 v[176:179], v233 offset:0
	ds_read_b128 v[180:183], v233 offset:1024
	v_mfma_f32_16x16x32_bf16 v[16:19], v[128:131], v[148:151], v[16:19]
	v_mfma_f32_16x16x32_bf16 v[20:23], v[132:135], v[148:151], v[20:23]
	v_mfma_f32_16x16x32_bf16 v[24:27], v[136:139], v[148:151], v[24:27]
	v_mfma_f32_16x16x32_bf16 v[28:31], v[140:143], v[148:151], v[28:31]
	ds_read_b128 v[184:187], v233 offset:2048
	ds_read_b128 v[188:191], v233 offset:3072
	v_mfma_f32_16x16x32_bf16 v[32:35], v[128:131], v[152:155], v[32:35]
	v_mfma_f32_16x16x32_bf16 v[36:39], v[132:135], v[152:155], v[36:39]
	v_mfma_f32_16x16x32_bf16 v[40:43], v[136:139], v[152:155], v[40:43]
	v_mfma_f32_16x16x32_bf16 v[44:47], v[140:143], v[152:155], v[44:47]
	ds_read_b128 v[192:195], v232 offset:0
	ds_read_b128 v[196:199], v232 offset:1024
	v_mfma_f32_16x16x32_bf16 v[48:51], v[128:131], v[156:159], v[48:51]
	v_mfma_f32_16x16x32_bf16 v[52:55], v[132:135], v[156:159], v[52:55]
	v_mfma_f32_16x16x32_bf16 v[56:59], v[136:139], v[156:159], v[56:59]
	v_mfma_f32_16x16x32_bf16 v[60:63], v[140:143], v[156:159], v[60:63]
	ds_read_b128 v[200:203], v232 offset:2048
	ds_read_b128 v[204:207], v232 offset:3072
	s_cmp_eq_u32 s10, 0
	s_cbranch_scc0 .Lg8_hi4
	s_setprio 0
; #define LWRITE(S, buf) do { bf16_t* sA_ = sbase + (buf) * BUF; bf16_t* sB_ = sA_ + 256 * PITCH; \
;     _Pragma("unroll") for (int i_ = 0; i_ < 4; ++i_) *(u32x4*)(sA_ + (sr + i_ * 64) * PITCH + scv * 8) = ra[S][i_]; \
;     _Pragma("unroll") for (int i_ = 0; i_ < 2; ++i_) *(u32x4*)(sB_ + (sr + i_ * 64) * PITCH + scv * 8) = rb[S][i_]; } while (0)
; template <class Epi>
; DI void gemm_tile(char* smem, const bf16_t* __restrict__ A0, int lda0, int ksplit, const bf16_t* __restrict__ A1, int lda1,
;                   const bf16_t* __restrict__ Bt, int K, int row0, int col0, const Epi& epi, int tid) {
;     ...
;     for (int kt = 0; kt < nk; kt += 2) {
;       LWRITE(1, 1);
;       __builtin_amdgcn_sched_barrier(0);
;       GLOAD(1, (kt + 3 < last ? kt + 3 : last));
;       __builtin_amdgcn_sched_barrier(0);
;       COMPUTE(0);
;       __syncthreads();
;       LWRITE(0, 0);
;       __builtin_amdgcn_sched_barrier(0);
;       GLOAD(0, (kt + 4 < last ? kt + 4 : last));
;       __builtin_amdgcn_sched_barrier(0);
;       COMPUTE(1);
;       __syncthreads();
;     }
.Lg8_hi4:
	v_mfma_f32_16x16x32_bf16 v[64:67], v[128:131], v[160:163], v[64:67]
	v_mfma_f32_16x16x32_bf16 v[68:71], v[132:135], v[160:163], v[68:71]
	v_mfma_f32_16x16x32_bf16 v[72:75], v[136:139], v[160:163], v[72:75]
	v_mfma_f32_16x16x32_bf16 v[76:79], v[140:143], v[160:163], v[76:79]
	ds_read_b128 v[208:211], v232 offset:4096
	v_mfma_f32_16x16x32_bf16 v[80:83], v[128:131], v[164:167], v[80:83]
	v_mfma_f32_16x16x32_bf16 v[84:87], v[132:135], v[164:167], v[84:87]
	v_mfma_f32_16x16x32_bf16 v[88:91], v[136:139], v[164:167], v[88:91]
	v_mfma_f32_16x16x32_bf16 v[92:95], v[140:143], v[164:167], v[92:95]
	ds_read_b128 v[212:215], v232 offset:5120
	v_mfma_f32_16x16x32_bf16 v[96:99], v[128:131], v[168:171], v[96:99]
	v_mfma_f32_16x16x32_bf16 v[100:103], v[132:135], v[168:171], v[100:103]
	v_mfma_f32_16x16x32_bf16 v[104:107], v[136:139], v[168:171], v[104:107]
	v_mfma_f32_16x16x32_bf16 v[108:111], v[140:143], v[168:171], v[108:111]
	ds_read_b128 v[216:219], v232 offset:6144
	s_add_u32 s98, s98, 24576
	s_cmp_eq_u32 s98, 73728
	s_cselect_b32 s98, 0, s98
	v_mfma_f32_16x16x32_bf16 v[112:115], v[128:131], v[172:175], v[112:115]
	v_mfma_f32_16x16x32_bf16 v[116:119], v[132:135], v[172:175], v[116:119]
	v_mfma_f32_16x16x32_bf16 v[120:123], v[136:139], v[172:175], v[120:123]
	v_mfma_f32_16x16x32_bf16 v[124:127], v[140:143], v[172:175], v[124:127]
	ds_read_b128 v[220:223], v232 offset:7168
	s_waitcnt lgkmcnt(0)
	s_barrier
	s_setprio 1
	v_mfma_f32_16x16x32_bf16 v[0:3], v[176:179], v[192:195], v[0:3]
	v_mfma_f32_16x16x32_bf16 v[4:7], v[180:183], v[192:195], v[4:7]
	v_mfma_f32_16x16x32_bf16 v[8:11], v[184:187], v[192:195], v[8:11]
	v_mfma_f32_16x16x32_bf16 v[12:15], v[188:191], v[192:195], v[12:15]
	v_mfma_f32_16x16x32_bf16 v[16:19], v[176:179], v[196:199], v[16:19]
	v_mfma_f32_16x16x32_bf16 v[20:23], v[180:183], v[196:199], v[20:23]
	v_mfma_f32_16x16x32_bf16 v[24:27], v[184:187], v[196:199], v[24:27]
	v_mfma_f32_16x16x32_bf16 v[28:31], v[188:191], v[196:199], v[28:31]
	v_mfma_f32_16x16x32_bf16 v[32:35], v[176:179], v[200:203], v[32:35]
	v_mfma_f32_16x16x32_bf16 v[36:39], v[180:183], v[200:203], v[36:39]
	v_mfma_f32_16x16x32_bf16 v[40:43], v[184:187], v[200:203], v[40:43]
	v_mfma_f32_16x16x32_bf16 v[44:47], v[188:191], v[200:203], v[44:47]
	v_mfma_f32_16x16x32_bf16 v[48:51], v[176:179], v[204:207], v[48:51]
	v_mfma_f32_16x16x32_bf16 v[52:55], v[180:183], v[204:207], v[52:55]
	v_mfma_f32_16x16x32_bf16 v[56:59], v[184:187], v[204:207], v[56:59]
	v_mfma_f32_16x16x32_bf16 v[60:63], v[188:191], v[204:207], v[60:63]
	s_cmp_eq_u32 s10, 0
	s_cbranch_scc0 .Lg8_hi5
	s_setprio 0

; #define LWRITE(S, buf) do { bf16_t* sA_ = sbase + (buf) * BUF; bf16_t* sB_ = sA_ + 256 * PITCH; \
;     _Pragma("unroll") for (int i_ = 0; i_ < 4; ++i_) *(u32x4*)(sA_ + (sr + i_ * 64) * PITCH + scv * 8) = ra[S][i_]; \
;     _Pragma("unroll") for (int i_ = 0; i_ < 2; ++i_) *(u32x4*)(sB_ + (sr + i_ * 64) * PITCH + scv * 8) = rb[S][i_]; } while (0)
; template <class Epi>
; DI void gemm_tile(char* smem, const bf16_t* __restrict__ A0, int lda0, int ksplit, const bf16_t* __restrict__ A1, int lda1,
;                   const bf16_t* __restrict__ Bt, int K, int row0, int col0, const Epi& epi, int tid) {
;     ...
;     for (int kt = 0; kt < nk; kt += 2) {
;       LWRITE(1, 1);
;       __builtin_amdgcn_sched_barrier(0);
;       GLOAD(1, (kt + 3 < last ? kt + 3 : last));
;       __builtin_amdgcn_sched_barrier(0);
;       COMPUTE(0);
;       __syncthreads();
;       LWRITE(0, 0);
;       __builtin_amdgcn_sched_barrier(0);
;       GLOAD(0, (kt + 4 < last ? kt + 4 : last));
;       __builtin_amdgcn_sched_barrier(0);
;       COMPUTE(1);
;       __syncthreads();
;     }
.Lg9_kloop:
	s_waitcnt vmcnt(6)
	s_waitcnt lgkmcnt(0)
	s_barrier
	v_add_u32_e32 v232, s98, v230
	v_add_u32_e32 v233, s98, v231
	s_add_u32 s9, s17, s101
	s_setprio 1
	v_mfma_f32_16x16x32_bf16 v[0:3], v[128:131], v[144:147], v[0:3]
	v_mfma_f32_16x16x32_bf16 v[4:7], v[132:135], v[144:147], v[4:7]
	v_mfma_f32_16x16x32_bf16 v[8:11], v[136:139], v[144:147], v[8:11]
	v_mfma_f32_16x16x32_bf16 v[12:15], v[140:143], v[144:147], v[12:15]
	ds_read_b128 v[176:179], v233 offset:0
	ds_read_b128 v[180:183], v233 offset:1024
	s_add_u32 m0, s9, 0
	s_nop 0
	global_load_lds_dwordx4 v224, s[0:1]
	v_mfma_f32_16x16x32_bf16 v[16:19], v[128:131], v[148:151], v[16:19]
	v_mfma_f32_16x16x32_bf16 v[20:23], v[132:135], v[148:151], v[20:23]
	v_mfma_f32_16x16x32_bf16 v[24:27], v[136:139], v[148:151], v[24:27]
	v_mfma_f32_16x16x32_bf16 v[28:31], v[140:143], v[148:151], v[28:31]
	ds_read_b128 v[184:187], v233 offset:2048
	ds_read_b128 v[188:191], v233 offset:3072
	s_add_u32 m0, s9, 4096
	s_nop 0
	global_load_lds_dwordx4 v225, s[0:1]
	v_mfma_f32_16x16x32_bf16 v[32:35], v[128:131], v[152:155], v[32:35]
	v_mfma_f32_16x16x32_bf16 v[36:39], v[132:135], v[152:155], v[36:39]
	v_mfma_f32_16x16x32_bf16 v[40:43], v[136:139], v[152:155], v[40:43]
	v_mfma_f32_16x16x32_bf16 v[44:47], v[140:143], v[152:155], v[44:47]
	ds_read_b128 v[192:195], v232 offset:0
	ds_read_b128 v[196:199], v232 offset:1024
	s_add_u32 m0, s9, 8192
	s_nop 0
	global_load_lds_dwordx4 v226, s[0:1]
	v_mfma_f32_16x16x32_bf16 v[48:51], v[128:131], v[156:159], v[48:51]
	v_mfma_f32_16x16x32_bf16 v[52:55], v[132:135], v[156:159], v[52:55]
	v_mfma_f32_16x16x32_bf16 v[56:59], v[136:139], v[156:159], v[56:59]
	v_mfma_f32_16x16x32_bf16 v[60:63], v[140:143], v[156:159], v[60:63]
	ds_read_b128 v[200:203], v232 offset:2048
	ds_read_b128 v[204:207], v232 offset:3072
	s_add_u32 m0, s9, 12288
	s_nop 0
	global_load_lds_dwordx4 v227, s[0:1]
	s_cmp_eq_u32 s8, 0
	s_cbranch_scc0 .Lg9_hi0
	s_setprio 0
.Lg9_hi0:
	v_mfma_f32_16x16x32_bf16 v[64:67], v[128:131], v[160:163], v[64:67]
	v_mfma_f32_16x16x32_bf16 v[68:71], v[132:135], v[160:163], v[68:71]
	v_mfma_f32_16x16x32_bf16 v[72:75], v[136:139], v[160:163], v[72:75]
	v_mfma_f32_16x16x32_bf16 v[76:79], v[140:143], v[160:163], v[76:79]
	ds_read_b128 v[208:211], v232 offset:4096
	s_add_u32 m0, s9, 16384
	s_nop 0
	global_load_lds_dwordx4 v228, s[2:3]
	v_mfma_f32_16x16x32_bf16 v[80:83], v[128:131], v[164:167], v[80:83]
	v_mfma_f32_16x16x32_bf16 v[84:87], v[132:135], v[164:167], v[84:87]
	v_mfma_f32_16x16x32_bf16 v[88:91], v[136:139], v[164:167], v[88:91]
	v_mfma_f32_16x16x32_bf16 v[92:95], v[140:143], v[164:167], v[92:95]
	ds_read_b128 v[212:215], v232 offset:5120
	s_add_u32 m0, s9, 20480
	s_nop 0
	global_load_lds_dwordx4 v229, s[2:3]
	v_mfma_f32_16x16x32_bf16 v[96:99], v[128:131], v[168:171], v[96:99]
	v_mfma_f32_16x16x32_bf16 v[100:103], v[132:135], v[168:171], v[100:103]
	v_mfma_f32_16x16x32_bf16 v[104:107], v[136:139], v[168:171], v[104:107]
	v_mfma_f32_16x16x32_bf16 v[108:111], v[140:143], v[168:171], v[108:111]
	ds_read_b128 v[216:219], v232 offset:6144
	s_add_u32 s0, s0, 64
	s_addc_u32 s1, s1, 0
	s_add_u32 s2, s2, 64
	s_addc_u32 s3, s3, 0
	s_add_u32 s100, s100, 1
	s_add_u32 s17, s17, 24576
	s_cmp_eq_u32 s17, 73728
	s_cselect_b32 s17, 0, s17
	s_add_u32 s98, s98, 24576
	s_cmp_eq_u32 s98, 73728
	s_cselect_b32 s98, 0, s98
	v_mfma_f32_16x16x32_bf16 v[112:115], v[128:131], v[172:175], v[112:115]
	v_mfma_f32_16x16x32_bf16 v[116:119], v[132:135], v[172:175], v[116:119]
	v_mfma_f32_16x16x32_bf16 v[120:123], v[136:139], v[172:175], v[120:123]
	v_mfma_f32_16x16x32_bf16 v[124:127], v[140:143], v[172:175], v[124:127]
	ds_read_b128 v[220:223], v232 offset:7168
	s_waitcnt vmcnt(6)
	s_waitcnt lgkmcnt(0)
	s_barrier
	v_add_u32_e32 v232, s98, v230
	v_add_u32_e32 v233, s98, v231
	s_add_u32 s9, s17, s101
	s_setprio 1
	v_mfma_f32_16x16x32_bf16 v[0:3], v[176:179], v[192:195], v[0:3]
	v_mfma_f32_16x16x32_bf16 v[4:7], v[180:183], v[192:195], v[4:7]
	v_mfma_f32_16x16x32_bf16 v[8:11], v[184:187], v[192:195], v[8:11]
	v_mfma_f32_16x16x32_bf16 v[12:15], v[188:191], v[192:195], v[12:15]
	ds_read_b128 v[128:131], v233 offset:0
	ds_read_b128 v[132:135], v233 offset:1024
	s_add_u32 m0, s9, 0
	s_nop 0
	global_load_lds_dwordx4 v224, s[0:1]
	v_mfma_f32_16x16x32_bf16 v[16:19], v[176:179], v[196:199], v[16:19]
	v_mfma_f32_16x16x32_bf16 v[20:23], v[180:183], v[196:199], v[20:23]
	v_mfma_f32_16x16x32_bf16 v[24:27], v[184:187], v[196:199], v[24:27]
	v_mfma_f32_16x16x32_bf16 v[28:31], v[188:191], v[196:199], v[28:31]
	ds_read_b128 v[136:139], v233 offset:2048
	ds_read_b128 v[140:143], v233 offset:3072
	s_add_u32 m0, s9, 4096
	s_nop 0
	global_load_lds_dwordx4 v225, s[0:1]
	v_mfma_f32_16x16x32_bf16 v[32:35], v[176:179], v[200:203], v[32:35]
	v_mfma_f32_16x16x32_bf16 v[36:39], v[180:183], v[200:203], v[36:39]
	v_mfma_f32_16x16x32_bf16 v[40:43], v[184:187], v[200:203], v[40:43]
	v_mfma_f32_16x16x32_bf16 v[44:47], v[188:191], v[200:203], v[44:47]
	ds_read_b128 v[144:147], v232 offset:0
	ds_read_b128 v[148:151], v232 offset:1024
	s_add_u32 m0, s9, 8192
	s_nop 0
	global_load_lds_dwordx4 v226, s[0:1]
	v_mfma_f32_16x16x32_bf16 v[48:51], v[176:179], v[204:207], v[48:51]
	v_mfma_f32_16x16x32_bf16 v[52:55], v[180:183], v[204:207], v[52:55]
	v_mfma_f32_16x16x32_bf16 v[56:59], v[184:187], v[204:207], v[56:59]
	v_mfma_f32_16x16x32_bf16 v[60:63], v[188:191], v[204:207], v[60:63]
	ds_read_b128 v[152:155], v232 offset:2048
	ds_read_b128 v[156:159], v232 offset:3072
	s_add_u32 m0, s9, 12288
	s_nop 0
	global_load_lds_dwordx4 v227, s[0:1]
	s_cmp_eq_u32 s8, 0
	s_cbranch_scc0 .Lg9_hi1
	s_setprio 0
; #define LWRITE(S, buf) do { bf16_t* sA_ = sbase + (buf) * BUF; bf16_t* sB_ = sA_ + 256 * PITCH; \
;     _Pragma("unroll") for (int i_ = 0; i_ < 4; ++i_) *(u32x4*)(sA_ + (sr + i_ * 64) * PITCH + scv * 8) = ra[S][i_]; \
;     _Pragma("unroll") for (int i_ = 0; i_ < 2; ++i_) *(u32x4*)(sB_ + (sr + i_ * 64) * PITCH + scv * 8) = rb[S][i_]; } while (0)
; template <class Epi>
; DI void gemm_tile(char* smem, const bf16_t* __restrict__ A0, int lda0, int ksplit, const bf16_t* __restrict__ A1, int lda1,
;                   const bf16_t* __restrict__ Bt, int K, int row0, int col0, const Epi& epi, int tid) {
;     ...
;     for (int kt = 0; kt < nk; kt += 2) {
;       LWRITE(1, 1);
;       __builtin_amdgcn_sched_barrier(0);
;       GLOAD(1, (kt + 3 < last ? kt + 3 : last));
;       __builtin_amdgcn_sched_barrier(0);
;       COMPUTE(0);
;       __syncthreads();
;       LWRITE(0, 0);
;       __builtin_amdgcn_sched_barrier(0);
;       GLOAD(0, (kt + 4 < last ? kt + 4 : last));
;       __builtin_amdgcn_sched_barrier(0);
;       COMPUTE(1);
;       __syncthreads();
;     }
.Lg9_hi1:
	v_mfma_f32_16x16x32_bf16 v[64:67], v[176:179], v[208:211], v[64:67]
	v_mfma_f32_16x16x32_bf16 v[68:71], v[180:183], v[208:211], v[68:71]
	v_mfma_f32_16x16x32_bf16 v[72:75], v[184:187], v[208:211], v[72:75]
	v_mfma_f32_16x16x32_bf16 v[76:79], v[188:191], v[208:211], v[76:79]
	ds_read_b128 v[160:163], v232 offset:4096
	s_add_u32 m0, s9, 16384
	s_nop 0
	global_load_lds_dwordx4 v228, s[2:3]
	v_mfma_f32_16x16x32_bf16 v[80:83], v[176:179], v[212:215], v[80:83]
	v_mfma_f32_16x16x32_bf16 v[84:87], v[180:183], v[212:215], v[84:87]
	v_mfma_f32_16x16x32_bf16 v[88:91], v[184:187], v[212:215], v[88:91]
	v_mfma_f32_16x16x32_bf16 v[92:95], v[188:191], v[212:215], v[92:95]
	ds_read_b128 v[164:167], v232 offset:5120
	s_add_u32 m0, s9, 20480
	s_nop 0
	global_load_lds_dwordx4 v229, s[2:3]
	v_mfma_f32_16x16x32_bf16 v[96:99], v[176:179], v[216:219], v[96:99]
	v_mfma_f32_16x16x32_bf16 v[100:103], v[180:183], v[216:219], v[100:103]
	v_mfma_f32_16x16x32_bf16 v[104:107], v[184:187], v[216:219], v[104:107]
	v_mfma_f32_16x16x32_bf16 v[108:111], v[188:191], v[216:219], v[108:111]
	ds_read_b128 v[168:171], v232 offset:6144
	s_add_u32 s0, s0, 64
	s_addc_u32 s1, s1, 0
	s_add_u32 s2, s2, 64
	s_addc_u32 s3, s3, 0
	s_add_u32 s100, s100, 1
	s_add_u32 s17, s17, 24576
	s_cmp_eq_u32 s17, 73728
	s_cselect_b32 s17, 0, s17
	s_add_u32 s98, s98, 24576
	s_cmp_eq_u32 s98, 73728
	s_cselect_b32 s98, 0, s98
	v_mfma_f32_16x16x32_bf16 v[112:115], v[176:179], v[220:223], v[112:115]
	v_mfma_f32_16x16x32_bf16 v[116:119], v[180:183], v[220:223], v[116:119]
	v_mfma_f32_16x16x32_bf16 v[120:123], v[184:187], v[220:223], v[120:123]
	v_mfma_f32_16x16x32_bf16 v[124:127], v[188:191], v[220:223], v[124:127]
	ds_read_b128 v[172:175], v232 offset:7168
	s_add_u32 s99, s99, 2
	s_cmp_lt_u32 s99, 124
	s_cbranch_scc1 .Lg9_kloop
	s_waitcnt vmcnt(6)
	s_waitcnt lgkmcnt(0)
	s_barrier
	v_add_u32_e32 v232, s98, v230
	v_add_u32_e32 v233, s98, v231
	s_add_u32 s9, s17, s101
	s_setprio 1
	v_mfma_f32_16x16x32_bf16 v[0:3], v[128:131], v[144:147], v[0:3]
	v_mfma_f32_16x16x32_bf16 v[4:7], v[132:135], v[144:147], v[4:7]
	v_mfma_f32_16x16x32_bf16 v[8:11], v[136:139], v[144:147], v[8:11]
	v_mfma_f32_16x16x32_bf16 v[12:15], v[140:143], v[144:147], v[12:15]
	ds_read_b128 v[176:179], v233 offset:0
	ds_read_b128 v[180:183], v233 offset:1024
	s_add_u32 m0, s9, 0
	s_nop 0
	global_load_lds_dwordx4 v224, s[0:1]
	v_mfma_f32_16x16x32_bf16 v[16:19], v[128:131], v[148:151], v[16:19]
	v_mfma_f32_16x16x32_bf16 v[20:23], v[132:135], v[148:151], v[20:23]
	v_mfma_f32_16x16x32_bf16 v[24:27], v[136:139], v[148:151], v[24:27]
	v_mfma_f32_16x16x32_bf16 v[28:31], v[140:143], v[148:151], v[28:31]
	ds_read_b128 v[184:187], v233 offset:2048
	ds_read_b128 v[188:191], v233 offset:3072
	s_add_u32 m0, s9, 4096
	s_nop 0
	global_load_lds_dwordx4 v225, s[0:1]
	v_mfma_f32_16x16x32_bf16 v[32:35], v[128:131], v[152:155], v[32:35]
	v_mfma_f32_16x16x32_bf16 v[36:39], v[132:135], v[152:155], v[36:39]
	v_mfma_f32_16x16x32_bf16 v[40:43], v[136:139], v[152:155], v[40:43]
	v_mfma_f32_16x16x32_bf16 v[44:47], v[140:143], v[152:155], v[44:47]
	ds_read_b128 v[192:195], v232 offset:0
	ds_read_b128 v[196:199], v232 offset:1024
	s_add_u32 m0, s9, 8192
	s_nop 0
	global_load_lds_dwordx4 v226, s[0:1]
	v_mfma_f32_16x16x32_bf16 v[48:51], v[128:131], v[156:159], v[48:51]
	v_mfma_f32_16x16x32_bf16 v[52:55], v[132:135], v[156:159], v[52:55]
	v_mfma_f32_16x16x32_bf16 v[56:59], v[136:139], v[156:159], v[56:59]
	v_mfma_f32_16x16x32_bf16 v[60:63], v[140:143], v[156:159], v[60:63]
	ds_read_b128 v[200:203], v232 offset:2048
	ds_read_b128 v[204:207], v232 offset:3072
	s_add_u32 m0, s9, 12288
	s_nop 0
	global_load_lds_dwordx4 v227, s[0:1]
	s_cmp_eq_u32 s8, 0
	s_cbranch_scc0 .Lg9_hi2
	s_setprio 0
.Lg9_hi2:
	v_mfma_f32_16x16x32_bf16 v[64:67], v[128:131], v[160:163], v[64:67]
	v_mfma_f32_16x16x32_bf16 v[68:71], v[132:135], v[160:163], v[68:71]
	v_mfma_f32_16x16x32_bf16 v[72:75], v[136:139], v[160:163], v[72:75]
	v_mfma_f32_16x16x32_bf16 v[76:79], v[140:143], v[160:163], v[76:79]
	ds_read_b128 v[208:211], v232 offset:4096
	s_add_u32 m0, s9, 16384
	s_nop 0
	global_load_lds_dwordx4 v228, s[2:3]
	v_mfma_f32_16x16x32_bf16 v[80:83], v[128:131], v[164:167], v[80:83]
	v_mfma_f32_16x16x32_bf16 v[84:87], v[132:135], v[164:167], v[84:87]
	v_mfma_f32_16x16x32_bf16 v[88:91], v[136:139], v[164:167], v[88:91]
	v_mfma_f32_16x16x32_bf16 v[92:95], v[140:143], v[164:167], v[92:95]
	ds_read_b128 v[212:215], v232 offset:5120
	s_add_u32 m0, s9, 20480
	s_nop 0
	global_load_lds_dwordx4 v229, s[2:3]
	v_mfma_f32_16x16x32_bf16 v[96:99], v[128:131], v[168:171], v[96:99]
	v_mfma_f32_16x16x32_bf16 v[100:103], v[132:135], v[168:171], v[100:103]
	v_mfma_f32_16x16x32_bf16 v[104:107], v[136:139], v[168:171], v[104:107]
	v_mfma_f32_16x16x32_bf16 v[108:111], v[140:143], v[168:171], v[108:111]
	ds_read_b128 v[216:219], v232 offset:6144
	s_add_u32 s0, s0, 64
	s_addc_u32 s1, s1, 0
	s_add_u32 s2, s2, 64
	s_addc_u32 s3, s3, 0
	s_add_u32 s100, s100, 1
	s_add_u32 s17, s17, 24576
	s_cmp_eq_u32 s17, 73728
	s_cselect_b32 s17, 0, s17
	s_add_u32 s98, s98, 24576
	s_cmp_eq_u32 s98, 73728
	s_cselect_b32 s98, 0, s98
	v_mfma_f32_16x16x32_bf16 v[112:115], v[128:131], v[172:175], v[112:115]
	v_mfma_f32_16x16x32_bf16 v[116:119], v[132:135], v[172:175], v[116:119]
	v_mfma_f32_16x16x32_bf16 v[120:123], v[136:139], v[172:175], v[120:123]
	v_mfma_f32_16x16x32_bf16 v[124:127], v[140:143], v[172:175], v[124:127]
	ds_read_b128 v[220:223], v232 offset:7168
	s_waitcnt vmcnt(6)
	s_waitcnt lgkmcnt(0)
	s_barrier
; #define LWRITE(S, buf) do { bf16_t* sA_ = sbase + (buf) * BUF; bf16_t* sB_ = sA_ + 256 * PITCH; \
;     _Pragma("unroll") for (int i_ = 0; i_ < 4; ++i_) *(u32x4*)(sA_ + (sr + i_ * 64) * PITCH + scv * 8) = ra[S][i_]; \
;     _Pragma("unroll") for (int i_ = 0; i_ < 2; ++i_) *(u32x4*)(sB_ + (sr + i_ * 64) * PITCH + scv * 8) = rb[S][i_]; } while (0)
; template <class Epi>
; DI void gemm_tile(char* smem, const bf16_t* __restrict__ A0, int lda0, int ksplit, const bf16_t* __restrict__ A1, int lda1,
;                   const bf16_t* __restrict__ Bt, int K, int row0, int col0, const Epi& epi, int tid) {
;     ...
;   __syncthreads();
;   {
;     const int last = nk - 1;
;     GLOAD(0, 0);
;     __builtin_amdgcn_sched_barrier(0);
;     GLOAD(1, 1);
;     __builtin_amdgcn_sched_barrier(0);
;     LWRITE(0, 0);
;     __builtin_amdgcn_sched_barrier(0);
;     GLOAD(0, (2 < last ? 2 : last));
;     __builtin_amdgcn_sched_barrier(0);
;     __syncthreads();
;     for (int kt = 0; kt < nk; kt += 2) {
;       LWRITE(1, 1);
;       __builtin_amdgcn_sched_barrier(0);
;       GLOAD(1, (kt + 3 < last ? kt + 3 : last));
;       __builtin_amdgcn_sched_barrier(0);
;       COMPUTE(0);
;       __syncthreads();
;       LWRITE(0, 0);
;       __builtin_amdgcn_sched_barrier(0);
;       GLOAD(0, (kt + 4 < last ? kt + 4 : last));
;       __builtin_amdgcn_sched_barrier(0);
;       COMPUTE(1);
;       __syncthreads();
;     }
	v_add_u32_e32 v232, s98, v230
	v_add_u32_e32 v233, s98, v231
	s_setprio 1
	v_mfma_f32_16x16x32_bf16 v[0:3], v[176:179], v[192:195], v[0:3]
	v_mfma_f32_16x16x32_bf16 v[4:7], v[180:183], v[192:195], v[4:7]
	v_mfma_f32_16x16x32_bf16 v[8:11], v[184:187], v[192:195], v[8:11]
	v_mfma_f32_16x16x32_bf16 v[12:15], v[188:191], v[192:195], v[12:15]
	ds_read_b128 v[128:131], v233 offset:0
	ds_read_b128 v[132:135], v233 offset:1024
	v_mfma_f32_16x16x32_bf16 v[16:19], v[176:179], v[196:199], v[16:19]
	v_mfma_f32_16x16x32_bf16 v[20:23], v[180:183], v[196:199], v[20:23]
	v_mfma_f32_16x16x32_bf16 v[24:27], v[184:187], v[196:199], v[24:27]
	v_mfma_f32_16x16x32_bf16 v[28:31], v[188:191], v[196:199], v[28:31]
	ds_read_b128 v[136:139], v233 offset:2048
	ds_read_b128 v[140:143], v233 offset:3072
	v_mfma_f32_16x16x32_bf16 v[32:35], v[176:179], v[200:203], v[32:35]
	v_mfma_f32_16x16x32_bf16 v[36:39], v[180:183], v[200:203], v[36:39]
	v_mfma_f32_16x16x32_bf16 v[40:43], v[184:187], v[200:203], v[40:43]
	v_mfma_f32_16x16x32_bf16 v[44:47], v[188:191], v[200:203], v[44:47]
	ds_read_b128 v[144:147], v232 offset:0
	ds_read_b128 v[148:151], v232 offset:1024
	v_mfma_f32_16x16x32_bf16 v[48:51], v[176:179], v[204:207], v[48:51]
	v_mfma_f32_16x16x32_bf16 v[52:55], v[180:183], v[204:207], v[52:55]
	v_mfma_f32_16x16x32_bf16 v[56:59], v[184:187], v[204:207], v[56:59]
	v_mfma_f32_16x16x32_bf16 v[60:63], v[188:191], v[204:207], v[60:63]
	ds_read_b128 v[152:155], v232 offset:2048
	ds_read_b128 v[156:159], v232 offset:3072
	s_cmp_eq_u32 s8, 0
	s_cbranch_scc0 .Lg9_hi3
	s_setprio 0
.Lg9_hi3:
	v_mfma_f32_16x16x32_bf16 v[64:67], v[176:179], v[208:211], v[64:67]
	v_mfma_f32_16x16x32_bf16 v[68:71], v[180:183], v[208:211], v[68:71]
	v_mfma_f32_16x16x32_bf16 v[72:75], v[184:187], v[208:211], v[72:75]
	v_mfma_f32_16x16x32_bf16 v[76:79], v[188:191], v[208:211], v[76:79]
	ds_read_b128 v[160:163], v232 offset:4096
	v_mfma_f32_16x16x32_bf16 v[80:83], v[176:179], v[212:215], v[80:83]
	v_mfma_f32_16x16x32_bf16 v[84:87], v[180:183], v[212:215], v[84:87]
	v_mfma_f32_16x16x32_bf16 v[88:91], v[184:187], v[212:215], v[88:91]
	v_mfma_f32_16x16x32_bf16 v[92:95], v[188:191], v[212:215], v[92:95]
	ds_read_b128 v[164:167], v232 offset:5120
	v_mfma_f32_16x16x32_bf16 v[96:99], v[176:179], v[216:219], v[96:99]
	v_mfma_f32_16x16x32_bf16 v[100:103], v[180:183], v[216:219], v[100:103]
	v_mfma_f32_16x16x32_bf16 v[104:107], v[184:187], v[216:219], v[104:107]
	v_mfma_f32_16x16x32_bf16 v[108:111], v[188:191], v[216:219], v[108:111]
	ds_read_b128 v[168:171], v232 offset:6144
	s_add_u32 s98, s98, 24576
	s_cmp_eq_u32 s98, 73728
	s_cselect_b32 s98, 0, s98
	v_mfma_f32_16x16x32_bf16 v[112:115], v[176:179], v[220:223], v[112:115]
	v_mfma_f32_16x16x32_bf16 v[116:119], v[180:183], v[220:223], v[116:119]
	v_mfma_f32_16x16x32_bf16 v[120:123], v[184:187], v[220:223], v[120:123]
	v_mfma_f32_16x16x32_bf16 v[124:127], v[188:191], v[220:223], v[124:127]
	ds_read_b128 v[172:175], v232 offset:7168
	s_waitcnt vmcnt(0)
	s_waitcnt lgkmcnt(0)
	s_barrier
	v_add_u32_e32 v232, s98, v230
	v_add_u32_e32 v233, s98, v231
	s_setprio 1
	v_mfma_f32_16x16x32_bf16 v[0:3], v[128:131], v[144:147], v[0:3]
	v_mfma_f32_16x16x32_bf16 v[4:7], v[132:135], v[144:147], v[4:7]
	v_mfma_f32_16x16x32_bf16 v[8:11], v[136:139], v[144:147], v[8:11]
	v_mfma_f32_16x16x32_bf16 v[12:15], v[140:143], v[144:147], v[12:15]
	ds_read_b128 v[176:179], v233 offset:0
	ds_read_b128 v[180:183], v233 offset:1024
	v_mfma_f32_16x16x32_bf16 v[16:19], v[128:131], v[148:151], v[16:19]
	v_mfma_f32_16x16x32_bf16 v[20:23], v[132:135], v[148:151], v[20:23]
	v_mfma_f32_16x16x32_bf16 v[24:27], v[136:139], v[148:151], v[24:27]
	v_mfma_f32_16x16x32_bf16 v[28:31], v[140:143], v[148:151], v[28:31]
	ds_read_b128 v[184:187], v233 offset:2048
	ds_read_b128 v[188:191], v233 offset:3072
	v_mfma_f32_16x16x32_bf16 v[32:35], v[128:131], v[152:155], v[32:35]
	v_mfma_f32_16x16x32_bf16 v[36:39], v[132:135], v[152:155], v[36:39]
	v_mfma_f32_16x16x32_bf16 v[40:43], v[136:139], v[152:155], v[40:43]
	v_mfma_f32_16x16x32_bf16 v[44:47], v[140:143], v[152:155], v[44:47]
	ds_read_b128 v[192:195], v232 offset:0
	ds_read_b128 v[196:199], v232 offset:1024
	v_mfma_f32_16x16x32_bf16 v[48:51], v[128:131], v[156:159], v[48:51]
	v_mfma_f32_16x16x32_bf16 v[52:55], v[132:135], v[156:159], v[52:55]
	v_mfma_f32_16x16x32_bf16 v[56:59], v[136:139], v[156:159], v[56:59]
	v_mfma_f32_16x16x32_bf16 v[60:63], v[140:143], v[156:159], v[60:63]
	ds_read_b128 v[200:203], v232 offset:2048
	ds_read_b128 v[204:207], v232 offset:3072
	s_cmp_eq_u32 s8, 0
	s_cbranch_scc0 .Lg9_hi4
	s_setprio 0
; #define LWRITE(S, buf) do { bf16_t* sA_ = sbase + (buf) * BUF; bf16_t* sB_ = sA_ + 256 * PITCH; \
;     _Pragma("unroll") for (int i_ = 0; i_ < 4; ++i_) *(u32x4*)(sA_ + (sr + i_ * 64) * PITCH + scv * 8) = ra[S][i_]; \
;     _Pragma("unroll") for (int i_ = 0; i_ < 2; ++i_) *(u32x4*)(sB_ + (sr + i_ * 64) * PITCH + scv * 8) = rb[S][i_]; } while (0)
; template <class Epi>
; DI void gemm_tile(char* smem, const bf16_t* __restrict__ A0, int lda0, int ksplit, const bf16_t* __restrict__ A1, int lda1,
;                   const bf16_t* __restrict__ Bt, int K, int row0, int col0, const Epi& epi, int tid) {
;     ...
;   __syncthreads();
;   {
;     const int last = nk - 1;
;     GLOAD(0, 0);
;     __builtin_amdgcn_sched_barrier(0);
;     GLOAD(1, 1);
;     __builtin_amdgcn_sched_barrier(0);
;     LWRITE(0, 0);
;     __builtin_amdgcn_sched_barrier(0);
;     GLOAD(0, (2 < last ? 2 : last));
;     __builtin_amdgcn_sched_barrier(0);
;     __syncthreads();
;     for (int kt = 0; kt < nk; kt += 2) {
;       LWRITE(1, 1);
;       __builtin_amdgcn_sched_barrier(0);
;       GLOAD(1, (kt + 3 < last ? kt + 3 : last));
;       __builtin_amdgcn_sched_barrier(0);
;       COMPUTE(0);
;       __syncthreads();
;       LWRITE(0, 0);
;       __builtin_amdgcn_sched_barrier(0);
;       GLOAD(0, (kt + 4 < last ? kt + 4 : last));
;       __builtin_amdgcn_sched_barrier(0);
;       COMPUTE(1);
;       __syncthreads();
;     }
.Lg9_hi4:
	v_mfma_f32_16x16x32_bf16 v[64:67], v[128:131], v[160:163], v[64:67]
	v_mfma_f32_16x16x32_bf16 v[68:71], v[132:135], v[160:163], v[68:71]
	v_mfma_f32_16x16x32_bf16 v[72:75], v[136:139], v[160:163], v[72:75]
	v_mfma_f32_16x16x32_bf16 v[76:79], v[140:143], v[160:163], v[76:79]
	ds_read_b128 v[208:211], v232 offset:4096
	v_mfma_f32_16x16x32_bf16 v[80:83], v[128:131], v[164:167], v[80:83]
	v_mfma_f32_16x16x32_bf16 v[84:87], v[132:135], v[164:167], v[84:87]
	v_mfma_f32_16x16x32_bf16 v[88:91], v[136:139], v[164:167], v[88:91]
	v_mfma_f32_16x16x32_bf16 v[92:95], v[140:143], v[164:167], v[92:95]
	ds_read_b128 v[212:215], v232 offset:5120
	v_mfma_f32_16x16x32_bf16 v[96:99], v[128:131], v[168:171], v[96:99]
	v_mfma_f32_16x16x32_bf16 v[100:103], v[132:135], v[168:171], v[100:103]
	v_mfma_f32_16x16x32_bf16 v[104:107], v[136:139], v[168:171], v[104:107]
	v_mfma_f32_16x16x32_bf16 v[108:111], v[140:143], v[168:171], v[108:111]
	ds_read_b128 v[216:219], v232 offset:6144
	s_add_u32 s98, s98, 24576
	s_cmp_eq_u32 s98, 73728
	s_cselect_b32 s98, 0, s98
	v_mfma_f32_16x16x32_bf16 v[112:115], v[128:131], v[172:175], v[112:115]
	v_mfma_f32_16x16x32_bf16 v[116:119], v[132:135], v[172:175], v[116:119]
	v_mfma_f32_16x16x32_bf16 v[120:123], v[136:139], v[172:175], v[120:123]
	v_mfma_f32_16x16x32_bf16 v[124:127], v[140:143], v[172:175], v[124:127]
	ds_read_b128 v[220:223], v232 offset:7168
	s_waitcnt lgkmcnt(0)
	s_barrier
	s_setprio 1
	v_mfma_f32_16x16x32_bf16 v[0:3], v[176:179], v[192:195], v[0:3]
	v_mfma_f32_16x16x32_bf16 v[4:7], v[180:183], v[192:195], v[4:7]
	v_mfma_f32_16x16x32_bf16 v[8:11], v[184:187], v[192:195], v[8:11]
	v_mfma_f32_16x16x32_bf16 v[12:15], v[188:191], v[192:195], v[12:15]
	v_mfma_f32_16x16x32_bf16 v[16:19], v[176:179], v[196:199], v[16:19]
	v_mfma_f32_16x16x32_bf16 v[20:23], v[180:183], v[196:199], v[20:23]
	v_mfma_f32_16x16x32_bf16 v[24:27], v[184:187], v[196:199], v[24:27]
	v_mfma_f32_16x16x32_bf16 v[28:31], v[188:191], v[196:199], v[28:31]
	v_mfma_f32_16x16x32_bf16 v[32:35], v[176:179], v[200:203], v[32:35]
	v_mfma_f32_16x16x32_bf16 v[36:39], v[180:183], v[200:203], v[36:39]
	v_mfma_f32_16x16x32_bf16 v[40:43], v[184:187], v[200:203], v[40:43]
	v_mfma_f32_16x16x32_bf16 v[44:47], v[188:191], v[200:203], v[44:47]
	v_mfma_f32_16x16x32_bf16 v[48:51], v[176:179], v[204:207], v[48:51]
	v_mfma_f32_16x16x32_bf16 v[52:55], v[180:183], v[204:207], v[52:55]
	v_mfma_f32_16x16x32_bf16 v[56:59], v[184:187], v[204:207], v[56:59]
	v_mfma_f32_16x16x32_bf16 v[60:63], v[188:191], v[204:207], v[60:63]
	s_cmp_eq_u32 s8, 0
	s_cbranch_scc0 .Lg9_hi5
	s_setprio 0

; #define LWRITE(S, buf) do { bf16_t* sA_ = sbase + (buf) * BUF; bf16_t* sB_ = sA_ + 256 * PITCH; \
;     _Pragma("unroll") for (int i_ = 0; i_ < 4; ++i_) *(u32x4*)(sA_ + (sr + i_ * 64) * PITCH + scv * 8) = ra[S][i_]; \
;     _Pragma("unroll") for (int i_ = 0; i_ < 2; ++i_) *(u32x4*)(sB_ + (sr + i_ * 64) * PITCH + scv * 8) = rb[S][i_]; } while (0)
; template <class Epi>
; DI void gemm_tile(char* smem, const bf16_t* __restrict__ A0, int lda0, int ksplit, const bf16_t* __restrict__ A1, int lda1,
;                   const bf16_t* __restrict__ Bt, int K, int row0, int col0, const Epi& epi, int tid) {
;     ...
;   __syncthreads();
;   {
;     const int last = nk - 1;
;     GLOAD(0, 0);
;     __builtin_amdgcn_sched_barrier(0);
;     GLOAD(1, 1);
;     __builtin_amdgcn_sched_barrier(0);
;     LWRITE(0, 0);
;     __builtin_amdgcn_sched_barrier(0);
;     GLOAD(0, (2 < last ? 2 : last));
;     __builtin_amdgcn_sched_barrier(0);
;     __syncthreads();
;     for (int kt = 0; kt < nk; kt += 2) {
;       LWRITE(1, 1);
;       __builtin_amdgcn_sched_barrier(0);
;       GLOAD(1, (kt + 3 < last ? kt + 3 : last));
;       __builtin_amdgcn_sched_barrier(0);
;       COMPUTE(0);
;       __syncthreads();
;       LWRITE(0, 0);
;       __builtin_amdgcn_sched_barrier(0);
;       GLOAD(0, (kt + 4 < last ? kt + 4 : last));
;       __builtin_amdgcn_sched_barrier(0);
;       COMPUTE(1);
;       __syncthreads();
;     }
.Lg11_kloop:
	s_waitcnt vmcnt(6)
	s_waitcnt lgkmcnt(0)
	s_barrier
	v_add_u32_e32 v232, s30, v230
	v_add_u32_e32 v233, s30, v231
	s_add_u32 s25, s29, s99
	s_setprio 1
	v_mfma_f32_16x16x32_bf16 v[0:3], v[128:131], v[144:147], v[0:3]
	v_mfma_f32_16x16x32_bf16 v[4:7], v[132:135], v[144:147], v[4:7]
	v_mfma_f32_16x16x32_bf16 v[8:11], v[136:139], v[144:147], v[8:11]
	v_mfma_f32_16x16x32_bf16 v[12:15], v[140:143], v[144:147], v[12:15]
	ds_read_b128 v[176:179], v233 offset:0
	ds_read_b128 v[180:183], v233 offset:1024
	s_add_u32 m0, s25, 0
	s_nop 0
	global_load_lds_dwordx4 v224, s[0:1]
	v_mfma_f32_16x16x32_bf16 v[16:19], v[128:131], v[148:151], v[16:19]
	v_mfma_f32_16x16x32_bf16 v[20:23], v[132:135], v[148:151], v[20:23]
	v_mfma_f32_16x16x32_bf16 v[24:27], v[136:139], v[148:151], v[24:27]
	v_mfma_f32_16x16x32_bf16 v[28:31], v[140:143], v[148:151], v[28:31]
	ds_read_b128 v[184:187], v233 offset:2048
	ds_read_b128 v[188:191], v233 offset:3072
	s_add_u32 m0, s25, 4096
	s_nop 0
	global_load_lds_dwordx4 v225, s[0:1]
	v_mfma_f32_16x16x32_bf16 v[32:35], v[128:131], v[152:155], v[32:35]
	v_mfma_f32_16x16x32_bf16 v[36:39], v[132:135], v[152:155], v[36:39]
	v_mfma_f32_16x16x32_bf16 v[40:43], v[136:139], v[152:155], v[40:43]
	v_mfma_f32_16x16x32_bf16 v[44:47], v[140:143], v[152:155], v[44:47]
	ds_read_b128 v[192:195], v232 offset:0
	ds_read_b128 v[196:199], v232 offset:1024
	s_add_u32 m0, s25, 8192
	s_nop 0
	global_load_lds_dwordx4 v226, s[0:1]
	v_mfma_f32_16x16x32_bf16 v[48:51], v[128:131], v[156:159], v[48:51]
	v_mfma_f32_16x16x32_bf16 v[52:55], v[132:135], v[156:159], v[52:55]
	v_mfma_f32_16x16x32_bf16 v[56:59], v[136:139], v[156:159], v[56:59]
	v_mfma_f32_16x16x32_bf16 v[60:63], v[140:143], v[156:159], v[60:63]
	ds_read_b128 v[200:203], v232 offset:2048
	ds_read_b128 v[204:207], v232 offset:3072
	s_add_u32 m0, s25, 12288
	s_nop 0
	global_load_lds_dwordx4 v227, s[0:1]
	s_cmp_eq_u32 s24, 0
	s_cbranch_scc0 .Lg11_hi0
	s_setprio 0
.Lg11_hi0:
	v_mfma_f32_16x16x32_bf16 v[64:67], v[128:131], v[160:163], v[64:67]
	v_mfma_f32_16x16x32_bf16 v[68:71], v[132:135], v[160:163], v[68:71]
	v_mfma_f32_16x16x32_bf16 v[72:75], v[136:139], v[160:163], v[72:75]
	v_mfma_f32_16x16x32_bf16 v[76:79], v[140:143], v[160:163], v[76:79]
	ds_read_b128 v[208:211], v232 offset:4096
	s_add_u32 m0, s25, 16384
	s_nop 0
	global_load_lds_dwordx4 v228, s[2:3]
	v_mfma_f32_16x16x32_bf16 v[80:83], v[128:131], v[164:167], v[80:83]
	v_mfma_f32_16x16x32_bf16 v[84:87], v[132:135], v[164:167], v[84:87]
	v_mfma_f32_16x16x32_bf16 v[88:91], v[136:139], v[164:167], v[88:91]
	v_mfma_f32_16x16x32_bf16 v[92:95], v[140:143], v[164:167], v[92:95]
	ds_read_b128 v[212:215], v232 offset:5120
	s_add_u32 m0, s25, 20480
	s_nop 0
	global_load_lds_dwordx4 v229, s[2:3]
	v_mfma_f32_16x16x32_bf16 v[96:99], v[128:131], v[168:171], v[96:99]
	v_mfma_f32_16x16x32_bf16 v[100:103], v[132:135], v[168:171], v[100:103]
	v_mfma_f32_16x16x32_bf16 v[104:107], v[136:139], v[168:171], v[104:107]
	v_mfma_f32_16x16x32_bf16 v[108:111], v[140:143], v[168:171], v[108:111]
	ds_read_b128 v[216:219], v232 offset:6144
	s_add_u32 s0, s0, 64
	s_addc_u32 s1, s1, 0
	s_add_u32 s2, s2, 64
	s_addc_u32 s3, s3, 0
	s_add_u32 s98, s98, 1
	s_add_u32 s29, s29, 24576
	s_cmp_eq_u32 s29, 73728
	s_cselect_b32 s29, 0, s29
	s_add_u32 s30, s30, 24576
	s_cmp_eq_u32 s30, 73728
	s_cselect_b32 s30, 0, s30
	v_mfma_f32_16x16x32_bf16 v[112:115], v[128:131], v[172:175], v[112:115]
	v_mfma_f32_16x16x32_bf16 v[116:119], v[132:135], v[172:175], v[116:119]
	v_mfma_f32_16x16x32_bf16 v[120:123], v[136:139], v[172:175], v[120:123]
	v_mfma_f32_16x16x32_bf16 v[124:127], v[140:143], v[172:175], v[124:127]
	ds_read_b128 v[220:223], v232 offset:7168
	s_waitcnt vmcnt(6)
	s_waitcnt lgkmcnt(0)
	s_barrier
	v_add_u32_e32 v232, s30, v230
	v_add_u32_e32 v233, s30, v231
	s_add_u32 s25, s29, s99
	s_setprio 1
	v_mfma_f32_16x16x32_bf16 v[0:3], v[176:179], v[192:195], v[0:3]
	v_mfma_f32_16x16x32_bf16 v[4:7], v[180:183], v[192:195], v[4:7]
	v_mfma_f32_16x16x32_bf16 v[8:11], v[184:187], v[192:195], v[8:11]
	v_mfma_f32_16x16x32_bf16 v[12:15], v[188:191], v[192:195], v[12:15]
	ds_read_b128 v[128:131], v233 offset:0
	ds_read_b128 v[132:135], v233 offset:1024
	s_add_u32 m0, s25, 0
	s_nop 0
	global_load_lds_dwordx4 v224, s[0:1]
	v_mfma_f32_16x16x32_bf16 v[16:19], v[176:179], v[196:199], v[16:19]
	v_mfma_f32_16x16x32_bf16 v[20:23], v[180:183], v[196:199], v[20:23]
	v_mfma_f32_16x16x32_bf16 v[24:27], v[184:187], v[196:199], v[24:27]
	v_mfma_f32_16x16x32_bf16 v[28:31], v[188:191], v[196:199], v[28:31]
	ds_read_b128 v[136:139], v233 offset:2048
	ds_read_b128 v[140:143], v233 offset:3072
	s_add_u32 m0, s25, 4096
	s_nop 0
	global_load_lds_dwordx4 v225, s[0:1]
	v_mfma_f32_16x16x32_bf16 v[32:35], v[176:179], v[200:203], v[32:35]
	v_mfma_f32_16x16x32_bf16 v[36:39], v[180:183], v[200:203], v[36:39]
	v_mfma_f32_16x16x32_bf16 v[40:43], v[184:187], v[200:203], v[40:43]
	v_mfma_f32_16x16x32_bf16 v[44:47], v[188:191], v[200:203], v[44:47]
	ds_read_b128 v[144:147], v232 offset:0
	ds_read_b128 v[148:151], v232 offset:1024
	s_add_u32 m0, s25, 8192
	s_nop 0
	global_load_lds_dwordx4 v226, s[0:1]
	v_mfma_f32_16x16x32_bf16 v[48:51], v[176:179], v[204:207], v[48:51]
	v_mfma_f32_16x16x32_bf16 v[52:55], v[180:183], v[204:207], v[52:55]
	v_mfma_f32_16x16x32_bf16 v[56:59], v[184:187], v[204:207], v[56:59]
	v_mfma_f32_16x16x32_bf16 v[60:63], v[188:191], v[204:207], v[60:63]
	ds_read_b128 v[152:155], v232 offset:2048
	ds_read_b128 v[156:159], v232 offset:3072
	s_add_u32 m0, s25, 12288
	s_nop 0
	global_load_lds_dwordx4 v227, s[0:1]
	s_cmp_eq_u32 s24, 0
	s_cbranch_scc0 .Lg11_hi1
	s_setprio 0
; #define LWRITE(S, buf) do { bf16_t* sA_ = sbase + (buf) * BUF; bf16_t* sB_ = sA_ + 256 * PITCH; \
;     _Pragma("unroll") for (int i_ = 0; i_ < 4; ++i_) *(u32x4*)(sA_ + (sr + i_ * 64) * PITCH + scv * 8) = ra[S][i_]; \
;     _Pragma("unroll") for (int i_ = 0; i_ < 2; ++i_) *(u32x4*)(sB_ + (sr + i_ * 64) * PITCH + scv * 8) = rb[S][i_]; } while (0)
; template <class Epi>
; DI void gemm_tile(char* smem, const bf16_t* __restrict__ A0, int lda0, int ksplit, const bf16_t* __restrict__ A1, int lda1,
;                   const bf16_t* __restrict__ Bt, int K, int row0, int col0, const Epi& epi, int tid) {
;     ...
;   __syncthreads();
;   {
;     const int last = nk - 1;
;     GLOAD(0, 0);
;     __builtin_amdgcn_sched_barrier(0);
;     GLOAD(1, 1);
;     __builtin_amdgcn_sched_barrier(0);
;     LWRITE(0, 0);
;     __builtin_amdgcn_sched_barrier(0);
;     GLOAD(0, (2 < last ? 2 : last));
;     __builtin_amdgcn_sched_barrier(0);
;     __syncthreads();
;     for (int kt = 0; kt < nk; kt += 2) {
;       LWRITE(1, 1);
;       __builtin_amdgcn_sched_barrier(0);
;       GLOAD(1, (kt + 3 < last ? kt + 3 : last));
;       __builtin_amdgcn_sched_barrier(0);
;       COMPUTE(0);
;       __syncthreads();
;       LWRITE(0, 0);
;       __builtin_amdgcn_sched_barrier(0);
;       GLOAD(0, (kt + 4 < last ? kt + 4 : last));
;       __builtin_amdgcn_sched_barrier(0);
;       COMPUTE(1);
;       __syncthreads();
;     }
.Lg11_hi1:
	v_mfma_f32_16x16x32_bf16 v[64:67], v[176:179], v[208:211], v[64:67]
	v_mfma_f32_16x16x32_bf16 v[68:71], v[180:183], v[208:211], v[68:71]
	v_mfma_f32_16x16x32_bf16 v[72:75], v[184:187], v[208:211], v[72:75]
	v_mfma_f32_16x16x32_bf16 v[76:79], v[188:191], v[208:211], v[76:79]
	ds_read_b128 v[160:163], v232 offset:4096
	s_add_u32 m0, s25, 16384
	s_nop 0
	global_load_lds_dwordx4 v228, s[2:3]
	v_mfma_f32_16x16x32_bf16 v[80:83], v[176:179], v[212:215], v[80:83]
	v_mfma_f32_16x16x32_bf16 v[84:87], v[180:183], v[212:215], v[84:87]
	v_mfma_f32_16x16x32_bf16 v[88:91], v[184:187], v[212:215], v[88:91]
	v_mfma_f32_16x16x32_bf16 v[92:95], v[188:191], v[212:215], v[92:95]
	ds_read_b128 v[164:167], v232 offset:5120
	s_add_u32 m0, s25, 20480
	s_nop 0
	global_load_lds_dwordx4 v229, s[2:3]
	v_mfma_f32_16x16x32_bf16 v[96:99], v[176:179], v[216:219], v[96:99]
	v_mfma_f32_16x16x32_bf16 v[100:103], v[180:183], v[216:219], v[100:103]
	v_mfma_f32_16x16x32_bf16 v[104:107], v[184:187], v[216:219], v[104:107]
	v_mfma_f32_16x16x32_bf16 v[108:111], v[188:191], v[216:219], v[108:111]
	ds_read_b128 v[168:171], v232 offset:6144
	s_add_u32 s0, s0, 64
	s_addc_u32 s1, s1, 0
	s_add_u32 s2, s2, 64
	s_addc_u32 s3, s3, 0
	s_add_u32 s98, s98, 1
	s_add_u32 s29, s29, 24576
	s_cmp_eq_u32 s29, 73728
	s_cselect_b32 s29, 0, s29
	s_add_u32 s30, s30, 24576
	s_cmp_eq_u32 s30, 73728
	s_cselect_b32 s30, 0, s30
	v_mfma_f32_16x16x32_bf16 v[112:115], v[176:179], v[220:223], v[112:115]
	v_mfma_f32_16x16x32_bf16 v[116:119], v[180:183], v[220:223], v[116:119]
	v_mfma_f32_16x16x32_bf16 v[120:123], v[184:187], v[220:223], v[120:123]
	v_mfma_f32_16x16x32_bf16 v[124:127], v[188:191], v[220:223], v[124:127]
	ds_read_b128 v[172:175], v232 offset:7168
	s_add_u32 s31, s31, 2
	s_cmp_lt_u32 s31, 28
	s_cbranch_scc1 .Lg11_kloop
	s_waitcnt vmcnt(6)
	s_waitcnt lgkmcnt(0)
	s_barrier
	v_add_u32_e32 v232, s30, v230
	v_add_u32_e32 v233, s30, v231
	s_add_u32 s25, s29, s99
	s_setprio 1
	v_mfma_f32_16x16x32_bf16 v[0:3], v[128:131], v[144:147], v[0:3]
	v_mfma_f32_16x16x32_bf16 v[4:7], v[132:135], v[144:147], v[4:7]
	v_mfma_f32_16x16x32_bf16 v[8:11], v[136:139], v[144:147], v[8:11]
	v_mfma_f32_16x16x32_bf16 v[12:15], v[140:143], v[144:147], v[12:15]
	ds_read_b128 v[176:179], v233 offset:0
	ds_read_b128 v[180:183], v233 offset:1024
	s_add_u32 m0, s25, 0
	s_nop 0
	global_load_lds_dwordx4 v224, s[0:1]
	v_mfma_f32_16x16x32_bf16 v[16:19], v[128:131], v[148:151], v[16:19]
	v_mfma_f32_16x16x32_bf16 v[20:23], v[132:135], v[148:151], v[20:23]
	v_mfma_f32_16x16x32_bf16 v[24:27], v[136:139], v[148:151], v[24:27]
	v_mfma_f32_16x16x32_bf16 v[28:31], v[140:143], v[148:151], v[28:31]
	ds_read_b128 v[184:187], v233 offset:2048
	ds_read_b128 v[188:191], v233 offset:3072
	s_add_u32 m0, s25, 4096
	s_nop 0
	global_load_lds_dwordx4 v225, s[0:1]
	v_mfma_f32_16x16x32_bf16 v[32:35], v[128:131], v[152:155], v[32:35]
	v_mfma_f32_16x16x32_bf16 v[36:39], v[132:135], v[152:155], v[36:39]
	v_mfma_f32_16x16x32_bf16 v[40:43], v[136:139], v[152:155], v[40:43]
	v_mfma_f32_16x16x32_bf16 v[44:47], v[140:143], v[152:155], v[44:47]
	ds_read_b128 v[192:195], v232 offset:0
	ds_read_b128 v[196:199], v232 offset:1024
	s_add_u32 m0, s25, 8192
	s_nop 0
	global_load_lds_dwordx4 v226, s[0:1]
	v_mfma_f32_16x16x32_bf16 v[48:51], v[128:131], v[156:159], v[48:51]
	v_mfma_f32_16x16x32_bf16 v[52:55], v[132:135], v[156:159], v[52:55]
	v_mfma_f32_16x16x32_bf16 v[56:59], v[136:139], v[156:159], v[56:59]
	v_mfma_f32_16x16x32_bf16 v[60:63], v[140:143], v[156:159], v[60:63]
	ds_read_b128 v[200:203], v232 offset:2048
	ds_read_b128 v[204:207], v232 offset:3072
	s_add_u32 m0, s25, 12288
	s_nop 0
	global_load_lds_dwordx4 v227, s[0:1]
	s_cmp_eq_u32 s24, 0
	s_cbranch_scc0 .Lg11_hi2
	s_setprio 0
.Lg11_hi2:
	v_mfma_f32_16x16x32_bf16 v[64:67], v[128:131], v[160:163], v[64:67]
	v_mfma_f32_16x16x32_bf16 v[68:71], v[132:135], v[160:163], v[68:71]
	v_mfma_f32_16x16x32_bf16 v[72:75], v[136:139], v[160:163], v[72:75]
	v_mfma_f32_16x16x32_bf16 v[76:79], v[140:143], v[160:163], v[76:79]
	ds_read_b128 v[208:211], v232 offset:4096
	s_add_u32 m0, s25, 16384
	s_nop 0
	global_load_lds_dwordx4 v228, s[2:3]
	v_mfma_f32_16x16x32_bf16 v[80:83], v[128:131], v[164:167], v[80:83]
	v_mfma_f32_16x16x32_bf16 v[84:87], v[132:135], v[164:167], v[84:87]
	v_mfma_f32_16x16x32_bf16 v[88:91], v[136:139], v[164:167], v[88:91]
	v_mfma_f32_16x16x32_bf16 v[92:95], v[140:143], v[164:167], v[92:95]
	ds_read_b128 v[212:215], v232 offset:5120
	s_add_u32 m0, s25, 20480
	s_nop 0
	global_load_lds_dwordx4 v229, s[2:3]
	v_mfma_f32_16x16x32_bf16 v[96:99], v[128:131], v[168:171], v[96:99]
	v_mfma_f32_16x16x32_bf16 v[100:103], v[132:135], v[168:171], v[100:103]
	v_mfma_f32_16x16x32_bf16 v[104:107], v[136:139], v[168:171], v[104:107]
	v_mfma_f32_16x16x32_bf16 v[108:111], v[140:143], v[168:171], v[108:111]
	ds_read_b128 v[216:219], v232 offset:6144
	s_add_u32 s0, s0, 64
	s_addc_u32 s1, s1, 0
	s_add_u32 s2, s2, 64
	s_addc_u32 s3, s3, 0
	s_add_u32 s98, s98, 1
	s_add_u32 s29, s29, 24576
	s_cmp_eq_u32 s29, 73728
	s_cselect_b32 s29, 0, s29
	s_add_u32 s30, s30, 24576
	s_cmp_eq_u32 s30, 73728
	s_cselect_b32 s30, 0, s30
	v_mfma_f32_16x16x32_bf16 v[112:115], v[128:131], v[172:175], v[112:115]
	v_mfma_f32_16x16x32_bf16 v[116:119], v[132:135], v[172:175], v[116:119]
	v_mfma_f32_16x16x32_bf16 v[120:123], v[136:139], v[172:175], v[120:123]
	v_mfma_f32_16x16x32_bf16 v[124:127], v[140:143], v[172:175], v[124:127]
	ds_read_b128 v[220:223], v232 offset:7168
	s_waitcnt vmcnt(6)
	s_waitcnt lgkmcnt(0)
	s_barrier
; #define LWRITE(S, buf) do { bf16_t* sA_ = sbase + (buf) * BUF; bf16_t* sB_ = sA_ + 256 * PITCH; \
;     _Pragma("unroll") for (int i_ = 0; i_ < 4; ++i_) *(u32x4*)(sA_ + (sr + i_ * 64) * PITCH + scv * 8) = ra[S][i_]; \
;     _Pragma("unroll") for (int i_ = 0; i_ < 2; ++i_) *(u32x4*)(sB_ + (sr + i_ * 64) * PITCH + scv * 8) = rb[S][i_]; } while (0)
; template <class Epi>
; DI void gemm_tile(char* smem, const bf16_t* __restrict__ A0, int lda0, int ksplit, const bf16_t* __restrict__ A1, int lda1,
;                   const bf16_t* __restrict__ Bt, int K, int row0, int col0, const Epi& epi, int tid) {
;     ...
;   __syncthreads();
;   {
;     const int last = nk - 1;
;     GLOAD(0, 0);
;     __builtin_amdgcn_sched_barrier(0);
;     GLOAD(1, 1);
;     __builtin_amdgcn_sched_barrier(0);
;     LWRITE(0, 0);
;     __builtin_amdgcn_sched_barrier(0);
;     GLOAD(0, (2 < last ? 2 : last));
;     __builtin_amdgcn_sched_barrier(0);
;     __syncthreads();
;     for (int kt = 0; kt < nk; kt += 2) {
;       LWRITE(1, 1);
;       __builtin_amdgcn_sched_barrier(0);
;       GLOAD(1, (kt + 3 < last ? kt + 3 : last));
;       __builtin_amdgcn_sched_barrier(0);
;       COMPUTE(0);
;       __syncthreads();
;       LWRITE(0, 0);
;       __builtin_amdgcn_sched_barrier(0);
;       GLOAD(0, (kt + 4 < last ? kt + 4 : last));
;       __builtin_amdgcn_sched_barrier(0);
;       COMPUTE(1);
;       __syncthreads();
;     }
	v_add_u32_e32 v232, s30, v230
	v_add_u32_e32 v233, s30, v231
	s_setprio 1
	v_mfma_f32_16x16x32_bf16 v[0:3], v[176:179], v[192:195], v[0:3]
	v_mfma_f32_16x16x32_bf16 v[4:7], v[180:183], v[192:195], v[4:7]
	v_mfma_f32_16x16x32_bf16 v[8:11], v[184:187], v[192:195], v[8:11]
	v_mfma_f32_16x16x32_bf16 v[12:15], v[188:191], v[192:195], v[12:15]
	ds_read_b128 v[128:131], v233 offset:0
	ds_read_b128 v[132:135], v233 offset:1024
	v_mfma_f32_16x16x32_bf16 v[16:19], v[176:179], v[196:199], v[16:19]
	v_mfma_f32_16x16x32_bf16 v[20:23], v[180:183], v[196:199], v[20:23]
	v_mfma_f32_16x16x32_bf16 v[24:27], v[184:187], v[196:199], v[24:27]
	v_mfma_f32_16x16x32_bf16 v[28:31], v[188:191], v[196:199], v[28:31]
	ds_read_b128 v[136:139], v233 offset:2048
	ds_read_b128 v[140:143], v233 offset:3072
	v_mfma_f32_16x16x32_bf16 v[32:35], v[176:179], v[200:203], v[32:35]
	v_mfma_f32_16x16x32_bf16 v[36:39], v[180:183], v[200:203], v[36:39]
	v_mfma_f32_16x16x32_bf16 v[40:43], v[184:187], v[200:203], v[40:43]
	v_mfma_f32_16x16x32_bf16 v[44:47], v[188:191], v[200:203], v[44:47]
	ds_read_b128 v[144:147], v232 offset:0
	ds_read_b128 v[148:151], v232 offset:1024
	v_mfma_f32_16x16x32_bf16 v[48:51], v[176:179], v[204:207], v[48:51]
	v_mfma_f32_16x16x32_bf16 v[52:55], v[180:183], v[204:207], v[52:55]
	v_mfma_f32_16x16x32_bf16 v[56:59], v[184:187], v[204:207], v[56:59]
	v_mfma_f32_16x16x32_bf16 v[60:63], v[188:191], v[204:207], v[60:63]
	ds_read_b128 v[152:155], v232 offset:2048
	ds_read_b128 v[156:159], v232 offset:3072
	s_cmp_eq_u32 s24, 0
	s_cbranch_scc0 .Lg11_hi3
	s_setprio 0
.Lg11_hi3:
	v_mfma_f32_16x16x32_bf16 v[64:67], v[176:179], v[208:211], v[64:67]
	v_mfma_f32_16x16x32_bf16 v[68:71], v[180:183], v[208:211], v[68:71]
	v_mfma_f32_16x16x32_bf16 v[72:75], v[184:187], v[208:211], v[72:75]
	v_mfma_f32_16x16x32_bf16 v[76:79], v[188:191], v[208:211], v[76:79]
	ds_read_b128 v[160:163], v232 offset:4096
	v_mfma_f32_16x16x32_bf16 v[80:83], v[176:179], v[212:215], v[80:83]
	v_mfma_f32_16x16x32_bf16 v[84:87], v[180:183], v[212:215], v[84:87]
	v_mfma_f32_16x16x32_bf16 v[88:91], v[184:187], v[212:215], v[88:91]
	v_mfma_f32_16x16x32_bf16 v[92:95], v[188:191], v[212:215], v[92:95]
	ds_read_b128 v[164:167], v232 offset:5120
	v_mfma_f32_16x16x32_bf16 v[96:99], v[176:179], v[216:219], v[96:99]
	v_mfma_f32_16x16x32_bf16 v[100:103], v[180:183], v[216:219], v[100:103]
	v_mfma_f32_16x16x32_bf16 v[104:107], v[184:187], v[216:219], v[104:107]
	v_mfma_f32_16x16x32_bf16 v[108:111], v[188:191], v[216:219], v[108:111]
	ds_read_b128 v[168:171], v232 offset:6144
	s_add_u32 s30, s30, 24576
	s_cmp_eq_u32 s30, 73728
	s_cselect_b32 s30, 0, s30
	v_mfma_f32_16x16x32_bf16 v[112:115], v[176:179], v[220:223], v[112:115]
	v_mfma_f32_16x16x32_bf16 v[116:119], v[180:183], v[220:223], v[116:119]
	v_mfma_f32_16x16x32_bf16 v[120:123], v[184:187], v[220:223], v[120:123]
	v_mfma_f32_16x16x32_bf16 v[124:127], v[188:191], v[220:223], v[124:127]
	ds_read_b128 v[172:175], v232 offset:7168
	s_waitcnt vmcnt(0)
	s_waitcnt lgkmcnt(0)
	s_barrier
	v_add_u32_e32 v232, s30, v230
	v_add_u32_e32 v233, s30, v231
	s_setprio 1
	v_mfma_f32_16x16x32_bf16 v[0:3], v[128:131], v[144:147], v[0:3]
	v_mfma_f32_16x16x32_bf16 v[4:7], v[132:135], v[144:147], v[4:7]
	v_mfma_f32_16x16x32_bf16 v[8:11], v[136:139], v[144:147], v[8:11]
	v_mfma_f32_16x16x32_bf16 v[12:15], v[140:143], v[144:147], v[12:15]
	ds_read_b128 v[176:179], v233 offset:0
	ds_read_b128 v[180:183], v233 offset:1024
	v_mfma_f32_16x16x32_bf16 v[16:19], v[128:131], v[148:151], v[16:19]
	v_mfma_f32_16x16x32_bf16 v[20:23], v[132:135], v[148:151], v[20:23]
	v_mfma_f32_16x16x32_bf16 v[24:27], v[136:139], v[148:151], v[24:27]
	v_mfma_f32_16x16x32_bf16 v[28:31], v[140:143], v[148:151], v[28:31]
	ds_read_b128 v[184:187], v233 offset:2048
	ds_read_b128 v[188:191], v233 offset:3072
	v_mfma_f32_16x16x32_bf16 v[32:35], v[128:131], v[152:155], v[32:35]
	v_mfma_f32_16x16x32_bf16 v[36:39], v[132:135], v[152:155], v[36:39]
	v_mfma_f32_16x16x32_bf16 v[40:43], v[136:139], v[152:155], v[40:43]
	v_mfma_f32_16x16x32_bf16 v[44:47], v[140:143], v[152:155], v[44:47]
	ds_read_b128 v[192:195], v232 offset:0
	ds_read_b128 v[196:199], v232 offset:1024
	v_mfma_f32_16x16x32_bf16 v[48:51], v[128:131], v[156:159], v[48:51]
	v_mfma_f32_16x16x32_bf16 v[52:55], v[132:135], v[156:159], v[52:55]
	v_mfma_f32_16x16x32_bf16 v[56:59], v[136:139], v[156:159], v[56:59]
	v_mfma_f32_16x16x32_bf16 v[60:63], v[140:143], v[156:159], v[60:63]
	ds_read_b128 v[200:203], v232 offset:2048
	ds_read_b128 v[204:207], v232 offset:3072
	s_cmp_eq_u32 s24, 0
	s_cbranch_scc0 .Lg11_hi4
	s_setprio 0
; #define LWRITE(S, buf) do { bf16_t* sA_ = sbase + (buf) * BUF; bf16_t* sB_ = sA_ + 256 * PITCH; \
;     _Pragma("unroll") for (int i_ = 0; i_ < 4; ++i_) *(u32x4*)(sA_ + (sr + i_ * 64) * PITCH + scv * 8) = ra[S][i_]; \
;     _Pragma("unroll") for (int i_ = 0; i_ < 2; ++i_) *(u32x4*)(sB_ + (sr + i_ * 64) * PITCH + scv * 8) = rb[S][i_]; } while (0)
; template <class Epi>
; DI void gemm_tile(char* smem, const bf16_t* __restrict__ A0, int lda0, int ksplit, const bf16_t* __restrict__ A1, int lda1,
;                   const bf16_t* __restrict__ Bt, int K, int row0, int col0, const Epi& epi, int tid) {
;     ...
;   __syncthreads();
;   {
;     const int last = nk - 1;
;     GLOAD(0, 0);
;     __builtin_amdgcn_sched_barrier(0);
;     GLOAD(1, 1);
;     __builtin_amdgcn_sched_barrier(0);
;     LWRITE(0, 0);
;     __builtin_amdgcn_sched_barrier(0);
;     GLOAD(0, (2 < last ? 2 : last));
;     __builtin_amdgcn_sched_barrier(0);
;     __syncthreads();
;     for (int kt = 0; kt < nk; kt += 2) {
;       LWRITE(1, 1);
;       __builtin_amdgcn_sched_barrier(0);
;       GLOAD(1, (kt + 3 < last ? kt + 3 : last));
;       __builtin_amdgcn_sched_barrier(0);
;       COMPUTE(0);
;       __syncthreads();
;       LWRITE(0, 0);
;       __builtin_amdgcn_sched_barrier(0);
;       GLOAD(0, (kt + 4 < last ? kt + 4 : last));
;       __builtin_amdgcn_sched_barrier(0);
;       COMPUTE(1);
;       __syncthreads();
;     }
.Lg11_hi4:
	v_mfma_f32_16x16x32_bf16 v[64:67], v[128:131], v[160:163], v[64:67]
	v_mfma_f32_16x16x32_bf16 v[68:71], v[132:135], v[160:163], v[68:71]
	v_mfma_f32_16x16x32_bf16 v[72:75], v[136:139], v[160:163], v[72:75]
	v_mfma_f32_16x16x32_bf16 v[76:79], v[140:143], v[160:163], v[76:79]
	ds_read_b128 v[208:211], v232 offset:4096
	v_mfma_f32_16x16x32_bf16 v[80:83], v[128:131], v[164:167], v[80:83]
	v_mfma_f32_16x16x32_bf16 v[84:87], v[132:135], v[164:167], v[84:87]
	v_mfma_f32_16x16x32_bf16 v[88:91], v[136:139], v[164:167], v[88:91]
	v_mfma_f32_16x16x32_bf16 v[92:95], v[140:143], v[164:167], v[92:95]
	ds_read_b128 v[212:215], v232 offset:5120
	v_mfma_f32_16x16x32_bf16 v[96:99], v[128:131], v[168:171], v[96:99]
	v_mfma_f32_16x16x32_bf16 v[100:103], v[132:135], v[168:171], v[100:103]
	v_mfma_f32_16x16x32_bf16 v[104:107], v[136:139], v[168:171], v[104:107]
	v_mfma_f32_16x16x32_bf16 v[108:111], v[140:143], v[168:171], v[108:111]
	ds_read_b128 v[216:219], v232 offset:6144
	s_add_u32 s30, s30, 24576
	s_cmp_eq_u32 s30, 73728
	s_cselect_b32 s30, 0, s30
	v_mfma_f32_16x16x32_bf16 v[112:115], v[128:131], v[172:175], v[112:115]
	v_mfma_f32_16x16x32_bf16 v[116:119], v[132:135], v[172:175], v[116:119]
	v_mfma_f32_16x16x32_bf16 v[120:123], v[136:139], v[172:175], v[120:123]
	v_mfma_f32_16x16x32_bf16 v[124:127], v[140:143], v[172:175], v[124:127]
	ds_read_b128 v[220:223], v232 offset:7168
	s_waitcnt lgkmcnt(0)
	s_barrier
	s_setprio 1
	v_mfma_f32_16x16x32_bf16 v[0:3], v[176:179], v[192:195], v[0:3]
	v_mfma_f32_16x16x32_bf16 v[4:7], v[180:183], v[192:195], v[4:7]
	v_mfma_f32_16x16x32_bf16 v[8:11], v[184:187], v[192:195], v[8:11]
	v_mfma_f32_16x16x32_bf16 v[12:15], v[188:191], v[192:195], v[12:15]
	v_mfma_f32_16x16x32_bf16 v[16:19], v[176:179], v[196:199], v[16:19]
	v_mfma_f32_16x16x32_bf16 v[20:23], v[180:183], v[196:199], v[20:23]
	v_mfma_f32_16x16x32_bf16 v[24:27], v[184:187], v[196:199], v[24:27]
	v_mfma_f32_16x16x32_bf16 v[28:31], v[188:191], v[196:199], v[28:31]
	v_mfma_f32_16x16x32_bf16 v[32:35], v[176:179], v[200:203], v[32:35]
	v_mfma_f32_16x16x32_bf16 v[36:39], v[180:183], v[200:203], v[36:39]
	v_mfma_f32_16x16x32_bf16 v[40:43], v[184:187], v[200:203], v[40:43]
	v_mfma_f32_16x16x32_bf16 v[44:47], v[188:191], v[200:203], v[44:47]
	v_mfma_f32_16x16x32_bf16 v[48:51], v[176:179], v[204:207], v[48:51]
	v_mfma_f32_16x16x32_bf16 v[52:55], v[180:183], v[204:207], v[52:55]
	v_mfma_f32_16x16x32_bf16 v[56:59], v[184:187], v[204:207], v[56:59]
	v_mfma_f32_16x16x32_bf16 v[60:63], v[188:191], v[204:207], v[60:63]
	s_cmp_eq_u32 s24, 0
	s_cbranch_scc0 .Lg11_hi5
	s_setprio 0

; #define LWRITE(S, buf) do { bf16_t* sA_ = sbase + (buf) * BUF; bf16_t* sB_ = sA_ + 256 * PITCH; \
;     _Pragma("unroll") for (int i_ = 0; i_ < 4; ++i_) *(u32x4*)(sA_ + (sr + i_ * 64) * PITCH + scv * 8) = ra[S][i_]; \
;     _Pragma("unroll") for (int i_ = 0; i_ < 2; ++i_) *(u32x4*)(sB_ + (sr + i_ * 64) * PITCH + scv * 8) = rb[S][i_]; } while (0)
; template <class Epi>
; DI void gemm_tile(char* smem, const bf16_t* __restrict__ A0, int lda0, int ksplit, const bf16_t* __restrict__ A1, int lda1,
;                   const bf16_t* __restrict__ Bt, int K, int row0, int col0, const Epi& epi, int tid) {
;     ...
;   __syncthreads();
;   {
;     const int last = nk - 1;
;     GLOAD(0, 0);
;     __builtin_amdgcn_sched_barrier(0);
;     GLOAD(1, 1);
;     __builtin_amdgcn_sched_barrier(0);
;     LWRITE(0, 0);
;     __builtin_amdgcn_sched_barrier(0);
;     GLOAD(0, (2 < last ? 2 : last));
;     __builtin_amdgcn_sched_barrier(0);
;     __syncthreads();
;     for (int kt = 0; kt < nk; kt += 2) {
;       LWRITE(1, 1);
;       __builtin_amdgcn_sched_barrier(0);
;       GLOAD(1, (kt + 3 < last ? kt + 3 : last));
;       __builtin_amdgcn_sched_barrier(0);
;       COMPUTE(0);
;       __syncthreads();
;       LWRITE(0, 0);
;       __builtin_amdgcn_sched_barrier(0);
;       GLOAD(0, (kt + 4 < last ? kt + 4 : last));
;       __builtin_amdgcn_sched_barrier(0);
;       COMPUTE(1);
;       __syncthreads();
;     }
.Lg14_hi1:
	v_mfma_f32_16x16x32_bf16 v[64:67], v[176:179], v[208:211], v[64:67]
	v_mfma_f32_16x16x32_bf16 v[68:71], v[180:183], v[208:211], v[68:71]
	v_mfma_f32_16x16x32_bf16 v[72:75], v[184:187], v[208:211], v[72:75]
	v_mfma_f32_16x16x32_bf16 v[76:79], v[188:191], v[208:211], v[76:79]
	ds_read_b128 v[160:163], v232 offset:4096
	s_add_u32 m0, s11, 16384
	s_nop 0
	global_load_lds_dwordx4 v228, s[2:3]
	v_mfma_f32_16x16x32_bf16 v[80:83], v[176:179], v[212:215], v[80:83]
	v_mfma_f32_16x16x32_bf16 v[84:87], v[180:183], v[212:215], v[84:87]
	v_mfma_f32_16x16x32_bf16 v[88:91], v[184:187], v[212:215], v[88:91]
	v_mfma_f32_16x16x32_bf16 v[92:95], v[188:191], v[212:215], v[92:95]
	ds_read_b128 v[164:167], v232 offset:5120
	s_add_u32 m0, s11, 20480
	s_nop 0
	global_load_lds_dwordx4 v229, s[2:3]
	v_mfma_f32_16x16x32_bf16 v[96:99], v[176:179], v[216:219], v[96:99]
	v_mfma_f32_16x16x32_bf16 v[100:103], v[180:183], v[216:219], v[100:103]
	v_mfma_f32_16x16x32_bf16 v[104:107], v[184:187], v[216:219], v[104:107]
	v_mfma_f32_16x16x32_bf16 v[108:111], v[188:191], v[216:219], v[108:111]
	ds_read_b128 v[168:171], v232 offset:6144
	s_add_u32 s0, s0, 64
	s_addc_u32 s1, s1, 0
	s_add_u32 s2, s2, 64
	s_addc_u32 s3, s3, 0
	s_add_u32 s100, s100, 1
	s_add_u32 s19, s19, 24576
	s_cmp_eq_u32 s19, 73728
	s_cselect_b32 s19, 0, s19
	s_add_u32 s98, s98, 24576
	s_cmp_eq_u32 s98, 73728
	s_cselect_b32 s98, 0, s98
	v_mfma_f32_16x16x32_bf16 v[112:115], v[176:179], v[220:223], v[112:115]
	v_mfma_f32_16x16x32_bf16 v[116:119], v[180:183], v[220:223], v[116:119]
	v_mfma_f32_16x16x32_bf16 v[120:123], v[184:187], v[220:223], v[120:123]
	v_mfma_f32_16x16x32_bf16 v[124:127], v[188:191], v[220:223], v[124:127]
	ds_read_b128 v[172:175], v232 offset:7168
	s_add_u32 s99, s99, 2
	s_cmp_lt_u32 s99, 12
	s_cbranch_scc1 .Lg14_kloop
	s_waitcnt vmcnt(6)
	s_waitcnt lgkmcnt(0)
	s_barrier
	v_add_u32_e32 v232, s98, v230
	v_add_u32_e32 v233, s98, v231
	s_add_u32 s11, s19, s101
	s_setprio 1
	v_mfma_f32_16x16x32_bf16 v[0:3], v[128:131], v[144:147], v[0:3]
	v_mfma_f32_16x16x32_bf16 v[4:7], v[132:135], v[144:147], v[4:7]
	v_mfma_f32_16x16x32_bf16 v[8:11], v[136:139], v[144:147], v[8:11]
	v_mfma_f32_16x16x32_bf16 v[12:15], v[140:143], v[144:147], v[12:15]
	ds_read_b128 v[176:179], v233 offset:0
	ds_read_b128 v[180:183], v233 offset:1024
	s_add_u32 m0, s11, 0
	s_nop 0
	global_load_lds_dwordx4 v224, s[0:1]
	v_mfma_f32_16x16x32_bf16 v[16:19], v[128:131], v[148:151], v[16:19]
	v_mfma_f32_16x16x32_bf16 v[20:23], v[132:135], v[148:151], v[20:23]
	v_mfma_f32_16x16x32_bf16 v[24:27], v[136:139], v[148:151], v[24:27]
	v_mfma_f32_16x16x32_bf16 v[28:31], v[140:143], v[148:151], v[28:31]
	ds_read_b128 v[184:187], v233 offset:2048
	ds_read_b128 v[188:191], v233 offset:3072
	s_add_u32 m0, s11, 4096
	s_nop 0
	global_load_lds_dwordx4 v225, s[0:1]
	v_mfma_f32_16x16x32_bf16 v[32:35], v[128:131], v[152:155], v[32:35]
	v_mfma_f32_16x16x32_bf16 v[36:39], v[132:135], v[152:155], v[36:39]
	v_mfma_f32_16x16x32_bf16 v[40:43], v[136:139], v[152:155], v[40:43]
	v_mfma_f32_16x16x32_bf16 v[44:47], v[140:143], v[152:155], v[44:47]
	ds_read_b128 v[192:195], v232 offset:0
	ds_read_b128 v[196:199], v232 offset:1024
	s_add_u32 m0, s11, 8192
	s_nop 0
	global_load_lds_dwordx4 v226, s[0:1]
	v_mfma_f32_16x16x32_bf16 v[48:51], v[128:131], v[156:159], v[48:51]
	v_mfma_f32_16x16x32_bf16 v[52:55], v[132:135], v[156:159], v[52:55]
	v_mfma_f32_16x16x32_bf16 v[56:59], v[136:139], v[156:159], v[56:59]
	v_mfma_f32_16x16x32_bf16 v[60:63], v[140:143], v[156:159], v[60:63]
	ds_read_b128 v[200:203], v232 offset:2048
	ds_read_b128 v[204:207], v232 offset:3072
	s_add_u32 m0, s11, 12288
	s_nop 0
	global_load_lds_dwordx4 v227, s[0:1]
	s_cmp_eq_u32 s10, 0
	s_cbranch_scc0 .Lg14_hi2
	s_setprio 0
